# GEMM MFMA order: accumulator-pair chains with shared operands; MLA P*V accumulator pairs; NSA unit order alternately reversed
# speedup vs baseline: 1.0149x; 1.0089x over previous
; #define PG8_STAGE(bufoff, gbase, voff) do { _Pragma("unroll") for (int _i = 0; _i < 2; ++_i) \
;         __builtin_amdgcn_global_load_lds((const unsigned*)((const char*)(gbase) + (voff)[_i]), (LAS unsigned*)(lds + (bufoff) + ldsw + _i * 8192), 16, 0, 0); } while (0)
; #define PG8_LDA(dst, b, h) do { _Pragma("unroll") for (int m = 0; m < 4; ++m) _Pragma("unroll") for (int k = 0; k < 2; ++k) dst[m][k] = *(const LAS bf16x8*)(lds + PG8_SA(b, h) + aoff + m * 2048 + k * 1024); } while (0)
; #define PG8_LDB(dst, b, h) do { _Pragma("unroll") for (int n = 0; n < 2; ++n) _Pragma("unroll") for (int k = 0; k < 2; ++k) dst[n][k] = *(const LAS bf16x8*)(lds + PG8_SB(b, h) + boff + n * 2048 + k * 1024); } while (0)
; #define PG8_WAIT_V(n) asm volatile("s_waitcnt vmcnt(" #n ")" ::: "memory")
; #define PG8_WAIT_L(n) asm volatile("s_waitcnt lgkmcnt(" #n ")" ::: "memory")
; #define PG8_BAR __builtin_amdgcn_s_barrier()
; DI void gemm_phase(LAS unsigned char* lds, const Gemm g, const StaticOrder& S, const Epi& E) {
;     ...
;         for (int t = 0; t < nt; t += 2) {
;             const bool last = (t == nt - 2);
;             const char* a1 = cA + (size_t)(t + 1) * kstep;
;             const char* a2 = last ? nA : cA + (size_t)(t + 2) * kstep; const char* b2 = last ? nB : cB + (size_t)(t + 2) * kstep;
;             const char* a3 = a2 + kstep; const char* b3 = b2 + kstep;
;             PG8_LDB(B0, 0, 0); PG8_LDB(B1, 0, 1); PG8_SCHED; PG8_LDA(At, 0, 0); PG8_STAGE(PG8_SA(1, 1), a1 + hsA, voffA);
;             PG8_WAIT_V(8); PG8_WAIT_L(0); PG8_BAR; PG8_MMA(0, 0, At, B0); PG8_MMA(0, 1, At, B1); PG8_BAR; PG8_SCHED;
;             PG8_LDA(At, 0, 1); PG8_STAGE(PG8_SB(0, 0), b2, voffB); PG8_STAGE(PG8_SB(0, 1), b2 + hsB, voffB); PG8_STAGE(PG8_SA(0, 0), a2, voffA);
;             PG8_WAIT_V(8); PG8_WAIT_L(0); PG8_BAR; PG8_MMA(1, 0, At, B0); PG8_MMA(1, 1, At, B1); PG8_BAR; PG8_SCHED;
;             PG8_LDB(B0, 1, 0); PG8_LDB(B1, 1, 1); PG8_SCHED; PG8_LDA(At, 1, 0); PG8_STAGE(PG8_SA(0, 1), a2 + hsA, voffA);
;             PG8_WAIT_V(8); PG8_WAIT_L(0); PG8_BAR; PG8_MMA(0, 0, At, B0); PG8_MMA(0, 1, At, B1); PG8_BAR; PG8_SCHED;
;             PG8_LDA(At, 1, 1); PG8_STAGE(PG8_SB(1, 0), b3, voffB); PG8_STAGE(PG8_SB(1, 1), b3 + hsB, voffB); PG8_STAGE(PG8_SA(1, 0), a3, voffA);
;             PG8_WAIT_V(8); PG8_WAIT_L(0); PG8_BAR; PG8_MMA(1, 0, At, B0); PG8_MMA(1, 1, At, B1); PG8_BAR; PG8_SCHED;
;         }
.LBB0_177:
	ds_read_b128 v[152:155], v149
	ds_read_b128 v[156:159], v149 offset:1024
	ds_read_b128 v[160:163], v149 offset:2048
	ds_read_b128 v[170:173], v149 offset:3072
	ds_read_b128 v[174:177], v150
	ds_read_b128 v[178:181], v150 offset:1024
	ds_read_b128 v[182:185], v150 offset:2048
	ds_read_b128 v[186:189], v150 offset:3072
	s_add_u32 s34, s30, 0xfff80080
	s_addc_u32 s35, s31, -1
	s_cmp_eq_u32 s56, 28
	s_cselect_b32 s39, s5, s35
	s_cselect_b32 s38, s23, s34
	s_cselect_b32 s35, s21, s55
	s_cselect_b32 s34, s29, s54
	v_lshl_add_u64 v[144:145], s[30:31], 0, v[136:137]
	s_add_i32 m0, s13, 0xc000
	ds_read_b128 v[190:193], v151
	ds_read_b128 v[194:197], v151 offset:1024
	ds_read_b128 v[198:201], v151 offset:2048
	ds_read_b128 v[202:205], v151 offset:3072
	ds_read_b128 v[206:209], v151 offset:4096
	ds_read_b128 v[210:213], v151 offset:5120
	ds_read_b128 v[214:217], v151 offset:6144
	ds_read_b128 v[218:221], v151 offset:7168
	global_load_lds_dwordx4 v[144:145], off
	v_lshl_add_u64 v[144:145], s[30:31], 0, v[138:139]
	s_add_i32 m0, s13, 0xe000
	s_nop 0
	global_load_lds_dwordx4 v[144:145], off
	s_waitcnt vmcnt(8)
	s_waitcnt lgkmcnt(0)
	s_barrier
	s_setprio 1
	s_waitcnt lgkmcnt(0)
	v_mfma_f32_16x16x32_bf16 v[124:127], v[152:155], v[190:193], v[124:127]
	v_mfma_f32_16x16x32_bf16 v[124:127], v[156:159], v[194:197], v[124:127]
	v_mfma_f32_16x16x32_bf16 v[120:123], v[170:173], v[194:197], v[120:123]
	v_mfma_f32_16x16x32_bf16 v[120:123], v[160:163], v[190:193], v[120:123]
	v_mfma_f32_16x16x32_bf16 v[108:111], v[160:163], v[198:201], v[108:111]
	v_mfma_f32_16x16x32_bf16 v[108:111], v[170:173], v[202:205], v[108:111]
	v_mfma_f32_16x16x32_bf16 v[116:119], v[156:159], v[202:205], v[116:119]
	v_mfma_f32_16x16x32_bf16 v[116:119], v[152:155], v[198:201], v[116:119]
	v_mfma_f32_16x16x32_bf16 v[100:103], v[152:155], v[206:209], v[100:103]
	v_mfma_f32_16x16x32_bf16 v[100:103], v[156:159], v[210:213], v[100:103]
	v_mfma_f32_16x16x32_bf16 v[92:95], v[170:173], v[210:213], v[92:95]
	v_mfma_f32_16x16x32_bf16 v[92:95], v[160:163], v[206:209], v[92:95]
	v_mfma_f32_16x16x32_bf16 v[76:79], v[160:163], v[214:217], v[76:79]
	v_mfma_f32_16x16x32_bf16 v[76:79], v[170:173], v[218:221], v[76:79]
	v_mfma_f32_16x16x32_bf16 v[84:87], v[156:159], v[218:221], v[84:87]
	v_mfma_f32_16x16x32_bf16 v[84:87], v[152:155], v[214:217], v[84:87]
	s_setprio 0
	s_setprio 1
	v_mfma_f32_16x16x32_bf16 v[112:115], v[174:177], v[190:193], v[112:115]
	v_mfma_f32_16x16x32_bf16 v[112:115], v[178:181], v[194:197], v[112:115]
	v_mfma_f32_16x16x32_bf16 v[104:107], v[186:189], v[194:197], v[104:107]
	v_mfma_f32_16x16x32_bf16 v[104:107], v[182:185], v[190:193], v[104:107]
	v_mfma_f32_16x16x32_bf16 v[88:91], v[182:185], v[198:201], v[88:91]
	v_mfma_f32_16x16x32_bf16 v[88:91], v[186:189], v[202:205], v[88:91]
	v_mfma_f32_16x16x32_bf16 v[96:99], v[178:181], v[202:205], v[96:99]
	v_mfma_f32_16x16x32_bf16 v[96:99], v[174:177], v[198:201], v[96:99]
	v_mfma_f32_16x16x32_bf16 v[80:83], v[174:177], v[206:209], v[80:83]
	v_mfma_f32_16x16x32_bf16 v[80:83], v[178:181], v[210:213], v[80:83]
	v_mfma_f32_16x16x32_bf16 v[72:75], v[186:189], v[210:213], v[72:75]
	v_mfma_f32_16x16x32_bf16 v[72:75], v[182:185], v[206:209], v[72:75]
	v_mfma_f32_16x16x32_bf16 v[64:67], v[182:185], v[214:217], v[64:67]
	v_mfma_f32_16x16x32_bf16 v[64:67], v[186:189], v[218:221], v[64:67]
	v_mfma_f32_16x16x32_bf16 v[68:71], v[178:181], v[218:221], v[68:71]
	v_mfma_f32_16x16x32_bf16 v[68:71], v[174:177], v[214:217], v[68:71]
	s_setprio 0
	s_barrier
	s_add_i32 s46, s50, s12
	v_lshl_add_u64 v[144:145], s[34:35], 0, v[130:131]
	s_mov_b32 m0, s46
	ds_read_b128 v[190:193], v151 offset:16384
	ds_read_b128 v[194:197], v151 offset:17408
	ds_read_b128 v[198:201], v151 offset:18432
	ds_read_b128 v[202:205], v151 offset:19456
	ds_read_b128 v[206:209], v151 offset:20480
	ds_read_b128 v[210:213], v151 offset:21504
	ds_read_b128 v[214:217], v151 offset:22528
	ds_read_b128 v[218:221], v151 offset:23552
	global_load_lds_dwordx4 v[144:145], off
	s_add_i32 m0, s46, 0x2000
	s_add_u32 s46, s34, 0x80000
	v_lshl_add_u64 v[164:165], s[34:35], 0, v[134:135]
	s_addc_u32 s47, s35, 0
	s_add_i32 s57, s51, s12
	global_load_lds_dwordx4 v[164:165], off
	v_lshl_add_u64 v[222:223], s[46:47], 0, v[130:131]
	s_mov_b32 m0, s57
	v_lshl_add_u64 v[224:225], s[38:39], 0, v[132:133]
	global_load_lds_dwordx4 v[222:223], off
	v_lshl_add_u64 v[222:223], s[46:47], 0, v[134:135]
	s_add_i32 m0, s57, 0x2000
	s_nop 0
	global_load_lds_dwordx4 v[222:223], off
	v_lshl_add_u64 v[222:223], s[38:39], 0, v[128:129]
	s_mov_b32 m0, s13
	s_nop 0
	global_load_lds_dwordx4 v[222:223], off
	s_mov_b32 m0, s33
	s_nop 0
	global_load_lds_dwordx4 v[224:225], off
	s_waitcnt vmcnt(8)
	s_waitcnt lgkmcnt(0)
	s_barrier
; #define PG8_STAGE(bufoff, gbase, voff) do { _Pragma("unroll") for (int _i = 0; _i < 2; ++_i) \
;         __builtin_amdgcn_global_load_lds((const unsigned*)((const char*)(gbase) + (voff)[_i]), (LAS unsigned*)(lds + (bufoff) + ldsw + _i * 8192), 16, 0, 0); } while (0)
; #define PG8_LDA(dst, b, h) do { _Pragma("unroll") for (int m = 0; m < 4; ++m) _Pragma("unroll") for (int k = 0; k < 2; ++k) dst[m][k] = *(const LAS bf16x8*)(lds + PG8_SA(b, h) + aoff + m * 2048 + k * 1024); } while (0)
; #define PG8_LDB(dst, b, h) do { _Pragma("unroll") for (int n = 0; n < 2; ++n) _Pragma("unroll") for (int k = 0; k < 2; ++k) dst[n][k] = *(const LAS bf16x8*)(lds + PG8_SB(b, h) + boff + n * 2048 + k * 1024); } while (0)
; #define PG8_MMA(ai, bj, At, Bt) do { __builtin_amdgcn_s_setprio(1); _Pragma("unroll") for (int m = 0; m < 4; ++m) _Pragma("unroll") for (int n = 0; n < 2; ++n) _Pragma("unroll") for (int k = 0; k < 2; ++k) \
;         acc[ai][bj][m][n] = __builtin_amdgcn_mfma_f32_16x16x32_bf16(Bt[n][k], At[m][k], acc[ai][bj][m][n], 0, 0, 0); __builtin_amdgcn_s_setprio(0); } while (0)
; #define PG8_WAIT_V(n) asm volatile("s_waitcnt vmcnt(" #n ")" ::: "memory")
; #define PG8_WAIT_L(n) asm volatile("s_waitcnt lgkmcnt(" #n ")" ::: "memory")
; DI void gemm_phase(LAS unsigned char* lds, const Gemm g, const StaticOrder& S, const Epi& E) {
;     ...
;             PG8_LDB(B0, 0, 0); PG8_LDB(B1, 0, 1); PG8_SCHED; PG8_LDA(At, 0, 0); PG8_STAGE(PG8_SA(1, 1), a1 + hsA, voffA);
;             PG8_WAIT_V(8); PG8_WAIT_L(0); PG8_BAR; PG8_MMA(0, 0, At, B0); PG8_MMA(0, 1, At, B1); PG8_BAR; PG8_SCHED;
;             PG8_LDA(At, 0, 1); PG8_STAGE(PG8_SB(0, 0), b2, voffB); PG8_STAGE(PG8_SB(0, 1), b2 + hsB, voffB); PG8_STAGE(PG8_SA(0, 0), a2, voffA);
;             PG8_WAIT_V(8); PG8_WAIT_L(0); PG8_BAR; PG8_MMA(1, 0, At, B0); PG8_MMA(1, 1, At, B1); PG8_BAR; PG8_SCHED;
;             PG8_LDB(B0, 1, 0); PG8_LDB(B1, 1, 1); PG8_SCHED; PG8_LDA(At, 1, 0); PG8_STAGE(PG8_SA(0, 1), a2 + hsA, voffA);
;             PG8_WAIT_V(8); PG8_WAIT_L(0); PG8_BAR; PG8_MMA(0, 0, At, B0); PG8_MMA(0, 1, At, B1); PG8_BAR; PG8_SCHED;
;             PG8_LDA(At, 1, 1); PG8_STAGE(PG8_SB(1, 0), b3, voffB); PG8_STAGE(PG8_SB(1, 1), b3 + hsB, voffB); PG8_STAGE(PG8_SA(1, 0), a3, voffA);
;             PG8_WAIT_V(8); PG8_WAIT_L(0); PG8_BAR; PG8_MMA(1, 0, At, B0); PG8_MMA(1, 1, At, B1); PG8_BAR; PG8_SCHED;
	s_setprio 1
	s_waitcnt lgkmcnt(0)
	v_mfma_f32_16x16x32_bf16 v[60:63], v[152:155], v[190:193], v[60:63]
	v_mfma_f32_16x16x32_bf16 v[60:63], v[156:159], v[194:197], v[60:63]
	v_mfma_f32_16x16x32_bf16 v[56:59], v[170:173], v[194:197], v[56:59]
	v_mfma_f32_16x16x32_bf16 v[56:59], v[160:163], v[190:193], v[56:59]
	v_mfma_f32_16x16x32_bf16 v[44:47], v[160:163], v[198:201], v[44:47]
	v_mfma_f32_16x16x32_bf16 v[44:47], v[170:173], v[202:205], v[44:47]
	v_mfma_f32_16x16x32_bf16 v[52:55], v[156:159], v[202:205], v[52:55]
	v_mfma_f32_16x16x32_bf16 v[52:55], v[152:155], v[198:201], v[52:55]
	v_mfma_f32_16x16x32_bf16 v[36:39], v[152:155], v[206:209], v[36:39]
	v_mfma_f32_16x16x32_bf16 v[36:39], v[156:159], v[210:213], v[36:39]
	v_mfma_f32_16x16x32_bf16 v[28:31], v[170:173], v[210:213], v[28:31]
	v_mfma_f32_16x16x32_bf16 v[28:31], v[160:163], v[206:209], v[28:31]
	v_mfma_f32_16x16x32_bf16 v[12:15], v[160:163], v[214:217], v[12:15]
	v_mfma_f32_16x16x32_bf16 v[12:15], v[170:173], v[218:221], v[12:15]
	v_mfma_f32_16x16x32_bf16 v[20:23], v[156:159], v[218:221], v[20:23]
	v_mfma_f32_16x16x32_bf16 v[20:23], v[152:155], v[214:217], v[20:23]
	s_setprio 0
	s_setprio 1
	v_mfma_f32_16x16x32_bf16 v[48:51], v[174:177], v[190:193], v[48:51]
	v_mfma_f32_16x16x32_bf16 v[48:51], v[178:181], v[194:197], v[48:51]
	v_mfma_f32_16x16x32_bf16 v[40:43], v[186:189], v[194:197], v[40:43]
	v_mfma_f32_16x16x32_bf16 v[40:43], v[182:185], v[190:193], v[40:43]
	v_mfma_f32_16x16x32_bf16 v[24:27], v[182:185], v[198:201], v[24:27]
	v_mfma_f32_16x16x32_bf16 v[24:27], v[186:189], v[202:205], v[24:27]
	v_mfma_f32_16x16x32_bf16 v[32:35], v[178:181], v[202:205], v[32:35]
	v_mfma_f32_16x16x32_bf16 v[32:35], v[174:177], v[198:201], v[32:35]
	v_mfma_f32_16x16x32_bf16 v[16:19], v[174:177], v[206:209], v[16:19]
	v_mfma_f32_16x16x32_bf16 v[16:19], v[178:181], v[210:213], v[16:19]
	v_mfma_f32_16x16x32_bf16 v[8:11], v[186:189], v[210:213], v[8:11]
	v_mfma_f32_16x16x32_bf16 v[8:11], v[182:185], v[206:209], v[8:11]
	v_mfma_f32_16x16x32_bf16 v[0:3], v[182:185], v[214:217], v[0:3]
	v_mfma_f32_16x16x32_bf16 v[0:3], v[186:189], v[218:221], v[0:3]
	v_mfma_f32_16x16x32_bf16 v[4:7], v[178:181], v[218:221], v[4:7]
	v_mfma_f32_16x16x32_bf16 v[4:7], v[174:177], v[214:217], v[4:7]
	s_setprio 0
	s_barrier
	s_add_i32 s46, 0, 0x18000
	v_add_u32_e32 v166, s46, v147
	s_add_i32 s47, 0, 0x1c000
	ds_read_b128 v[152:155], v166
	ds_read_b128 v[156:159], v166 offset:1024
	ds_read_b128 v[160:163], v166 offset:2048
	ds_read_b128 v[170:173], v166 offset:3072
	v_add_u32_e32 v166, s47, v147
	ds_read_b128 v[174:177], v166
	ds_read_b128 v[178:181], v166 offset:1024
	ds_read_b128 v[182:185], v166 offset:2048
	ds_read_b128 v[186:189], v166 offset:3072
	s_add_u32 s38, s38, 0x80000
	s_addc_u32 s39, s39, 0
	s_mov_b32 m0, s40
	v_lshl_add_u64 v[226:227], s[38:39], 0, v[128:129]
	ds_read_b128 v[190:193], v151 offset:32768
	ds_read_b128 v[194:197], v151 offset:33792
	ds_read_b128 v[198:201], v151 offset:34816
	ds_read_b128 v[202:205], v151 offset:35840
	ds_read_b128 v[206:209], v151 offset:36864
	ds_read_b128 v[210:213], v151 offset:37888
	ds_read_b128 v[214:217], v151 offset:38912
	ds_read_b128 v[218:221], v151 offset:39936
	global_load_lds_dwordx4 v[226:227], off
	v_lshl_add_u64 v[226:227], s[38:39], 0, v[132:133]
	s_mov_b32 m0, s41
	s_nop 0
	global_load_lds_dwordx4 v[226:227], off
	s_waitcnt vmcnt(8)
	s_waitcnt lgkmcnt(0)
	s_barrier
	s_setprio 1
	s_waitcnt lgkmcnt(0)
	v_mfma_f32_16x16x32_bf16 v[124:127], v[152:155], v[190:193], v[124:127]
	v_mfma_f32_16x16x32_bf16 v[124:127], v[156:159], v[194:197], v[124:127]
	v_mfma_f32_16x16x32_bf16 v[120:123], v[170:173], v[194:197], v[120:123]
	v_mfma_f32_16x16x32_bf16 v[120:123], v[160:163], v[190:193], v[120:123]
	v_mfma_f32_16x16x32_bf16 v[108:111], v[160:163], v[198:201], v[108:111]
	v_mfma_f32_16x16x32_bf16 v[108:111], v[170:173], v[202:205], v[108:111]
	v_mfma_f32_16x16x32_bf16 v[116:119], v[156:159], v[202:205], v[116:119]
	v_mfma_f32_16x16x32_bf16 v[116:119], v[152:155], v[198:201], v[116:119]
	v_mfma_f32_16x16x32_bf16 v[100:103], v[152:155], v[206:209], v[100:103]
	v_mfma_f32_16x16x32_bf16 v[100:103], v[156:159], v[210:213], v[100:103]
	v_mfma_f32_16x16x32_bf16 v[92:95], v[170:173], v[210:213], v[92:95]
	v_mfma_f32_16x16x32_bf16 v[92:95], v[160:163], v[206:209], v[92:95]
	v_mfma_f32_16x16x32_bf16 v[76:79], v[160:163], v[214:217], v[76:79]
	v_mfma_f32_16x16x32_bf16 v[76:79], v[170:173], v[218:221], v[76:79]
	v_mfma_f32_16x16x32_bf16 v[84:87], v[156:159], v[218:221], v[84:87]
	v_mfma_f32_16x16x32_bf16 v[84:87], v[152:155], v[214:217], v[84:87]
	s_setprio 0
	s_setprio 1
	v_mfma_f32_16x16x32_bf16 v[112:115], v[174:177], v[190:193], v[112:115]
	v_mfma_f32_16x16x32_bf16 v[112:115], v[178:181], v[194:197], v[112:115]
	v_mfma_f32_16x16x32_bf16 v[104:107], v[186:189], v[194:197], v[104:107]
	v_mfma_f32_16x16x32_bf16 v[104:107], v[182:185], v[190:193], v[104:107]
	v_mfma_f32_16x16x32_bf16 v[88:91], v[182:185], v[198:201], v[88:91]
	v_mfma_f32_16x16x32_bf16 v[88:91], v[186:189], v[202:205], v[88:91]
	v_mfma_f32_16x16x32_bf16 v[96:99], v[178:181], v[202:205], v[96:99]
	v_mfma_f32_16x16x32_bf16 v[96:99], v[174:177], v[198:201], v[96:99]
	v_mfma_f32_16x16x32_bf16 v[80:83], v[174:177], v[206:209], v[80:83]
	v_mfma_f32_16x16x32_bf16 v[80:83], v[178:181], v[210:213], v[80:83]
	v_mfma_f32_16x16x32_bf16 v[72:75], v[186:189], v[210:213], v[72:75]
	v_mfma_f32_16x16x32_bf16 v[72:75], v[182:185], v[206:209], v[72:75]
	v_mfma_f32_16x16x32_bf16 v[64:67], v[182:185], v[214:217], v[64:67]
	v_mfma_f32_16x16x32_bf16 v[64:67], v[186:189], v[218:221], v[64:67]
	v_mfma_f32_16x16x32_bf16 v[68:71], v[178:181], v[218:221], v[68:71]
	v_mfma_f32_16x16x32_bf16 v[68:71], v[174:177], v[214:217], v[68:71]
	s_setprio 0
	s_barrier
; #define PG8_STAGE(bufoff, gbase, voff) do { _Pragma("unroll") for (int _i = 0; _i < 2; ++_i) \
;         __builtin_amdgcn_global_load_lds((const unsigned*)((const char*)(gbase) + (voff)[_i]), (LAS unsigned*)(lds + (bufoff) + ldsw + _i * 8192), 16, 0, 0); } while (0)
; #define PG8_LDA(dst, b, h) do { _Pragma("unroll") for (int m = 0; m < 4; ++m) _Pragma("unroll") for (int k = 0; k < 2; ++k) dst[m][k] = *(const LAS bf16x8*)(lds + PG8_SA(b, h) + aoff + m * 2048 + k * 1024); } while (0)
; #define PG8_LDB(dst, b, h) do { _Pragma("unroll") for (int n = 0; n < 2; ++n) _Pragma("unroll") for (int k = 0; k < 2; ++k) dst[n][k] = *(const LAS bf16x8*)(lds + PG8_SB(b, h) + boff + n * 2048 + k * 1024); } while (0)
; #define PG8_MMA(ai, bj, At, Bt) do { __builtin_amdgcn_s_setprio(1); _Pragma("unroll") for (int m = 0; m < 4; ++m) _Pragma("unroll") for (int n = 0; n < 2; ++n) _Pragma("unroll") for (int k = 0; k < 2; ++k) \
;         acc[ai][bj][m][n] = __builtin_amdgcn_mfma_f32_16x16x32_bf16(Bt[n][k], At[m][k], acc[ai][bj][m][n], 0, 0, 0); __builtin_amdgcn_s_setprio(0); } while (0)
; #define PG8_WAIT_V(n) asm volatile("s_waitcnt vmcnt(" #n ")" ::: "memory")
; #define PG8_WAIT_L(n) asm volatile("s_waitcnt lgkmcnt(" #n ")" ::: "memory")
; #define PG8_BAR __builtin_amdgcn_s_barrier()
; #define PG8_SCHED __builtin_amdgcn_sched_barrier(0)
; DI void gemm_phase(LAS unsigned char* lds, const Gemm g, const StaticOrder& S, const Epi& E) {
;     ...
;             PG8_LDB(B0, 1, 0); PG8_LDB(B1, 1, 1); PG8_SCHED; PG8_LDA(At, 1, 0); PG8_STAGE(PG8_SA(0, 1), a2 + hsA, voffA);
;             PG8_WAIT_V(8); PG8_WAIT_L(0); PG8_BAR; PG8_MMA(0, 0, At, B0); PG8_MMA(0, 1, At, B1); PG8_BAR; PG8_SCHED;
;             PG8_LDA(At, 1, 1); PG8_STAGE(PG8_SB(1, 0), b3, voffB); PG8_STAGE(PG8_SB(1, 1), b3 + hsB, voffB); PG8_STAGE(PG8_SA(1, 0), a3, voffA);
;             PG8_WAIT_V(8); PG8_WAIT_L(0); PG8_BAR; PG8_MMA(1, 0, At, B0); PG8_MMA(1, 1, At, B1); PG8_BAR; PG8_SCHED;
;         }
;         if (wr == 0) PG8_BAR;
	s_add_i32 s38, s46, s12
	v_lshl_add_u64 v[144:145], v[144:145], 0, s[16:17]
	s_mov_b32 m0, s38
	ds_read_b128 v[190:193], v151 offset:49152
	ds_read_b128 v[194:197], v151 offset:50176
	ds_read_b128 v[198:201], v151 offset:51200
	ds_read_b128 v[202:205], v151 offset:52224
	ds_read_b128 v[206:209], v151 offset:53248
	ds_read_b128 v[210:213], v151 offset:54272
	ds_read_b128 v[214:217], v151 offset:55296
	ds_read_b128 v[218:221], v151 offset:56320
	global_load_lds_dwordx4 v[144:145], off
	s_add_i32 m0, s38, 0x2000
	s_add_u32 s34, s34, 0x80080
	v_lshl_add_u64 v[144:145], v[164:165], 0, s[16:17]
	s_addc_u32 s35, s35, 0
	s_add_i32 s38, s47, s12
	global_load_lds_dwordx4 v[144:145], off
	v_lshl_add_u64 v[144:145], s[34:35], 0, v[130:131]
	s_mov_b32 m0, s38
	s_nop 0
	global_load_lds_dwordx4 v[144:145], off
	v_lshl_add_u64 v[144:145], s[34:35], 0, v[134:135]
	s_add_i32 m0, s38, 0x2000
	s_nop 0
	global_load_lds_dwordx4 v[144:145], off
	v_lshl_add_u64 v[144:145], v[222:223], 0, s[16:17]
	s_mov_b32 m0, s43
	s_nop 0
	global_load_lds_dwordx4 v[144:145], off
	v_lshl_add_u64 v[144:145], v[224:225], 0, s[16:17]
	s_mov_b32 m0, s48
	s_nop 0
	global_load_lds_dwordx4 v[144:145], off
	s_waitcnt vmcnt(8)
	s_waitcnt lgkmcnt(0)
	s_barrier
	s_setprio 1
	s_waitcnt lgkmcnt(0)
	v_mfma_f32_16x16x32_bf16 v[60:63], v[152:155], v[190:193], v[60:63]
	v_mfma_f32_16x16x32_bf16 v[60:63], v[156:159], v[194:197], v[60:63]
	v_mfma_f32_16x16x32_bf16 v[56:59], v[170:173], v[194:197], v[56:59]
	v_mfma_f32_16x16x32_bf16 v[56:59], v[160:163], v[190:193], v[56:59]
	v_mfma_f32_16x16x32_bf16 v[44:47], v[160:163], v[198:201], v[44:47]
	v_mfma_f32_16x16x32_bf16 v[44:47], v[170:173], v[202:205], v[44:47]
	v_mfma_f32_16x16x32_bf16 v[52:55], v[156:159], v[202:205], v[52:55]
	v_mfma_f32_16x16x32_bf16 v[52:55], v[152:155], v[198:201], v[52:55]
	v_mfma_f32_16x16x32_bf16 v[36:39], v[152:155], v[206:209], v[36:39]
	v_mfma_f32_16x16x32_bf16 v[36:39], v[156:159], v[210:213], v[36:39]
	v_mfma_f32_16x16x32_bf16 v[28:31], v[170:173], v[210:213], v[28:31]
	v_mfma_f32_16x16x32_bf16 v[28:31], v[160:163], v[206:209], v[28:31]
	v_mfma_f32_16x16x32_bf16 v[12:15], v[160:163], v[214:217], v[12:15]
	v_mfma_f32_16x16x32_bf16 v[12:15], v[170:173], v[218:221], v[12:15]
	v_mfma_f32_16x16x32_bf16 v[20:23], v[156:159], v[218:221], v[20:23]
	v_mfma_f32_16x16x32_bf16 v[20:23], v[152:155], v[214:217], v[20:23]
	s_setprio 0
	s_setprio 1
	v_mfma_f32_16x16x32_bf16 v[48:51], v[174:177], v[190:193], v[48:51]
	v_mfma_f32_16x16x32_bf16 v[48:51], v[178:181], v[194:197], v[48:51]
	v_mfma_f32_16x16x32_bf16 v[40:43], v[186:189], v[194:197], v[40:43]
	v_mfma_f32_16x16x32_bf16 v[40:43], v[182:185], v[190:193], v[40:43]
	v_mfma_f32_16x16x32_bf16 v[24:27], v[182:185], v[198:201], v[24:27]
	v_mfma_f32_16x16x32_bf16 v[24:27], v[186:189], v[202:205], v[24:27]
	v_mfma_f32_16x16x32_bf16 v[32:35], v[178:181], v[202:205], v[32:35]
	v_mfma_f32_16x16x32_bf16 v[32:35], v[174:177], v[198:201], v[32:35]
	v_mfma_f32_16x16x32_bf16 v[16:19], v[174:177], v[206:209], v[16:19]
	v_mfma_f32_16x16x32_bf16 v[16:19], v[178:181], v[210:213], v[16:19]
	v_mfma_f32_16x16x32_bf16 v[8:11], v[186:189], v[210:213], v[8:11]
	v_mfma_f32_16x16x32_bf16 v[8:11], v[182:185], v[206:209], v[8:11]
	v_mfma_f32_16x16x32_bf16 v[0:3], v[182:185], v[214:217], v[0:3]
	v_mfma_f32_16x16x32_bf16 v[0:3], v[186:189], v[218:221], v[0:3]
	v_mfma_f32_16x16x32_bf16 v[4:7], v[178:181], v[218:221], v[4:7]
	v_mfma_f32_16x16x32_bf16 v[4:7], v[174:177], v[214:217], v[4:7]
	s_setprio 0
	s_barrier
	s_add_i32 s56, s56, 2
	s_add_u32 s30, s30, 0x100
	s_addc_u32 s31, s31, 0
	s_add_u32 s54, s54, 0x100
	s_addc_u32 s55, s55, 0
	s_cmp_gt_u32 s56, 29
	s_cbranch_scc0 .LBB0_177
	s_and_b64 vcc, exec, s[18:19]
	s_cbranch_vccz .LBB0_180
	s_barrier

; #define PG8_STAGE(bufoff, gbase, voff) do { _Pragma("unroll") for (int _i = 0; _i < 2; ++_i) \
;         __builtin_amdgcn_global_load_lds((const unsigned*)((const char*)(gbase) + (voff)[_i]), (LAS unsigned*)(lds + (bufoff) + ldsw + _i * 8192), 16, 0, 0); } while (0)
; #define PG8_LDA(dst, b, h) do { _Pragma("unroll") for (int m = 0; m < 4; ++m) _Pragma("unroll") for (int k = 0; k < 2; ++k) dst[m][k] = *(const LAS bf16x8*)(lds + PG8_SA(b, h) + aoff + m * 2048 + k * 1024); } while (0)
; #define PG8_LDB(dst, b, h) do { _Pragma("unroll") for (int n = 0; n < 2; ++n) _Pragma("unroll") for (int k = 0; k < 2; ++k) dst[n][k] = *(const LAS bf16x8*)(lds + PG8_SB(b, h) + boff + n * 2048 + k * 1024); } while (0)
; #define PG8_MMA(ai, bj, At, Bt) do { __builtin_amdgcn_s_setprio(1); _Pragma("unroll") for (int m = 0; m < 4; ++m) _Pragma("unroll") for (int n = 0; n < 2; ++n) _Pragma("unroll") for (int k = 0; k < 2; ++k) \
;         acc[ai][bj][m][n] = __builtin_amdgcn_mfma_f32_16x16x32_bf16(Bt[n][k], At[m][k], acc[ai][bj][m][n], 0, 0, 0); __builtin_amdgcn_s_setprio(0); } while (0)
; #define PG8_WAIT_V(n) asm volatile("s_waitcnt vmcnt(" #n ")" ::: "memory")
; #define PG8_WAIT_L(n) asm volatile("s_waitcnt lgkmcnt(" #n ")" ::: "memory")
; #define PG8_BAR __builtin_amdgcn_s_barrier()
; #define PG8_SCHED __builtin_amdgcn_sched_barrier(0)
; DI void gemm_phase(LAS unsigned char* lds, const Gemm g, const StaticOrder& S, const Epi& E) {
;     ...
;             PG8_LDB(B0, 0, 0); PG8_LDB(B1, 0, 1); PG8_SCHED; PG8_LDA(At, 0, 0); PG8_STAGE(PG8_SA(1, 1), a1 + hsA, voffA);
;             PG8_WAIT_V(8); PG8_WAIT_L(0); PG8_BAR; PG8_MMA(0, 0, At, B0); PG8_MMA(0, 1, At, B1); PG8_BAR; PG8_SCHED;
;             PG8_LDA(At, 0, 1); PG8_STAGE(PG8_SB(0, 0), b2, voffB); PG8_STAGE(PG8_SB(0, 1), b2 + hsB, voffB); PG8_STAGE(PG8_SA(0, 0), a2, voffA);
;             PG8_WAIT_V(8); PG8_WAIT_L(0); PG8_BAR; PG8_MMA(1, 0, At, B0); PG8_MMA(1, 1, At, B1); PG8_BAR; PG8_SCHED;
.LBB0_343:
	ds_read_b128 v[146:149], v159
	ds_read_b128 v[150:153], v159 offset:1024
	ds_read_b128 v[162:165], v159 offset:2048
	ds_read_b128 v[170:173], v159 offset:3072
	ds_read_b128 v[174:177], v160
	ds_read_b128 v[178:181], v160 offset:1024
	ds_read_b128 v[182:185], v160 offset:2048
	ds_read_b128 v[186:189], v160 offset:3072
	s_add_u32 s4, s34, 0x100
	s_addc_u32 s5, s35, 0
	s_cmp_eq_u32 s70, 4
	s_cselect_b32 s53, s27, s5
	s_cselect_b32 s52, s26, s4
	s_cselect_b32 s51, s25, s69
	s_cselect_b32 s50, s31, s68
	v_lshl_add_u64 v[154:155], s[34:35], 0, v[138:139]
	s_add_i32 m0, s13, 0xc000
	ds_read_b128 v[190:193], v161
	ds_read_b128 v[194:197], v161 offset:1024
	ds_read_b128 v[198:201], v161 offset:2048
	ds_read_b128 v[202:205], v161 offset:3072
	ds_read_b128 v[206:209], v161 offset:4096
	ds_read_b128 v[210:213], v161 offset:5120
	ds_read_b128 v[214:217], v161 offset:6144
	ds_read_b128 v[218:221], v161 offset:7168
	global_load_lds_dwordx4 v[154:155], off
	v_lshl_add_u64 v[154:155], s[34:35], 0, v[140:141]
	s_add_i32 m0, s13, 0xe000
	s_nop 0
	global_load_lds_dwordx4 v[154:155], off
	s_waitcnt vmcnt(8)
	s_waitcnt lgkmcnt(0)
	s_barrier
	s_setprio 1
	s_waitcnt lgkmcnt(0)
	v_mfma_f32_16x16x32_bf16 v[124:127], v[146:149], v[190:193], v[124:127]
	v_mfma_f32_16x16x32_bf16 v[124:127], v[150:153], v[194:197], v[124:127]
	v_mfma_f32_16x16x32_bf16 v[120:123], v[170:173], v[194:197], v[120:123]
	v_mfma_f32_16x16x32_bf16 v[120:123], v[162:165], v[190:193], v[120:123]
	v_mfma_f32_16x16x32_bf16 v[104:107], v[162:165], v[198:201], v[104:107]
	v_mfma_f32_16x16x32_bf16 v[104:107], v[170:173], v[202:205], v[104:107]
	v_mfma_f32_16x16x32_bf16 v[108:111], v[150:153], v[202:205], v[108:111]
	v_mfma_f32_16x16x32_bf16 v[108:111], v[146:149], v[198:201], v[108:111]
	v_mfma_f32_16x16x32_bf16 v[92:95], v[146:149], v[206:209], v[92:95]
	v_mfma_f32_16x16x32_bf16 v[92:95], v[150:153], v[210:213], v[92:95]
	v_mfma_f32_16x16x32_bf16 v[88:91], v[170:173], v[210:213], v[88:91]
	v_mfma_f32_16x16x32_bf16 v[88:91], v[162:165], v[206:209], v[88:91]
	v_mfma_f32_16x16x32_bf16 v[72:75], v[162:165], v[214:217], v[72:75]
	v_mfma_f32_16x16x32_bf16 v[72:75], v[170:173], v[218:221], v[72:75]
	v_mfma_f32_16x16x32_bf16 v[76:79], v[150:153], v[218:221], v[76:79]
	v_mfma_f32_16x16x32_bf16 v[76:79], v[146:149], v[214:217], v[76:79]
	s_setprio 0
	s_setprio 1
	v_mfma_f32_16x16x32_bf16 v[116:119], v[174:177], v[190:193], v[116:119]
	v_mfma_f32_16x16x32_bf16 v[116:119], v[178:181], v[194:197], v[116:119]
	v_mfma_f32_16x16x32_bf16 v[112:115], v[186:189], v[194:197], v[112:115]
	v_mfma_f32_16x16x32_bf16 v[112:115], v[182:185], v[190:193], v[112:115]
	v_mfma_f32_16x16x32_bf16 v[96:99], v[182:185], v[198:201], v[96:99]
	v_mfma_f32_16x16x32_bf16 v[96:99], v[186:189], v[202:205], v[96:99]
	v_mfma_f32_16x16x32_bf16 v[100:103], v[178:181], v[202:205], v[100:103]
	v_mfma_f32_16x16x32_bf16 v[100:103], v[174:177], v[198:201], v[100:103]
	v_mfma_f32_16x16x32_bf16 v[84:87], v[174:177], v[206:209], v[84:87]
	v_mfma_f32_16x16x32_bf16 v[84:87], v[178:181], v[210:213], v[84:87]
	v_mfma_f32_16x16x32_bf16 v[80:83], v[186:189], v[210:213], v[80:83]
	v_mfma_f32_16x16x32_bf16 v[80:83], v[182:185], v[206:209], v[80:83]
	v_mfma_f32_16x16x32_bf16 v[64:67], v[182:185], v[214:217], v[64:67]
	v_mfma_f32_16x16x32_bf16 v[64:67], v[186:189], v[218:221], v[64:67]
	v_mfma_f32_16x16x32_bf16 v[68:71], v[178:181], v[218:221], v[68:71]
	v_mfma_f32_16x16x32_bf16 v[68:71], v[174:177], v[214:217], v[68:71]
	s_setprio 0
	s_barrier
	s_add_i32 s34, s56, s12
	v_lshl_add_u64 v[154:155], s[50:51], 0, v[130:131]
	s_mov_b32 m0, s34
	ds_read_b128 v[190:193], v161 offset:16384
	ds_read_b128 v[194:197], v161 offset:17408
	ds_read_b128 v[198:201], v161 offset:18432
	ds_read_b128 v[202:205], v161 offset:19456
	ds_read_b128 v[206:209], v161 offset:20480
	ds_read_b128 v[210:213], v161 offset:21504
	ds_read_b128 v[214:217], v161 offset:22528
	ds_read_b128 v[218:221], v161 offset:23552
	global_load_lds_dwordx4 v[154:155], off
	s_add_i32 m0, s34, 0x2000
	s_add_u32 s34, s50, 0x20000
	v_lshl_add_u64 v[222:223], s[50:51], 0, v[134:135]
	s_addc_u32 s35, s51, 0
	s_add_i32 s46, s57, s12
	global_load_lds_dwordx4 v[222:223], off
	v_lshl_add_u64 v[224:225], s[34:35], 0, v[130:131]
	s_mov_b32 m0, s46
	v_lshl_add_u64 v[226:227], s[52:53], 0, v[132:133]
	global_load_lds_dwordx4 v[224:225], off
	v_lshl_add_u64 v[224:225], s[34:35], 0, v[134:135]
	s_add_i32 m0, s46, 0x2000
	s_nop 0
	global_load_lds_dwordx4 v[224:225], off
	v_lshl_add_u64 v[224:225], s[52:53], 0, v[128:129]
	s_mov_b32 m0, s13
	s_nop 0
	global_load_lds_dwordx4 v[224:225], off
	s_mov_b32 m0, s33
	s_nop 0
	global_load_lds_dwordx4 v[226:227], off
	s_waitcnt vmcnt(8)
	s_waitcnt lgkmcnt(0)
	s_barrier
; #define PG8_STAGE(bufoff, gbase, voff) do { _Pragma("unroll") for (int _i = 0; _i < 2; ++_i) \
;         __builtin_amdgcn_global_load_lds((const unsigned*)((const char*)(gbase) + (voff)[_i]), (LAS unsigned*)(lds + (bufoff) + ldsw + _i * 8192), 16, 0, 0); } while (0)
; #define PG8_LDA(dst, b, h) do { _Pragma("unroll") for (int m = 0; m < 4; ++m) _Pragma("unroll") for (int k = 0; k < 2; ++k) dst[m][k] = *(const LAS bf16x8*)(lds + PG8_SA(b, h) + aoff + m * 2048 + k * 1024); } while (0)
; #define PG8_LDB(dst, b, h) do { _Pragma("unroll") for (int n = 0; n < 2; ++n) _Pragma("unroll") for (int k = 0; k < 2; ++k) dst[n][k] = *(const LAS bf16x8*)(lds + PG8_SB(b, h) + boff + n * 2048 + k * 1024); } while (0)
; #define PG8_MMA(ai, bj, At, Bt) do { __builtin_amdgcn_s_setprio(1); _Pragma("unroll") for (int m = 0; m < 4; ++m) _Pragma("unroll") for (int n = 0; n < 2; ++n) _Pragma("unroll") for (int k = 0; k < 2; ++k) \
;         acc[ai][bj][m][n] = __builtin_amdgcn_mfma_f32_16x16x32_bf16(Bt[n][k], At[m][k], acc[ai][bj][m][n], 0, 0, 0); __builtin_amdgcn_s_setprio(0); } while (0)
; #define PG8_WAIT_V(n) asm volatile("s_waitcnt vmcnt(" #n ")" ::: "memory")
; #define PG8_WAIT_L(n) asm volatile("s_waitcnt lgkmcnt(" #n ")" ::: "memory")
; DI void gemm_phase(LAS unsigned char* lds, const Gemm g, const StaticOrder& S, const Epi& E) {
;     ...
;             PG8_LDB(B0, 0, 0); PG8_LDB(B1, 0, 1); PG8_SCHED; PG8_LDA(At, 0, 0); PG8_STAGE(PG8_SA(1, 1), a1 + hsA, voffA);
;             PG8_WAIT_V(8); PG8_WAIT_L(0); PG8_BAR; PG8_MMA(0, 0, At, B0); PG8_MMA(0, 1, At, B1); PG8_BAR; PG8_SCHED;
;             PG8_LDA(At, 0, 1); PG8_STAGE(PG8_SB(0, 0), b2, voffB); PG8_STAGE(PG8_SB(0, 1), b2 + hsB, voffB); PG8_STAGE(PG8_SA(0, 0), a2, voffA);
;             PG8_WAIT_V(8); PG8_WAIT_L(0); PG8_BAR; PG8_MMA(1, 0, At, B0); PG8_MMA(1, 1, At, B1); PG8_BAR; PG8_SCHED;
;             PG8_LDB(B0, 1, 0); PG8_LDB(B1, 1, 1); PG8_SCHED; PG8_LDA(At, 1, 0); PG8_STAGE(PG8_SA(0, 1), a2 + hsA, voffA);
;             PG8_WAIT_V(8); PG8_WAIT_L(0); PG8_BAR; PG8_MMA(0, 0, At, B0); PG8_MMA(0, 1, At, B1); PG8_BAR; PG8_SCHED;
;             PG8_LDA(At, 1, 1); PG8_STAGE(PG8_SB(1, 0), b3, voffB); PG8_STAGE(PG8_SB(1, 1), b3 + hsB, voffB); PG8_STAGE(PG8_SA(1, 0), a3, voffA);
;             PG8_WAIT_V(8); PG8_WAIT_L(0); PG8_BAR; PG8_MMA(1, 0, At, B0); PG8_MMA(1, 1, At, B1); PG8_BAR; PG8_SCHED;
	s_setprio 1
	s_waitcnt lgkmcnt(0)
	v_mfma_f32_16x16x32_bf16 v[60:63], v[146:149], v[190:193], v[60:63]
	v_mfma_f32_16x16x32_bf16 v[60:63], v[150:153], v[194:197], v[60:63]
	v_mfma_f32_16x16x32_bf16 v[56:59], v[170:173], v[194:197], v[56:59]
	v_mfma_f32_16x16x32_bf16 v[56:59], v[162:165], v[190:193], v[56:59]
	v_mfma_f32_16x16x32_bf16 v[40:43], v[162:165], v[198:201], v[40:43]
	v_mfma_f32_16x16x32_bf16 v[40:43], v[170:173], v[202:205], v[40:43]
	v_mfma_f32_16x16x32_bf16 v[44:47], v[150:153], v[202:205], v[44:47]
	v_mfma_f32_16x16x32_bf16 v[44:47], v[146:149], v[198:201], v[44:47]
	v_mfma_f32_16x16x32_bf16 v[28:31], v[146:149], v[206:209], v[28:31]
	v_mfma_f32_16x16x32_bf16 v[28:31], v[150:153], v[210:213], v[28:31]
	v_mfma_f32_16x16x32_bf16 v[24:27], v[170:173], v[210:213], v[24:27]
	v_mfma_f32_16x16x32_bf16 v[24:27], v[162:165], v[206:209], v[24:27]
	v_mfma_f32_16x16x32_bf16 v[8:11], v[162:165], v[214:217], v[8:11]
	v_mfma_f32_16x16x32_bf16 v[8:11], v[170:173], v[218:221], v[8:11]
	v_mfma_f32_16x16x32_bf16 v[12:15], v[150:153], v[218:221], v[12:15]
	v_mfma_f32_16x16x32_bf16 v[12:15], v[146:149], v[214:217], v[12:15]
	s_setprio 0
	s_setprio 1
	v_mfma_f32_16x16x32_bf16 v[52:55], v[174:177], v[190:193], v[52:55]
	v_mfma_f32_16x16x32_bf16 v[52:55], v[178:181], v[194:197], v[52:55]
	v_mfma_f32_16x16x32_bf16 v[48:51], v[186:189], v[194:197], v[48:51]
	v_mfma_f32_16x16x32_bf16 v[48:51], v[182:185], v[190:193], v[48:51]
	v_mfma_f32_16x16x32_bf16 v[32:35], v[182:185], v[198:201], v[32:35]
	v_mfma_f32_16x16x32_bf16 v[32:35], v[186:189], v[202:205], v[32:35]
	v_mfma_f32_16x16x32_bf16 v[36:39], v[178:181], v[202:205], v[36:39]
	v_mfma_f32_16x16x32_bf16 v[36:39], v[174:177], v[198:201], v[36:39]
	v_mfma_f32_16x16x32_bf16 v[20:23], v[174:177], v[206:209], v[20:23]
	v_mfma_f32_16x16x32_bf16 v[20:23], v[178:181], v[210:213], v[20:23]
	v_mfma_f32_16x16x32_bf16 v[16:19], v[186:189], v[210:213], v[16:19]
	v_mfma_f32_16x16x32_bf16 v[16:19], v[182:185], v[206:209], v[16:19]
	v_mfma_f32_16x16x32_bf16 v[0:3], v[182:185], v[214:217], v[0:3]
	v_mfma_f32_16x16x32_bf16 v[0:3], v[186:189], v[218:221], v[0:3]
	v_mfma_f32_16x16x32_bf16 v[4:7], v[178:181], v[218:221], v[4:7]
	v_mfma_f32_16x16x32_bf16 v[4:7], v[174:177], v[214:217], v[4:7]
	s_setprio 0
	s_barrier
	s_add_i32 s46, 0, 0x18000
	v_add_u32_e32 v136, s46, v157
	s_add_i32 s47, 0, 0x1c000
	ds_read_b128 v[146:149], v136
	ds_read_b128 v[150:153], v136 offset:1024
	ds_read_b128 v[162:165], v136 offset:2048
	ds_read_b128 v[170:173], v136 offset:3072
	v_add_u32_e32 v136, s47, v157
	ds_read_b128 v[174:177], v136
	ds_read_b128 v[178:181], v136 offset:1024
	ds_read_b128 v[182:185], v136 offset:2048
	ds_read_b128 v[186:189], v136 offset:3072
	s_add_u32 s34, s52, 0xb0000
	s_addc_u32 s35, s53, 0
	s_mov_b32 m0, s40
	v_lshl_add_u64 v[228:229], s[34:35], 0, v[128:129]
	ds_read_b128 v[190:193], v161 offset:32768
	ds_read_b128 v[194:197], v161 offset:33792
	ds_read_b128 v[198:201], v161 offset:34816
	ds_read_b128 v[202:205], v161 offset:35840
	ds_read_b128 v[206:209], v161 offset:36864
	ds_read_b128 v[210:213], v161 offset:37888
	ds_read_b128 v[214:217], v161 offset:38912
	ds_read_b128 v[218:221], v161 offset:39936
	global_load_lds_dwordx4 v[228:229], off
	v_lshl_add_u64 v[228:229], s[34:35], 0, v[132:133]
	s_mov_b32 m0, s41
	s_nop 0
	global_load_lds_dwordx4 v[228:229], off
	s_waitcnt vmcnt(8)
	s_waitcnt lgkmcnt(0)
	s_barrier
	s_setprio 1
	s_waitcnt lgkmcnt(0)
	v_mfma_f32_16x16x32_bf16 v[124:127], v[146:149], v[190:193], v[124:127]
	v_mfma_f32_16x16x32_bf16 v[124:127], v[150:153], v[194:197], v[124:127]
	v_mfma_f32_16x16x32_bf16 v[120:123], v[170:173], v[194:197], v[120:123]
	v_mfma_f32_16x16x32_bf16 v[120:123], v[162:165], v[190:193], v[120:123]
	v_mfma_f32_16x16x32_bf16 v[104:107], v[162:165], v[198:201], v[104:107]
	v_mfma_f32_16x16x32_bf16 v[104:107], v[170:173], v[202:205], v[104:107]
	v_mfma_f32_16x16x32_bf16 v[108:111], v[150:153], v[202:205], v[108:111]
	v_mfma_f32_16x16x32_bf16 v[108:111], v[146:149], v[198:201], v[108:111]
	v_mfma_f32_16x16x32_bf16 v[92:95], v[146:149], v[206:209], v[92:95]
	v_mfma_f32_16x16x32_bf16 v[92:95], v[150:153], v[210:213], v[92:95]
	v_mfma_f32_16x16x32_bf16 v[88:91], v[170:173], v[210:213], v[88:91]
	v_mfma_f32_16x16x32_bf16 v[88:91], v[162:165], v[206:209], v[88:91]
	v_mfma_f32_16x16x32_bf16 v[72:75], v[162:165], v[214:217], v[72:75]
	v_mfma_f32_16x16x32_bf16 v[72:75], v[170:173], v[218:221], v[72:75]
	v_mfma_f32_16x16x32_bf16 v[76:79], v[150:153], v[218:221], v[76:79]
	v_mfma_f32_16x16x32_bf16 v[76:79], v[146:149], v[214:217], v[76:79]
	s_setprio 0
	s_setprio 1
	v_mfma_f32_16x16x32_bf16 v[116:119], v[174:177], v[190:193], v[116:119]
	v_mfma_f32_16x16x32_bf16 v[116:119], v[178:181], v[194:197], v[116:119]
	v_mfma_f32_16x16x32_bf16 v[112:115], v[186:189], v[194:197], v[112:115]
	v_mfma_f32_16x16x32_bf16 v[112:115], v[182:185], v[190:193], v[112:115]
	v_mfma_f32_16x16x32_bf16 v[96:99], v[182:185], v[198:201], v[96:99]
	v_mfma_f32_16x16x32_bf16 v[96:99], v[186:189], v[202:205], v[96:99]
	v_mfma_f32_16x16x32_bf16 v[100:103], v[178:181], v[202:205], v[100:103]
	v_mfma_f32_16x16x32_bf16 v[100:103], v[174:177], v[198:201], v[100:103]
	v_mfma_f32_16x16x32_bf16 v[84:87], v[174:177], v[206:209], v[84:87]
	v_mfma_f32_16x16x32_bf16 v[84:87], v[178:181], v[210:213], v[84:87]
	v_mfma_f32_16x16x32_bf16 v[80:83], v[186:189], v[210:213], v[80:83]
	v_mfma_f32_16x16x32_bf16 v[80:83], v[182:185], v[206:209], v[80:83]
	v_mfma_f32_16x16x32_bf16 v[64:67], v[182:185], v[214:217], v[64:67]
	v_mfma_f32_16x16x32_bf16 v[64:67], v[186:189], v[218:221], v[64:67]
	v_mfma_f32_16x16x32_bf16 v[68:71], v[178:181], v[218:221], v[68:71]
	v_mfma_f32_16x16x32_bf16 v[68:71], v[174:177], v[214:217], v[68:71]
	s_setprio 0
	s_barrier
; #define PG8_STAGE(bufoff, gbase, voff) do { _Pragma("unroll") for (int _i = 0; _i < 2; ++_i) \
;         __builtin_amdgcn_global_load_lds((const unsigned*)((const char*)(gbase) + (voff)[_i]), (LAS unsigned*)(lds + (bufoff) + ldsw + _i * 8192), 16, 0, 0); } while (0)
; #define PG8_LDA(dst, b, h) do { _Pragma("unroll") for (int m = 0; m < 4; ++m) _Pragma("unroll") for (int k = 0; k < 2; ++k) dst[m][k] = *(const LAS bf16x8*)(lds + PG8_SA(b, h) + aoff + m * 2048 + k * 1024); } while (0)
; #define PG8_LDB(dst, b, h) do { _Pragma("unroll") for (int n = 0; n < 2; ++n) _Pragma("unroll") for (int k = 0; k < 2; ++k) dst[n][k] = *(const LAS bf16x8*)(lds + PG8_SB(b, h) + boff + n * 2048 + k * 1024); } while (0)
; #define PG8_MMA(ai, bj, At, Bt) do { __builtin_amdgcn_s_setprio(1); _Pragma("unroll") for (int m = 0; m < 4; ++m) _Pragma("unroll") for (int n = 0; n < 2; ++n) _Pragma("unroll") for (int k = 0; k < 2; ++k) \
;         acc[ai][bj][m][n] = __builtin_amdgcn_mfma_f32_16x16x32_bf16(Bt[n][k], At[m][k], acc[ai][bj][m][n], 0, 0, 0); __builtin_amdgcn_s_setprio(0); } while (0)
; #define PG8_WAIT_V(n) asm volatile("s_waitcnt vmcnt(" #n ")" ::: "memory")
; #define PG8_WAIT_L(n) asm volatile("s_waitcnt lgkmcnt(" #n ")" ::: "memory")
; #define PG8_BAR __builtin_amdgcn_s_barrier()
; #define PG8_SCHED __builtin_amdgcn_sched_barrier(0)
; DI void gemm_phase(LAS unsigned char* lds, const Gemm g, const StaticOrder& S, const Epi& E) {
;     ...
;             PG8_LDB(B0, 1, 0); PG8_LDB(B1, 1, 1); PG8_SCHED; PG8_LDA(At, 1, 0); PG8_STAGE(PG8_SA(0, 1), a2 + hsA, voffA);
;             PG8_WAIT_V(8); PG8_WAIT_L(0); PG8_BAR; PG8_MMA(0, 0, At, B0); PG8_MMA(0, 1, At, B1); PG8_BAR; PG8_SCHED;
;             PG8_LDA(At, 1, 1); PG8_STAGE(PG8_SB(1, 0), b3, voffB); PG8_STAGE(PG8_SB(1, 1), b3 + hsB, voffB); PG8_STAGE(PG8_SA(1, 0), a3, voffA);
;             PG8_WAIT_V(8); PG8_WAIT_L(0); PG8_BAR; PG8_MMA(1, 0, At, B0); PG8_MMA(1, 1, At, B1); PG8_BAR; PG8_SCHED;
;         }
;         if (wr == 0) PG8_BAR;
	s_add_i32 s34, s46, s12
	v_lshl_add_u64 v[154:155], v[154:155], 0, s[20:21]
	s_mov_b32 m0, s34
	ds_read_b128 v[190:193], v161 offset:49152
	ds_read_b128 v[194:197], v161 offset:50176
	ds_read_b128 v[198:201], v161 offset:51200
	ds_read_b128 v[202:205], v161 offset:52224
	ds_read_b128 v[206:209], v161 offset:53248
	ds_read_b128 v[210:213], v161 offset:54272
	ds_read_b128 v[214:217], v161 offset:55296
	ds_read_b128 v[218:221], v161 offset:56320
	global_load_lds_dwordx4 v[154:155], off
	s_add_i32 m0, s34, 0x2000
	s_add_u32 s34, s50, 0x20080
	v_lshl_add_u64 v[154:155], v[222:223], 0, s[20:21]
	s_addc_u32 s35, s51, 0
	s_add_i32 s46, s47, s12
	global_load_lds_dwordx4 v[154:155], off
	v_lshl_add_u64 v[154:155], s[34:35], 0, v[130:131]
	s_mov_b32 m0, s46
	s_nop 0
	global_load_lds_dwordx4 v[154:155], off
	v_lshl_add_u64 v[154:155], s[34:35], 0, v[134:135]
	s_add_i32 m0, s46, 0x2000
	s_nop 0
	global_load_lds_dwordx4 v[154:155], off
	v_lshl_add_u64 v[154:155], v[224:225], 0, s[20:21]
	s_mov_b32 m0, s48
	s_nop 0
	global_load_lds_dwordx4 v[154:155], off
	v_lshl_add_u64 v[154:155], v[226:227], 0, s[20:21]
	s_mov_b32 m0, s49
	s_nop 0
	global_load_lds_dwordx4 v[154:155], off
	s_waitcnt vmcnt(8)
	s_waitcnt lgkmcnt(0)
	s_barrier
	s_setprio 1
	s_waitcnt lgkmcnt(0)
	v_mfma_f32_16x16x32_bf16 v[60:63], v[146:149], v[190:193], v[60:63]
	v_mfma_f32_16x16x32_bf16 v[60:63], v[150:153], v[194:197], v[60:63]
	v_mfma_f32_16x16x32_bf16 v[56:59], v[170:173], v[194:197], v[56:59]
	v_mfma_f32_16x16x32_bf16 v[56:59], v[162:165], v[190:193], v[56:59]
	v_mfma_f32_16x16x32_bf16 v[40:43], v[162:165], v[198:201], v[40:43]
	v_mfma_f32_16x16x32_bf16 v[40:43], v[170:173], v[202:205], v[40:43]
	v_mfma_f32_16x16x32_bf16 v[44:47], v[150:153], v[202:205], v[44:47]
	v_mfma_f32_16x16x32_bf16 v[44:47], v[146:149], v[198:201], v[44:47]
	v_mfma_f32_16x16x32_bf16 v[28:31], v[146:149], v[206:209], v[28:31]
	v_mfma_f32_16x16x32_bf16 v[28:31], v[150:153], v[210:213], v[28:31]
	v_mfma_f32_16x16x32_bf16 v[24:27], v[170:173], v[210:213], v[24:27]
	v_mfma_f32_16x16x32_bf16 v[24:27], v[162:165], v[206:209], v[24:27]
	v_mfma_f32_16x16x32_bf16 v[8:11], v[162:165], v[214:217], v[8:11]
	v_mfma_f32_16x16x32_bf16 v[8:11], v[170:173], v[218:221], v[8:11]
	v_mfma_f32_16x16x32_bf16 v[12:15], v[150:153], v[218:221], v[12:15]
	v_mfma_f32_16x16x32_bf16 v[12:15], v[146:149], v[214:217], v[12:15]
	s_setprio 0
	s_setprio 1
	v_mfma_f32_16x16x32_bf16 v[52:55], v[174:177], v[190:193], v[52:55]
	v_mfma_f32_16x16x32_bf16 v[52:55], v[178:181], v[194:197], v[52:55]
	v_mfma_f32_16x16x32_bf16 v[48:51], v[186:189], v[194:197], v[48:51]
	v_mfma_f32_16x16x32_bf16 v[48:51], v[182:185], v[190:193], v[48:51]
	v_mfma_f32_16x16x32_bf16 v[32:35], v[182:185], v[198:201], v[32:35]
	v_mfma_f32_16x16x32_bf16 v[32:35], v[186:189], v[202:205], v[32:35]
	v_mfma_f32_16x16x32_bf16 v[36:39], v[178:181], v[202:205], v[36:39]
	v_mfma_f32_16x16x32_bf16 v[36:39], v[174:177], v[198:201], v[36:39]
	v_mfma_f32_16x16x32_bf16 v[20:23], v[174:177], v[206:209], v[20:23]
	v_mfma_f32_16x16x32_bf16 v[20:23], v[178:181], v[210:213], v[20:23]
	v_mfma_f32_16x16x32_bf16 v[16:19], v[186:189], v[210:213], v[16:19]
	v_mfma_f32_16x16x32_bf16 v[16:19], v[182:185], v[206:209], v[16:19]
	v_mfma_f32_16x16x32_bf16 v[0:3], v[182:185], v[214:217], v[0:3]
	v_mfma_f32_16x16x32_bf16 v[0:3], v[186:189], v[218:221], v[0:3]
	v_mfma_f32_16x16x32_bf16 v[4:7], v[178:181], v[218:221], v[4:7]
	v_mfma_f32_16x16x32_bf16 v[4:7], v[174:177], v[214:217], v[4:7]
	s_setprio 0
	s_barrier
	s_add_i32 s70, s70, 2
	s_add_u32 s68, s68, 0x100
	s_addc_u32 s69, s69, 0
	s_cmp_gt_u32 s70, 5
	s_mov_b64 s[34:35], s[4:5]
	s_cbranch_scc0 .LBB0_343
	s_and_b64 vcc, exec, s[22:23]
	s_cbranch_vccz .LBB0_346
	s_barrier

; #define PG8_STAGE(bufoff, gbase, voff) do { _Pragma("unroll") for (int _i = 0; _i < 2; ++_i) \
;         __builtin_amdgcn_global_load_lds((const unsigned*)((const char*)(gbase) + (voff)[_i]), (LAS unsigned*)(lds + (bufoff) + ldsw + _i * 8192), 16, 0, 0); } while (0)
; #define PG8_LDA(dst, b, h) do { _Pragma("unroll") for (int m = 0; m < 4; ++m) _Pragma("unroll") for (int k = 0; k < 2; ++k) dst[m][k] = *(const LAS bf16x8*)(lds + PG8_SA(b, h) + aoff + m * 2048 + k * 1024); } while (0)
; #define PG8_LDB(dst, b, h) do { _Pragma("unroll") for (int n = 0; n < 2; ++n) _Pragma("unroll") for (int k = 0; k < 2; ++k) dst[n][k] = *(const LAS bf16x8*)(lds + PG8_SB(b, h) + boff + n * 2048 + k * 1024); } while (0)
; #define PG8_MMA(ai, bj, At, Bt) do { __builtin_amdgcn_s_setprio(1); _Pragma("unroll") for (int m = 0; m < 4; ++m) _Pragma("unroll") for (int n = 0; n < 2; ++n) _Pragma("unroll") for (int k = 0; k < 2; ++k) \
;         acc[ai][bj][m][n] = __builtin_amdgcn_mfma_f32_16x16x32_bf16(Bt[n][k], At[m][k], acc[ai][bj][m][n], 0, 0, 0); __builtin_amdgcn_s_setprio(0); } while (0)
; #define PG8_WAIT_V(n) asm volatile("s_waitcnt vmcnt(" #n ")" ::: "memory")
; #define PG8_WAIT_L(n) asm volatile("s_waitcnt lgkmcnt(" #n ")" ::: "memory")
; #define PG8_BAR __builtin_amdgcn_s_barrier()
; #define PG8_SCHED __builtin_amdgcn_sched_barrier(0)
; DI void gemm_phase(LAS unsigned char* lds, const Gemm g, const StaticOrder& S, const Epi& E) {
;     ...
;         for (int t = 0; t < nt; t += 2) {
;             const bool last = (t == nt - 2);
;             const char* a1 = cA + (size_t)(t + 1) * kstep;
;             const char* a2 = last ? nA : cA + (size_t)(t + 2) * kstep; const char* b2 = last ? nB : cB + (size_t)(t + 2) * kstep;
;             const char* a3 = a2 + kstep; const char* b3 = b2 + kstep;
;             PG8_LDB(B0, 0, 0); PG8_LDB(B1, 0, 1); PG8_SCHED; PG8_LDA(At, 0, 0); PG8_STAGE(PG8_SA(1, 1), a1 + hsA, voffA);
;             PG8_WAIT_V(8); PG8_WAIT_L(0); PG8_BAR; PG8_MMA(0, 0, At, B0); PG8_MMA(0, 1, At, B1); PG8_BAR; PG8_SCHED;
;             PG8_LDA(At, 0, 1); PG8_STAGE(PG8_SB(0, 0), b2, voffB); PG8_STAGE(PG8_SB(0, 1), b2 + hsB, voffB); PG8_STAGE(PG8_SA(0, 0), a2, voffA);
;             PG8_WAIT_V(8); PG8_WAIT_L(0); PG8_BAR; PG8_MMA(1, 0, At, B0); PG8_MMA(1, 1, At, B1); PG8_BAR; PG8_SCHED;
.LBB0_403:
	s_add_u32 s47, s30, s46
	s_addc_u32 s66, s31, 0
	s_add_u32 s54, s47, 0x100
	s_addc_u32 s55, s66, 0
	s_and_b64 s[52:53], s[34:35], exec
	s_cselect_b32 s55, s23, s55
	s_cselect_b32 s54, s22, s54
	s_add_u32 s46, s28, s46
	s_addc_u32 s52, s29, 0
	s_add_u32 s46, s46, 0x100
	s_addc_u32 s52, s52, 0
	s_and_b64 s[34:35], s[34:35], exec
	s_cselect_b32 s57, s21, s52
	s_cselect_b32 s56, s27, s46
	s_add_u32 s68, s47, 0xb0080
	ds_read_b128 v[140:143], v153
	ds_read_b128 v[144:147], v153 offset:1024
	ds_read_b128 v[156:159], v153 offset:2048
	ds_read_b128 v[160:163], v153 offset:3072
	ds_read_b128 v[170:173], v154
	ds_read_b128 v[174:177], v154 offset:1024
	ds_read_b128 v[178:181], v154 offset:2048
	ds_read_b128 v[182:185], v154 offset:3072
	s_addc_u32 s69, s66, 0
	s_add_i32 s79, s70, s33
	s_add_i32 m0, s40, 0xc000
	s_add_i32 s82, s40, 0xe000
	s_add_i32 s76, s79, 0x2000
	s_add_u32 s66, s56, 0x10000
	s_addc_u32 s67, s57, 0
	s_add_i32 s78, s71, s33
	s_add_i32 s77, s78, 0x2000
	s_add_i32 s75, 0, 0x18000
	s_add_i32 s74, 0, 0x1c000
	s_add_u32 s52, s54, 0xb0000
	s_addc_u32 s53, s55, 0
	s_add_i32 s47, s75, s33
	s_add_i32 s46, s47, 0x2000
	s_add_u32 s34, s56, 0x10080
	s_addc_u32 s35, s57, 0
	s_add_i32 s81, s74, s33
	s_add_i32 s80, s81, 0x2000
	v_lshl_add_u64 v[148:149], s[68:69], 0, v[128:129]
	ds_read_b128 v[186:189], v155
	ds_read_b128 v[190:193], v155 offset:1024
	ds_read_b128 v[194:197], v155 offset:2048
	ds_read_b128 v[198:201], v155 offset:3072
	ds_read_b128 v[202:205], v155 offset:4096
	ds_read_b128 v[206:209], v155 offset:5120
	ds_read_b128 v[210:213], v155 offset:6144
	ds_read_b128 v[214:217], v155 offset:7168
	global_load_lds_dwordx4 v[148:149], off
	v_lshl_add_u64 v[148:149], s[68:69], 0, v[132:133]
	s_mov_b32 m0, s82
	s_nop 0
	global_load_lds_dwordx4 v[148:149], off
	s_waitcnt vmcnt(8)
	s_waitcnt lgkmcnt(0)
	s_barrier
	s_setprio 1
	s_waitcnt lgkmcnt(0)
	v_mfma_f32_16x16x32_bf16 v[124:127], v[140:143], v[186:189], v[124:127]
	v_mfma_f32_16x16x32_bf16 v[124:127], v[144:147], v[190:193], v[124:127]
	v_mfma_f32_16x16x32_bf16 v[120:123], v[160:163], v[190:193], v[120:123]
	v_mfma_f32_16x16x32_bf16 v[120:123], v[156:159], v[186:189], v[120:123]
	v_mfma_f32_16x16x32_bf16 v[104:107], v[156:159], v[194:197], v[104:107]
	v_mfma_f32_16x16x32_bf16 v[104:107], v[160:163], v[198:201], v[104:107]
	v_mfma_f32_16x16x32_bf16 v[108:111], v[144:147], v[198:201], v[108:111]
	v_mfma_f32_16x16x32_bf16 v[108:111], v[140:143], v[194:197], v[108:111]
	v_mfma_f32_16x16x32_bf16 v[92:95], v[140:143], v[202:205], v[92:95]
	v_mfma_f32_16x16x32_bf16 v[92:95], v[144:147], v[206:209], v[92:95]
	v_mfma_f32_16x16x32_bf16 v[88:91], v[160:163], v[206:209], v[88:91]
	v_mfma_f32_16x16x32_bf16 v[88:91], v[156:159], v[202:205], v[88:91]
	v_mfma_f32_16x16x32_bf16 v[72:75], v[156:159], v[210:213], v[72:75]
	v_mfma_f32_16x16x32_bf16 v[72:75], v[160:163], v[214:217], v[72:75]
	v_mfma_f32_16x16x32_bf16 v[76:79], v[144:147], v[214:217], v[76:79]
	v_mfma_f32_16x16x32_bf16 v[76:79], v[140:143], v[210:213], v[76:79]
	s_setprio 0
	s_setprio 1
	v_mfma_f32_16x16x32_bf16 v[116:119], v[170:173], v[186:189], v[116:119]
	v_mfma_f32_16x16x32_bf16 v[116:119], v[174:177], v[190:193], v[116:119]
	v_mfma_f32_16x16x32_bf16 v[112:115], v[182:185], v[190:193], v[112:115]
	v_mfma_f32_16x16x32_bf16 v[112:115], v[178:181], v[186:189], v[112:115]
	v_mfma_f32_16x16x32_bf16 v[96:99], v[178:181], v[194:197], v[96:99]
	v_mfma_f32_16x16x32_bf16 v[96:99], v[182:185], v[198:201], v[96:99]
	v_mfma_f32_16x16x32_bf16 v[100:103], v[174:177], v[198:201], v[100:103]
	v_mfma_f32_16x16x32_bf16 v[100:103], v[170:173], v[194:197], v[100:103]
	v_mfma_f32_16x16x32_bf16 v[84:87], v[170:173], v[202:205], v[84:87]
	v_mfma_f32_16x16x32_bf16 v[84:87], v[174:177], v[206:209], v[84:87]
	v_mfma_f32_16x16x32_bf16 v[80:83], v[182:185], v[206:209], v[80:83]
	v_mfma_f32_16x16x32_bf16 v[80:83], v[178:181], v[202:205], v[80:83]
	v_mfma_f32_16x16x32_bf16 v[64:67], v[178:181], v[210:213], v[64:67]
	v_mfma_f32_16x16x32_bf16 v[64:67], v[182:185], v[214:217], v[64:67]
	v_mfma_f32_16x16x32_bf16 v[68:71], v[174:177], v[214:217], v[68:71]
	v_mfma_f32_16x16x32_bf16 v[68:71], v[170:173], v[210:213], v[68:71]
	s_setprio 0
	s_barrier
	s_mov_b32 m0, s79
	v_lshl_add_u64 v[148:149], s[56:57], 0, v[130:131]
	ds_read_b128 v[186:189], v155 offset:16384
	ds_read_b128 v[190:193], v155 offset:17408
	ds_read_b128 v[194:197], v155 offset:18432
	ds_read_b128 v[198:201], v155 offset:19456
	ds_read_b128 v[202:205], v155 offset:20480
	ds_read_b128 v[206:209], v155 offset:21504
	ds_read_b128 v[210:213], v155 offset:22528
	ds_read_b128 v[214:217], v155 offset:23552
	global_load_lds_dwordx4 v[148:149], off
	v_lshl_add_u64 v[164:165], s[56:57], 0, v[134:135]
	s_mov_b32 m0, s76
	v_lshl_add_u64 v[218:219], s[66:67], 0, v[130:131]
	global_load_lds_dwordx4 v[164:165], off
	s_mov_b32 m0, s78
	v_lshl_add_u64 v[220:221], s[54:55], 0, v[132:133]
	global_load_lds_dwordx4 v[218:219], off
	v_lshl_add_u64 v[218:219], s[66:67], 0, v[134:135]
	s_mov_b32 m0, s77
	s_nop 0
	global_load_lds_dwordx4 v[218:219], off
	v_lshl_add_u64 v[218:219], s[54:55], 0, v[128:129]
	s_mov_b32 m0, s40
	s_nop 0
	global_load_lds_dwordx4 v[218:219], off
	s_mov_b32 m0, s41
	s_nop 0
	global_load_lds_dwordx4 v[220:221], off
	s_waitcnt vmcnt(8)
	s_waitcnt lgkmcnt(0)
	s_barrier
; #define PG8_STAGE(bufoff, gbase, voff) do { _Pragma("unroll") for (int _i = 0; _i < 2; ++_i) \
;         __builtin_amdgcn_global_load_lds((const unsigned*)((const char*)(gbase) + (voff)[_i]), (LAS unsigned*)(lds + (bufoff) + ldsw + _i * 8192), 16, 0, 0); } while (0)
; #define PG8_LDA(dst, b, h) do { _Pragma("unroll") for (int m = 0; m < 4; ++m) _Pragma("unroll") for (int k = 0; k < 2; ++k) dst[m][k] = *(const LAS bf16x8*)(lds + PG8_SA(b, h) + aoff + m * 2048 + k * 1024); } while (0)
; #define PG8_LDB(dst, b, h) do { _Pragma("unroll") for (int n = 0; n < 2; ++n) _Pragma("unroll") for (int k = 0; k < 2; ++k) dst[n][k] = *(const LAS bf16x8*)(lds + PG8_SB(b, h) + boff + n * 2048 + k * 1024); } while (0)
; #define PG8_MMA(ai, bj, At, Bt) do { __builtin_amdgcn_s_setprio(1); _Pragma("unroll") for (int m = 0; m < 4; ++m) _Pragma("unroll") for (int n = 0; n < 2; ++n) _Pragma("unroll") for (int k = 0; k < 2; ++k) \
;         acc[ai][bj][m][n] = __builtin_amdgcn_mfma_f32_16x16x32_bf16(Bt[n][k], At[m][k], acc[ai][bj][m][n], 0, 0, 0); __builtin_amdgcn_s_setprio(0); } while (0)
; #define PG8_WAIT_V(n) asm volatile("s_waitcnt vmcnt(" #n ")" ::: "memory")
; #define PG8_WAIT_L(n) asm volatile("s_waitcnt lgkmcnt(" #n ")" ::: "memory")
; DI void gemm_phase(LAS unsigned char* lds, const Gemm g, const StaticOrder& S, const Epi& E) {
;     ...
;             PG8_LDB(B0, 0, 0); PG8_LDB(B1, 0, 1); PG8_SCHED; PG8_LDA(At, 0, 0); PG8_STAGE(PG8_SA(1, 1), a1 + hsA, voffA);
;             PG8_WAIT_V(8); PG8_WAIT_L(0); PG8_BAR; PG8_MMA(0, 0, At, B0); PG8_MMA(0, 1, At, B1); PG8_BAR; PG8_SCHED;
;             PG8_LDA(At, 0, 1); PG8_STAGE(PG8_SB(0, 0), b2, voffB); PG8_STAGE(PG8_SB(0, 1), b2 + hsB, voffB); PG8_STAGE(PG8_SA(0, 0), a2, voffA);
;             PG8_WAIT_V(8); PG8_WAIT_L(0); PG8_BAR; PG8_MMA(1, 0, At, B0); PG8_MMA(1, 1, At, B1); PG8_BAR; PG8_SCHED;
;             PG8_LDB(B0, 1, 0); PG8_LDB(B1, 1, 1); PG8_SCHED; PG8_LDA(At, 1, 0); PG8_STAGE(PG8_SA(0, 1), a2 + hsA, voffA);
;             PG8_WAIT_V(8); PG8_WAIT_L(0); PG8_BAR; PG8_MMA(0, 0, At, B0); PG8_MMA(0, 1, At, B1); PG8_BAR; PG8_SCHED;
;             PG8_LDA(At, 1, 1); PG8_STAGE(PG8_SB(1, 0), b3, voffB); PG8_STAGE(PG8_SB(1, 1), b3 + hsB, voffB); PG8_STAGE(PG8_SA(1, 0), a3, voffA);
;             PG8_WAIT_V(8); PG8_WAIT_L(0); PG8_BAR; PG8_MMA(1, 0, At, B0); PG8_MMA(1, 1, At, B1); PG8_BAR; PG8_SCHED;
	s_setprio 1
	s_waitcnt lgkmcnt(0)
	v_mfma_f32_16x16x32_bf16 v[60:63], v[140:143], v[186:189], v[60:63]
	v_mfma_f32_16x16x32_bf16 v[60:63], v[144:147], v[190:193], v[60:63]
	v_mfma_f32_16x16x32_bf16 v[56:59], v[160:163], v[190:193], v[56:59]
	v_mfma_f32_16x16x32_bf16 v[56:59], v[156:159], v[186:189], v[56:59]
	v_mfma_f32_16x16x32_bf16 v[40:43], v[156:159], v[194:197], v[40:43]
	v_mfma_f32_16x16x32_bf16 v[40:43], v[160:163], v[198:201], v[40:43]
	v_mfma_f32_16x16x32_bf16 v[44:47], v[144:147], v[198:201], v[44:47]
	v_mfma_f32_16x16x32_bf16 v[44:47], v[140:143], v[194:197], v[44:47]
	v_mfma_f32_16x16x32_bf16 v[28:31], v[140:143], v[202:205], v[28:31]
	v_mfma_f32_16x16x32_bf16 v[28:31], v[144:147], v[206:209], v[28:31]
	v_mfma_f32_16x16x32_bf16 v[24:27], v[160:163], v[206:209], v[24:27]
	v_mfma_f32_16x16x32_bf16 v[24:27], v[156:159], v[202:205], v[24:27]
	v_mfma_f32_16x16x32_bf16 v[8:11], v[156:159], v[210:213], v[8:11]
	v_mfma_f32_16x16x32_bf16 v[8:11], v[160:163], v[214:217], v[8:11]
	v_mfma_f32_16x16x32_bf16 v[12:15], v[144:147], v[214:217], v[12:15]
	v_mfma_f32_16x16x32_bf16 v[12:15], v[140:143], v[210:213], v[12:15]
	s_setprio 0
	s_setprio 1
	v_mfma_f32_16x16x32_bf16 v[52:55], v[170:173], v[186:189], v[52:55]
	v_mfma_f32_16x16x32_bf16 v[52:55], v[174:177], v[190:193], v[52:55]
	v_mfma_f32_16x16x32_bf16 v[48:51], v[182:185], v[190:193], v[48:51]
	v_mfma_f32_16x16x32_bf16 v[48:51], v[178:181], v[186:189], v[48:51]
	v_mfma_f32_16x16x32_bf16 v[32:35], v[178:181], v[194:197], v[32:35]
	v_mfma_f32_16x16x32_bf16 v[32:35], v[182:185], v[198:201], v[32:35]
	v_mfma_f32_16x16x32_bf16 v[36:39], v[174:177], v[198:201], v[36:39]
	v_mfma_f32_16x16x32_bf16 v[36:39], v[170:173], v[194:197], v[36:39]
	v_mfma_f32_16x16x32_bf16 v[20:23], v[170:173], v[202:205], v[20:23]
	v_mfma_f32_16x16x32_bf16 v[20:23], v[174:177], v[206:209], v[20:23]
	v_mfma_f32_16x16x32_bf16 v[16:19], v[182:185], v[206:209], v[16:19]
	v_mfma_f32_16x16x32_bf16 v[16:19], v[178:181], v[202:205], v[16:19]
	v_mfma_f32_16x16x32_bf16 v[0:3], v[178:181], v[210:213], v[0:3]
	v_mfma_f32_16x16x32_bf16 v[0:3], v[182:185], v[214:217], v[0:3]
	v_mfma_f32_16x16x32_bf16 v[4:7], v[174:177], v[214:217], v[4:7]
	v_mfma_f32_16x16x32_bf16 v[4:7], v[170:173], v[210:213], v[4:7]
	s_setprio 0
	s_barrier
	v_add_u32_e32 v160, s75, v151
	v_add_u32_e32 v166, s74, v151
	ds_read_b128 v[140:143], v160
	ds_read_b128 v[144:147], v160 offset:1024
	ds_read_b128 v[156:159], v160 offset:2048
	ds_read_b128 v[160:163], v160 offset:3072
	ds_read_b128 v[170:173], v166
	ds_read_b128 v[174:177], v166 offset:1024
	ds_read_b128 v[178:181], v166 offset:2048
	ds_read_b128 v[182:185], v166 offset:3072
	s_mov_b32 m0, s42
	v_lshl_add_u64 v[222:223], s[52:53], 0, v[128:129]
	ds_read_b128 v[186:189], v155 offset:32768
	ds_read_b128 v[190:193], v155 offset:33792
	ds_read_b128 v[194:197], v155 offset:34816
	ds_read_b128 v[198:201], v155 offset:35840
	ds_read_b128 v[202:205], v155 offset:36864
	ds_read_b128 v[206:209], v155 offset:37888
	ds_read_b128 v[210:213], v155 offset:38912
	ds_read_b128 v[214:217], v155 offset:39936
	global_load_lds_dwordx4 v[222:223], off
	v_lshl_add_u64 v[222:223], s[52:53], 0, v[132:133]
	s_mov_b32 m0, s43
	s_nop 0
	global_load_lds_dwordx4 v[222:223], off
	s_waitcnt vmcnt(8)
	s_waitcnt lgkmcnt(0)
	s_barrier
	s_setprio 1
	s_waitcnt lgkmcnt(0)
	v_mfma_f32_16x16x32_bf16 v[124:127], v[140:143], v[186:189], v[124:127]
	v_mfma_f32_16x16x32_bf16 v[124:127], v[144:147], v[190:193], v[124:127]
	v_mfma_f32_16x16x32_bf16 v[120:123], v[160:163], v[190:193], v[120:123]
	v_mfma_f32_16x16x32_bf16 v[120:123], v[156:159], v[186:189], v[120:123]
	v_mfma_f32_16x16x32_bf16 v[104:107], v[156:159], v[194:197], v[104:107]
	v_mfma_f32_16x16x32_bf16 v[104:107], v[160:163], v[198:201], v[104:107]
	v_mfma_f32_16x16x32_bf16 v[108:111], v[144:147], v[198:201], v[108:111]
	v_mfma_f32_16x16x32_bf16 v[108:111], v[140:143], v[194:197], v[108:111]
	v_mfma_f32_16x16x32_bf16 v[92:95], v[140:143], v[202:205], v[92:95]
	v_mfma_f32_16x16x32_bf16 v[92:95], v[144:147], v[206:209], v[92:95]
	v_mfma_f32_16x16x32_bf16 v[88:91], v[160:163], v[206:209], v[88:91]
	v_mfma_f32_16x16x32_bf16 v[88:91], v[156:159], v[202:205], v[88:91]
	v_mfma_f32_16x16x32_bf16 v[72:75], v[156:159], v[210:213], v[72:75]
	v_mfma_f32_16x16x32_bf16 v[72:75], v[160:163], v[214:217], v[72:75]
	v_mfma_f32_16x16x32_bf16 v[76:79], v[144:147], v[214:217], v[76:79]
	v_mfma_f32_16x16x32_bf16 v[76:79], v[140:143], v[210:213], v[76:79]
	s_setprio 0
	s_setprio 1
	v_mfma_f32_16x16x32_bf16 v[116:119], v[170:173], v[186:189], v[116:119]
	v_mfma_f32_16x16x32_bf16 v[116:119], v[174:177], v[190:193], v[116:119]
	v_mfma_f32_16x16x32_bf16 v[112:115], v[182:185], v[190:193], v[112:115]
	v_mfma_f32_16x16x32_bf16 v[112:115], v[178:181], v[186:189], v[112:115]
	v_mfma_f32_16x16x32_bf16 v[96:99], v[178:181], v[194:197], v[96:99]
	v_mfma_f32_16x16x32_bf16 v[96:99], v[182:185], v[198:201], v[96:99]
	v_mfma_f32_16x16x32_bf16 v[100:103], v[174:177], v[198:201], v[100:103]
	v_mfma_f32_16x16x32_bf16 v[100:103], v[170:173], v[194:197], v[100:103]
	v_mfma_f32_16x16x32_bf16 v[84:87], v[170:173], v[202:205], v[84:87]
	v_mfma_f32_16x16x32_bf16 v[84:87], v[174:177], v[206:209], v[84:87]
	v_mfma_f32_16x16x32_bf16 v[80:83], v[182:185], v[206:209], v[80:83]
	v_mfma_f32_16x16x32_bf16 v[80:83], v[178:181], v[202:205], v[80:83]
	v_mfma_f32_16x16x32_bf16 v[64:67], v[178:181], v[210:213], v[64:67]
	v_mfma_f32_16x16x32_bf16 v[64:67], v[182:185], v[214:217], v[64:67]
	v_mfma_f32_16x16x32_bf16 v[68:71], v[174:177], v[214:217], v[68:71]
	v_mfma_f32_16x16x32_bf16 v[68:71], v[170:173], v[210:213], v[68:71]
	s_setprio 0
	s_barrier
; #define PG8_STAGE(bufoff, gbase, voff) do { _Pragma("unroll") for (int _i = 0; _i < 2; ++_i) \
;         __builtin_amdgcn_global_load_lds((const unsigned*)((const char*)(gbase) + (voff)[_i]), (LAS unsigned*)(lds + (bufoff) + ldsw + _i * 8192), 16, 0, 0); } while (0)
; #define PG8_LDA(dst, b, h) do { _Pragma("unroll") for (int m = 0; m < 4; ++m) _Pragma("unroll") for (int k = 0; k < 2; ++k) dst[m][k] = *(const LAS bf16x8*)(lds + PG8_SA(b, h) + aoff + m * 2048 + k * 1024); } while (0)
; #define PG8_LDB(dst, b, h) do { _Pragma("unroll") for (int n = 0; n < 2; ++n) _Pragma("unroll") for (int k = 0; k < 2; ++k) dst[n][k] = *(const LAS bf16x8*)(lds + PG8_SB(b, h) + boff + n * 2048 + k * 1024); } while (0)
; #define PG8_MMA(ai, bj, At, Bt) do { __builtin_amdgcn_s_setprio(1); _Pragma("unroll") for (int m = 0; m < 4; ++m) _Pragma("unroll") for (int n = 0; n < 2; ++n) _Pragma("unroll") for (int k = 0; k < 2; ++k) \
;         acc[ai][bj][m][n] = __builtin_amdgcn_mfma_f32_16x16x32_bf16(Bt[n][k], At[m][k], acc[ai][bj][m][n], 0, 0, 0); __builtin_amdgcn_s_setprio(0); } while (0)
; #define PG8_WAIT_V(n) asm volatile("s_waitcnt vmcnt(" #n ")" ::: "memory")
; #define PG8_WAIT_L(n) asm volatile("s_waitcnt lgkmcnt(" #n ")" ::: "memory")
; #define PG8_BAR __builtin_amdgcn_s_barrier()
; #define PG8_SCHED __builtin_amdgcn_sched_barrier(0)
; DI void gemm_phase(LAS unsigned char* lds, const Gemm g, const StaticOrder& S, const Epi& E) {
;     ...
;             PG8_LDB(B0, 1, 0); PG8_LDB(B1, 1, 1); PG8_SCHED; PG8_LDA(At, 1, 0); PG8_STAGE(PG8_SA(0, 1), a2 + hsA, voffA);
;             PG8_WAIT_V(8); PG8_WAIT_L(0); PG8_BAR; PG8_MMA(0, 0, At, B0); PG8_MMA(0, 1, At, B1); PG8_BAR; PG8_SCHED;
;             PG8_LDA(At, 1, 1); PG8_STAGE(PG8_SB(1, 0), b3, voffB); PG8_STAGE(PG8_SB(1, 1), b3 + hsB, voffB); PG8_STAGE(PG8_SA(1, 0), a3, voffA);
;             PG8_WAIT_V(8); PG8_WAIT_L(0); PG8_BAR; PG8_MMA(1, 0, At, B0); PG8_MMA(1, 1, At, B1); PG8_BAR; PG8_SCHED;
;         }
	s_mov_b32 m0, s47
	v_lshl_add_u64 v[148:149], v[148:149], 0, s[16:17]
	ds_read_b128 v[186:189], v155 offset:49152
	ds_read_b128 v[190:193], v155 offset:50176
	ds_read_b128 v[194:197], v155 offset:51200
	ds_read_b128 v[198:201], v155 offset:52224
	ds_read_b128 v[202:205], v155 offset:53248
	ds_read_b128 v[206:209], v155 offset:54272
	ds_read_b128 v[210:213], v155 offset:55296
	ds_read_b128 v[214:217], v155 offset:56320
	global_load_lds_dwordx4 v[148:149], off
	v_lshl_add_u64 v[148:149], v[164:165], 0, s[16:17]
	s_mov_b32 m0, s46
	s_nop 0
	global_load_lds_dwordx4 v[148:149], off
	v_lshl_add_u64 v[148:149], s[34:35], 0, v[130:131]
	s_mov_b32 m0, s81
	s_nop 0
	global_load_lds_dwordx4 v[148:149], off
	v_lshl_add_u64 v[148:149], s[34:35], 0, v[134:135]
	s_mov_b32 m0, s80
	s_nop 0
	global_load_lds_dwordx4 v[148:149], off
	v_lshl_add_u64 v[148:149], v[218:219], 0, s[16:17]
	s_mov_b32 m0, s58
	s_nop 0
	global_load_lds_dwordx4 v[148:149], off
	v_lshl_add_u64 v[148:149], v[220:221], 0, s[16:17]
	s_mov_b32 m0, s59
	s_nop 0
	global_load_lds_dwordx4 v[148:149], off
	s_waitcnt vmcnt(8)
	s_waitcnt lgkmcnt(0)
	s_barrier
	s_setprio 1
	s_waitcnt lgkmcnt(0)
	v_mfma_f32_16x16x32_bf16 v[60:63], v[140:143], v[186:189], v[60:63]
	v_mfma_f32_16x16x32_bf16 v[60:63], v[144:147], v[190:193], v[60:63]
	v_mfma_f32_16x16x32_bf16 v[56:59], v[160:163], v[190:193], v[56:59]
	v_mfma_f32_16x16x32_bf16 v[56:59], v[156:159], v[186:189], v[56:59]
	v_mfma_f32_16x16x32_bf16 v[40:43], v[156:159], v[194:197], v[40:43]
	v_mfma_f32_16x16x32_bf16 v[40:43], v[160:163], v[198:201], v[40:43]
	v_mfma_f32_16x16x32_bf16 v[44:47], v[144:147], v[198:201], v[44:47]
	v_mfma_f32_16x16x32_bf16 v[44:47], v[140:143], v[194:197], v[44:47]
	v_mfma_f32_16x16x32_bf16 v[28:31], v[140:143], v[202:205], v[28:31]
	v_mfma_f32_16x16x32_bf16 v[28:31], v[144:147], v[206:209], v[28:31]
	v_mfma_f32_16x16x32_bf16 v[24:27], v[160:163], v[206:209], v[24:27]
	v_mfma_f32_16x16x32_bf16 v[24:27], v[156:159], v[202:205], v[24:27]
	v_mfma_f32_16x16x32_bf16 v[8:11], v[156:159], v[210:213], v[8:11]
	v_mfma_f32_16x16x32_bf16 v[8:11], v[160:163], v[214:217], v[8:11]
	v_mfma_f32_16x16x32_bf16 v[12:15], v[144:147], v[214:217], v[12:15]
	v_mfma_f32_16x16x32_bf16 v[12:15], v[140:143], v[210:213], v[12:15]
	s_setprio 0
	s_setprio 1
	v_mfma_f32_16x16x32_bf16 v[52:55], v[170:173], v[186:189], v[52:55]
	v_mfma_f32_16x16x32_bf16 v[52:55], v[174:177], v[190:193], v[52:55]
	v_mfma_f32_16x16x32_bf16 v[48:51], v[182:185], v[190:193], v[48:51]
	v_mfma_f32_16x16x32_bf16 v[48:51], v[178:181], v[186:189], v[48:51]
	v_mfma_f32_16x16x32_bf16 v[32:35], v[178:181], v[194:197], v[32:35]
	v_mfma_f32_16x16x32_bf16 v[32:35], v[182:185], v[198:201], v[32:35]
	v_mfma_f32_16x16x32_bf16 v[36:39], v[174:177], v[198:201], v[36:39]
	v_mfma_f32_16x16x32_bf16 v[36:39], v[170:173], v[194:197], v[36:39]
	v_mfma_f32_16x16x32_bf16 v[20:23], v[170:173], v[202:205], v[20:23]
	v_mfma_f32_16x16x32_bf16 v[20:23], v[174:177], v[206:209], v[20:23]
	v_mfma_f32_16x16x32_bf16 v[16:19], v[182:185], v[206:209], v[16:19]
	v_mfma_f32_16x16x32_bf16 v[16:19], v[178:181], v[202:205], v[16:19]
	v_mfma_f32_16x16x32_bf16 v[0:3], v[178:181], v[210:213], v[0:3]
	v_mfma_f32_16x16x32_bf16 v[0:3], v[182:185], v[214:217], v[0:3]
	v_mfma_f32_16x16x32_bf16 v[4:7], v[174:177], v[214:217], v[4:7]
	v_mfma_f32_16x16x32_bf16 v[4:7], v[170:173], v[210:213], v[4:7]
	s_setprio 0
	s_barrier
	s_movk_i32 s46, 0x100
	s_andn2_b64 vcc, exec, s[6:7]
	s_mov_b64 s[34:35], -1
	s_mov_b64 s[6:7], 0
	s_cbranch_vccz .LBB0_403
	s_and_b64 vcc, exec, s[18:19]
	s_cbranch_vccz .LBB0_406
	s_barrier

; #define PG8_STAGE(bufoff, gbase, voff) do { _Pragma("unroll") for (int _i = 0; _i < 2; ++_i) \
;         __builtin_amdgcn_global_load_lds((const unsigned*)((const char*)(gbase) + (voff)[_i]), (LAS unsigned*)(lds + (bufoff) + ldsw + _i * 8192), 16, 0, 0); } while (0)
; #define PG8_LDA(dst, b, h) do { _Pragma("unroll") for (int m = 0; m < 4; ++m) _Pragma("unroll") for (int k = 0; k < 2; ++k) dst[m][k] = *(const LAS bf16x8*)(lds + PG8_SA(b, h) + aoff + m * 2048 + k * 1024); } while (0)
; #define PG8_LDB(dst, b, h) do { _Pragma("unroll") for (int n = 0; n < 2; ++n) _Pragma("unroll") for (int k = 0; k < 2; ++k) dst[n][k] = *(const LAS bf16x8*)(lds + PG8_SB(b, h) + boff + n * 2048 + k * 1024); } while (0)
; #define PG8_MMA(ai, bj, At, Bt) do { __builtin_amdgcn_s_setprio(1); _Pragma("unroll") for (int m = 0; m < 4; ++m) _Pragma("unroll") for (int n = 0; n < 2; ++n) _Pragma("unroll") for (int k = 0; k < 2; ++k) \
;         acc[ai][bj][m][n] = __builtin_amdgcn_mfma_f32_16x16x32_bf16(Bt[n][k], At[m][k], acc[ai][bj][m][n], 0, 0, 0); __builtin_amdgcn_s_setprio(0); } while (0)
; #define PG8_WAIT_V(n) asm volatile("s_waitcnt vmcnt(" #n ")" ::: "memory")
; #define PG8_WAIT_L(n) asm volatile("s_waitcnt lgkmcnt(" #n ")" ::: "memory")
; #define PG8_BAR __builtin_amdgcn_s_barrier()
; #define PG8_SCHED __builtin_amdgcn_sched_barrier(0)
; DI void gemm_phase(LAS unsigned char* lds, const Gemm g, const StaticOrder& S, const Epi& E) {
;     ...
;         for (int t = 0; t < nt; t += 2) {
;             const bool last = (t == nt - 2);
;             const char* a1 = cA + (size_t)(t + 1) * kstep;
;             const char* a2 = last ? nA : cA + (size_t)(t + 2) * kstep; const char* b2 = last ? nB : cB + (size_t)(t + 2) * kstep;
;             const char* a3 = a2 + kstep; const char* b3 = b2 + kstep;
;             PG8_LDB(B0, 0, 0); PG8_LDB(B1, 0, 1); PG8_SCHED; PG8_LDA(At, 0, 0); PG8_STAGE(PG8_SA(1, 1), a1 + hsA, voffA);
;             PG8_WAIT_V(8); PG8_WAIT_L(0); PG8_BAR; PG8_MMA(0, 0, At, B0); PG8_MMA(0, 1, At, B1); PG8_BAR; PG8_SCHED;
;             PG8_LDA(At, 0, 1); PG8_STAGE(PG8_SB(0, 0), b2, voffB); PG8_STAGE(PG8_SB(0, 1), b2 + hsB, voffB); PG8_STAGE(PG8_SA(0, 0), a2, voffA);
;             PG8_WAIT_V(8); PG8_WAIT_L(0); PG8_BAR; PG8_MMA(1, 0, At, B0); PG8_MMA(1, 1, At, B1); PG8_BAR; PG8_SCHED;
.LBB0_461:
	s_add_u32 s47, s30, s46
	s_addc_u32 s68, s31, 0
	s_add_u32 s56, s47, 0x100
	s_addc_u32 s57, s68, 0
	s_and_b64 s[54:55], s[34:35], exec
	s_cselect_b32 s57, s21, s57
	s_cselect_b32 s56, s76, s56
	s_add_u32 s46, s28, s46
	s_addc_u32 s54, s29, 0
	s_add_u32 s46, s46, 0x100
	s_addc_u32 s54, s54, 0
	s_and_b64 s[34:35], s[34:35], exec
	s_cselect_b32 s67, s23, s54
	s_cselect_b32 s66, s22, s46
	s_add_u32 s70, s47, 0x10080
	s_addc_u32 s71, s68, 0
	s_add_i32 s84, s58, s33
	ds_read_b128 v[140:143], v149
	ds_read_b128 v[152:155], v149 offset:1024
	ds_read_b128 v[156:159], v149 offset:2048
	ds_read_b128 v[160:163], v149 offset:3072
	ds_read_b128 v[170:173], v150
	ds_read_b128 v[174:177], v150 offset:1024
	ds_read_b128 v[178:181], v150 offset:2048
	ds_read_b128 v[182:185], v150 offset:3072
	s_add_i32 m0, s27, 0xc000
	s_add_i32 s85, s27, 0xe000
	s_add_i32 s81, s84, 0x2000
	s_add_u32 s68, s66, 0xb0000
	s_addc_u32 s69, s67, 0
	s_add_i32 s83, s59, s33
	s_add_i32 s82, s83, 0x2000
	s_add_i32 s80, 0, 0x18000
	s_add_i32 s79, 0, 0x1c000
	s_add_u32 s54, s56, 0x10000
	s_addc_u32 s55, s57, 0
	s_add_i32 s78, s80, s33
	s_add_i32 s47, s78, 0x2000
	s_add_u32 s34, s66, 0xb0080
	s_addc_u32 s35, s67, 0
	s_add_i32 s77, s79, s33
	s_add_i32 s46, s77, 0x2000
	v_lshl_add_u64 v[144:145], s[70:71], 0, v[128:129]
	ds_read_b128 v[186:189], v151
	ds_read_b128 v[190:193], v151 offset:1024
	ds_read_b128 v[194:197], v151 offset:2048
	ds_read_b128 v[198:201], v151 offset:3072
	ds_read_b128 v[202:205], v151 offset:4096
	ds_read_b128 v[206:209], v151 offset:5120
	ds_read_b128 v[210:213], v151 offset:6144
	ds_read_b128 v[214:217], v151 offset:7168
	global_load_lds_dwordx4 v[144:145], off
	v_lshl_add_u64 v[144:145], s[70:71], 0, v[132:133]
	s_mov_b32 m0, s85
	s_nop 0
	global_load_lds_dwordx4 v[144:145], off
	s_waitcnt vmcnt(8)
	s_waitcnt lgkmcnt(0)
	s_barrier
	s_setprio 1
	s_waitcnt lgkmcnt(0)
	v_mfma_f32_16x16x32_bf16 v[124:127], v[140:143], v[186:189], v[124:127]
	v_mfma_f32_16x16x32_bf16 v[124:127], v[152:155], v[190:193], v[124:127]
	v_mfma_f32_16x16x32_bf16 v[120:123], v[160:163], v[190:193], v[120:123]
	v_mfma_f32_16x16x32_bf16 v[120:123], v[156:159], v[186:189], v[120:123]
	v_mfma_f32_16x16x32_bf16 v[104:107], v[156:159], v[194:197], v[104:107]
	v_mfma_f32_16x16x32_bf16 v[104:107], v[160:163], v[198:201], v[104:107]
	v_mfma_f32_16x16x32_bf16 v[108:111], v[152:155], v[198:201], v[108:111]
	v_mfma_f32_16x16x32_bf16 v[108:111], v[140:143], v[194:197], v[108:111]
	v_mfma_f32_16x16x32_bf16 v[92:95], v[140:143], v[202:205], v[92:95]
	v_mfma_f32_16x16x32_bf16 v[92:95], v[152:155], v[206:209], v[92:95]
	v_mfma_f32_16x16x32_bf16 v[88:91], v[160:163], v[206:209], v[88:91]
	v_mfma_f32_16x16x32_bf16 v[88:91], v[156:159], v[202:205], v[88:91]
	v_mfma_f32_16x16x32_bf16 v[72:75], v[156:159], v[210:213], v[72:75]
	v_mfma_f32_16x16x32_bf16 v[72:75], v[160:163], v[214:217], v[72:75]
	v_mfma_f32_16x16x32_bf16 v[76:79], v[152:155], v[214:217], v[76:79]
	v_mfma_f32_16x16x32_bf16 v[76:79], v[140:143], v[210:213], v[76:79]
	s_setprio 0
	s_setprio 1
	v_mfma_f32_16x16x32_bf16 v[116:119], v[170:173], v[186:189], v[116:119]
	v_mfma_f32_16x16x32_bf16 v[116:119], v[174:177], v[190:193], v[116:119]
	v_mfma_f32_16x16x32_bf16 v[112:115], v[182:185], v[190:193], v[112:115]
	v_mfma_f32_16x16x32_bf16 v[112:115], v[178:181], v[186:189], v[112:115]
	v_mfma_f32_16x16x32_bf16 v[96:99], v[178:181], v[194:197], v[96:99]
	v_mfma_f32_16x16x32_bf16 v[96:99], v[182:185], v[198:201], v[96:99]
	v_mfma_f32_16x16x32_bf16 v[100:103], v[174:177], v[198:201], v[100:103]
	v_mfma_f32_16x16x32_bf16 v[100:103], v[170:173], v[194:197], v[100:103]
	v_mfma_f32_16x16x32_bf16 v[84:87], v[170:173], v[202:205], v[84:87]
	v_mfma_f32_16x16x32_bf16 v[84:87], v[174:177], v[206:209], v[84:87]
	v_mfma_f32_16x16x32_bf16 v[80:83], v[182:185], v[206:209], v[80:83]
	v_mfma_f32_16x16x32_bf16 v[80:83], v[178:181], v[202:205], v[80:83]
	v_mfma_f32_16x16x32_bf16 v[64:67], v[178:181], v[210:213], v[64:67]
	v_mfma_f32_16x16x32_bf16 v[64:67], v[182:185], v[214:217], v[64:67]
	v_mfma_f32_16x16x32_bf16 v[68:71], v[174:177], v[214:217], v[68:71]
	v_mfma_f32_16x16x32_bf16 v[68:71], v[170:173], v[210:213], v[68:71]
	s_setprio 0
	s_barrier
	s_mov_b32 m0, s84
	v_lshl_add_u64 v[144:145], s[66:67], 0, v[130:131]
	ds_read_b128 v[186:189], v151 offset:16384
	ds_read_b128 v[190:193], v151 offset:17408
	ds_read_b128 v[194:197], v151 offset:18432
	ds_read_b128 v[198:201], v151 offset:19456
	ds_read_b128 v[202:205], v151 offset:20480
	ds_read_b128 v[206:209], v151 offset:21504
	ds_read_b128 v[210:213], v151 offset:22528
	ds_read_b128 v[214:217], v151 offset:23552
	global_load_lds_dwordx4 v[144:145], off
	v_lshl_add_u64 v[164:165], s[66:67], 0, v[134:135]
	s_mov_b32 m0, s81
	v_lshl_add_u64 v[218:219], s[68:69], 0, v[130:131]
	global_load_lds_dwordx4 v[164:165], off
	s_mov_b32 m0, s83
	v_lshl_add_u64 v[220:221], s[56:57], 0, v[132:133]
	global_load_lds_dwordx4 v[218:219], off
	v_lshl_add_u64 v[218:219], s[68:69], 0, v[134:135]
	s_mov_b32 m0, s82
	s_nop 0
	global_load_lds_dwordx4 v[218:219], off
	v_lshl_add_u64 v[218:219], s[56:57], 0, v[128:129]
	s_mov_b32 m0, s27
	s_nop 0
	global_load_lds_dwordx4 v[218:219], off
	s_mov_b32 m0, s40
	s_nop 0
	global_load_lds_dwordx4 v[220:221], off
	s_waitcnt vmcnt(8)
	s_waitcnt lgkmcnt(0)
	s_barrier
; #define PG8_STAGE(bufoff, gbase, voff) do { _Pragma("unroll") for (int _i = 0; _i < 2; ++_i) \
;         __builtin_amdgcn_global_load_lds((const unsigned*)((const char*)(gbase) + (voff)[_i]), (LAS unsigned*)(lds + (bufoff) + ldsw + _i * 8192), 16, 0, 0); } while (0)
; #define PG8_LDA(dst, b, h) do { _Pragma("unroll") for (int m = 0; m < 4; ++m) _Pragma("unroll") for (int k = 0; k < 2; ++k) dst[m][k] = *(const LAS bf16x8*)(lds + PG8_SA(b, h) + aoff + m * 2048 + k * 1024); } while (0)
; #define PG8_LDB(dst, b, h) do { _Pragma("unroll") for (int n = 0; n < 2; ++n) _Pragma("unroll") for (int k = 0; k < 2; ++k) dst[n][k] = *(const LAS bf16x8*)(lds + PG8_SB(b, h) + boff + n * 2048 + k * 1024); } while (0)
; #define PG8_MMA(ai, bj, At, Bt) do { __builtin_amdgcn_s_setprio(1); _Pragma("unroll") for (int m = 0; m < 4; ++m) _Pragma("unroll") for (int n = 0; n < 2; ++n) _Pragma("unroll") for (int k = 0; k < 2; ++k) \
;         acc[ai][bj][m][n] = __builtin_amdgcn_mfma_f32_16x16x32_bf16(Bt[n][k], At[m][k], acc[ai][bj][m][n], 0, 0, 0); __builtin_amdgcn_s_setprio(0); } while (0)
; #define PG8_WAIT_V(n) asm volatile("s_waitcnt vmcnt(" #n ")" ::: "memory")
; #define PG8_WAIT_L(n) asm volatile("s_waitcnt lgkmcnt(" #n ")" ::: "memory")
; DI void gemm_phase(LAS unsigned char* lds, const Gemm g, const StaticOrder& S, const Epi& E) {
;     ...
;             PG8_LDB(B0, 0, 0); PG8_LDB(B1, 0, 1); PG8_SCHED; PG8_LDA(At, 0, 0); PG8_STAGE(PG8_SA(1, 1), a1 + hsA, voffA);
;             PG8_WAIT_V(8); PG8_WAIT_L(0); PG8_BAR; PG8_MMA(0, 0, At, B0); PG8_MMA(0, 1, At, B1); PG8_BAR; PG8_SCHED;
;             PG8_LDA(At, 0, 1); PG8_STAGE(PG8_SB(0, 0), b2, voffB); PG8_STAGE(PG8_SB(0, 1), b2 + hsB, voffB); PG8_STAGE(PG8_SA(0, 0), a2, voffA);
;             PG8_WAIT_V(8); PG8_WAIT_L(0); PG8_BAR; PG8_MMA(1, 0, At, B0); PG8_MMA(1, 1, At, B1); PG8_BAR; PG8_SCHED;
;             PG8_LDB(B0, 1, 0); PG8_LDB(B1, 1, 1); PG8_SCHED; PG8_LDA(At, 1, 0); PG8_STAGE(PG8_SA(0, 1), a2 + hsA, voffA);
;             PG8_WAIT_V(8); PG8_WAIT_L(0); PG8_BAR; PG8_MMA(0, 0, At, B0); PG8_MMA(0, 1, At, B1); PG8_BAR; PG8_SCHED;
;             PG8_LDA(At, 1, 1); PG8_STAGE(PG8_SB(1, 0), b3, voffB); PG8_STAGE(PG8_SB(1, 1), b3 + hsB, voffB); PG8_STAGE(PG8_SA(1, 0), a3, voffA);
;             PG8_WAIT_V(8); PG8_WAIT_L(0); PG8_BAR; PG8_MMA(1, 0, At, B0); PG8_MMA(1, 1, At, B1); PG8_BAR; PG8_SCHED;
	s_setprio 1
	s_waitcnt lgkmcnt(0)
	v_mfma_f32_16x16x32_bf16 v[60:63], v[140:143], v[186:189], v[60:63]
	v_mfma_f32_16x16x32_bf16 v[60:63], v[152:155], v[190:193], v[60:63]
	v_mfma_f32_16x16x32_bf16 v[56:59], v[160:163], v[190:193], v[56:59]
	v_mfma_f32_16x16x32_bf16 v[56:59], v[156:159], v[186:189], v[56:59]
	v_mfma_f32_16x16x32_bf16 v[40:43], v[156:159], v[194:197], v[40:43]
	v_mfma_f32_16x16x32_bf16 v[40:43], v[160:163], v[198:201], v[40:43]
	v_mfma_f32_16x16x32_bf16 v[44:47], v[152:155], v[198:201], v[44:47]
	v_mfma_f32_16x16x32_bf16 v[44:47], v[140:143], v[194:197], v[44:47]
	v_mfma_f32_16x16x32_bf16 v[28:31], v[140:143], v[202:205], v[28:31]
	v_mfma_f32_16x16x32_bf16 v[28:31], v[152:155], v[206:209], v[28:31]
	v_mfma_f32_16x16x32_bf16 v[24:27], v[160:163], v[206:209], v[24:27]
	v_mfma_f32_16x16x32_bf16 v[24:27], v[156:159], v[202:205], v[24:27]
	v_mfma_f32_16x16x32_bf16 v[8:11], v[156:159], v[210:213], v[8:11]
	v_mfma_f32_16x16x32_bf16 v[8:11], v[160:163], v[214:217], v[8:11]
	v_mfma_f32_16x16x32_bf16 v[12:15], v[152:155], v[214:217], v[12:15]
	v_mfma_f32_16x16x32_bf16 v[12:15], v[140:143], v[210:213], v[12:15]
	s_setprio 0
	s_setprio 1
	v_mfma_f32_16x16x32_bf16 v[52:55], v[170:173], v[186:189], v[52:55]
	v_mfma_f32_16x16x32_bf16 v[52:55], v[174:177], v[190:193], v[52:55]
	v_mfma_f32_16x16x32_bf16 v[48:51], v[182:185], v[190:193], v[48:51]
	v_mfma_f32_16x16x32_bf16 v[48:51], v[178:181], v[186:189], v[48:51]
	v_mfma_f32_16x16x32_bf16 v[32:35], v[178:181], v[194:197], v[32:35]
	v_mfma_f32_16x16x32_bf16 v[32:35], v[182:185], v[198:201], v[32:35]
	v_mfma_f32_16x16x32_bf16 v[36:39], v[174:177], v[198:201], v[36:39]
	v_mfma_f32_16x16x32_bf16 v[36:39], v[170:173], v[194:197], v[36:39]
	v_mfma_f32_16x16x32_bf16 v[20:23], v[170:173], v[202:205], v[20:23]
	v_mfma_f32_16x16x32_bf16 v[20:23], v[174:177], v[206:209], v[20:23]
	v_mfma_f32_16x16x32_bf16 v[16:19], v[182:185], v[206:209], v[16:19]
	v_mfma_f32_16x16x32_bf16 v[16:19], v[178:181], v[202:205], v[16:19]
	v_mfma_f32_16x16x32_bf16 v[0:3], v[178:181], v[210:213], v[0:3]
	v_mfma_f32_16x16x32_bf16 v[0:3], v[182:185], v[214:217], v[0:3]
	v_mfma_f32_16x16x32_bf16 v[4:7], v[174:177], v[214:217], v[4:7]
	v_mfma_f32_16x16x32_bf16 v[4:7], v[170:173], v[210:213], v[4:7]
	s_setprio 0
	s_barrier
	v_add_u32_e32 v160, s80, v147
	v_add_u32_e32 v166, s79, v147
	ds_read_b128 v[140:143], v160
	ds_read_b128 v[152:155], v160 offset:1024
	ds_read_b128 v[156:159], v160 offset:2048
	ds_read_b128 v[160:163], v160 offset:3072
	ds_read_b128 v[170:173], v166
	ds_read_b128 v[174:177], v166 offset:1024
	ds_read_b128 v[178:181], v166 offset:2048
	ds_read_b128 v[182:185], v166 offset:3072
	s_mov_b32 m0, s41
	v_lshl_add_u64 v[222:223], s[54:55], 0, v[128:129]
	ds_read_b128 v[186:189], v151 offset:32768
	ds_read_b128 v[190:193], v151 offset:33792
	ds_read_b128 v[194:197], v151 offset:34816
	ds_read_b128 v[198:201], v151 offset:35840
	ds_read_b128 v[202:205], v151 offset:36864
	ds_read_b128 v[206:209], v151 offset:37888
	ds_read_b128 v[210:213], v151 offset:38912
	ds_read_b128 v[214:217], v151 offset:39936
	global_load_lds_dwordx4 v[222:223], off
	v_lshl_add_u64 v[222:223], s[54:55], 0, v[132:133]
	s_mov_b32 m0, s42
	s_nop 0
	global_load_lds_dwordx4 v[222:223], off
	s_waitcnt vmcnt(8)
	s_waitcnt lgkmcnt(0)
	s_barrier
	s_setprio 1
	s_waitcnt lgkmcnt(0)
	v_mfma_f32_16x16x32_bf16 v[124:127], v[140:143], v[186:189], v[124:127]
	v_mfma_f32_16x16x32_bf16 v[124:127], v[152:155], v[190:193], v[124:127]
	v_mfma_f32_16x16x32_bf16 v[120:123], v[160:163], v[190:193], v[120:123]
	v_mfma_f32_16x16x32_bf16 v[120:123], v[156:159], v[186:189], v[120:123]
	v_mfma_f32_16x16x32_bf16 v[104:107], v[156:159], v[194:197], v[104:107]
	v_mfma_f32_16x16x32_bf16 v[104:107], v[160:163], v[198:201], v[104:107]
	v_mfma_f32_16x16x32_bf16 v[108:111], v[152:155], v[198:201], v[108:111]
	v_mfma_f32_16x16x32_bf16 v[108:111], v[140:143], v[194:197], v[108:111]
	v_mfma_f32_16x16x32_bf16 v[92:95], v[140:143], v[202:205], v[92:95]
	v_mfma_f32_16x16x32_bf16 v[92:95], v[152:155], v[206:209], v[92:95]
	v_mfma_f32_16x16x32_bf16 v[88:91], v[160:163], v[206:209], v[88:91]
	v_mfma_f32_16x16x32_bf16 v[88:91], v[156:159], v[202:205], v[88:91]
	v_mfma_f32_16x16x32_bf16 v[72:75], v[156:159], v[210:213], v[72:75]
	v_mfma_f32_16x16x32_bf16 v[72:75], v[160:163], v[214:217], v[72:75]
	v_mfma_f32_16x16x32_bf16 v[76:79], v[152:155], v[214:217], v[76:79]
	v_mfma_f32_16x16x32_bf16 v[76:79], v[140:143], v[210:213], v[76:79]
	s_setprio 0
	s_setprio 1
	v_mfma_f32_16x16x32_bf16 v[116:119], v[170:173], v[186:189], v[116:119]
	v_mfma_f32_16x16x32_bf16 v[116:119], v[174:177], v[190:193], v[116:119]
	v_mfma_f32_16x16x32_bf16 v[112:115], v[182:185], v[190:193], v[112:115]
	v_mfma_f32_16x16x32_bf16 v[112:115], v[178:181], v[186:189], v[112:115]
	v_mfma_f32_16x16x32_bf16 v[96:99], v[178:181], v[194:197], v[96:99]
	v_mfma_f32_16x16x32_bf16 v[96:99], v[182:185], v[198:201], v[96:99]
	v_mfma_f32_16x16x32_bf16 v[100:103], v[174:177], v[198:201], v[100:103]
	v_mfma_f32_16x16x32_bf16 v[100:103], v[170:173], v[194:197], v[100:103]
	v_mfma_f32_16x16x32_bf16 v[84:87], v[170:173], v[202:205], v[84:87]
	v_mfma_f32_16x16x32_bf16 v[84:87], v[174:177], v[206:209], v[84:87]
	v_mfma_f32_16x16x32_bf16 v[80:83], v[182:185], v[206:209], v[80:83]
	v_mfma_f32_16x16x32_bf16 v[80:83], v[178:181], v[202:205], v[80:83]
	v_mfma_f32_16x16x32_bf16 v[64:67], v[178:181], v[210:213], v[64:67]
	v_mfma_f32_16x16x32_bf16 v[64:67], v[182:185], v[214:217], v[64:67]
	v_mfma_f32_16x16x32_bf16 v[68:71], v[174:177], v[214:217], v[68:71]
	v_mfma_f32_16x16x32_bf16 v[68:71], v[170:173], v[210:213], v[68:71]
	s_setprio 0
	s_barrier
; #define PG8_STAGE(bufoff, gbase, voff) do { _Pragma("unroll") for (int _i = 0; _i < 2; ++_i) \
;         __builtin_amdgcn_global_load_lds((const unsigned*)((const char*)(gbase) + (voff)[_i]), (LAS unsigned*)(lds + (bufoff) + ldsw + _i * 8192), 16, 0, 0); } while (0)
; #define PG8_LDA(dst, b, h) do { _Pragma("unroll") for (int m = 0; m < 4; ++m) _Pragma("unroll") for (int k = 0; k < 2; ++k) dst[m][k] = *(const LAS bf16x8*)(lds + PG8_SA(b, h) + aoff + m * 2048 + k * 1024); } while (0)
; #define PG8_MMA(ai, bj, At, Bt) do { __builtin_amdgcn_s_setprio(1); _Pragma("unroll") for (int m = 0; m < 4; ++m) _Pragma("unroll") for (int n = 0; n < 2; ++n) _Pragma("unroll") for (int k = 0; k < 2; ++k) \
;         acc[ai][bj][m][n] = __builtin_amdgcn_mfma_f32_16x16x32_bf16(Bt[n][k], At[m][k], acc[ai][bj][m][n], 0, 0, 0); __builtin_amdgcn_s_setprio(0); } while (0)
; #define PG8_WAIT_V(n) asm volatile("s_waitcnt vmcnt(" #n ")" ::: "memory")
; #define PG8_WAIT_L(n) asm volatile("s_waitcnt lgkmcnt(" #n ")" ::: "memory")
; #define PG8_BAR __builtin_amdgcn_s_barrier()
; #define PG8_SCHED __builtin_amdgcn_sched_barrier(0)
; DI void gemm_phase(LAS unsigned char* lds, const Gemm g, const StaticOrder& S, const Epi& E) {
;     ...
;             PG8_LDA(At, 1, 1); PG8_STAGE(PG8_SB(1, 0), b3, voffB); PG8_STAGE(PG8_SB(1, 1), b3 + hsB, voffB); PG8_STAGE(PG8_SA(1, 0), a3, voffA);
;             PG8_WAIT_V(8); PG8_WAIT_L(0); PG8_BAR; PG8_MMA(1, 0, At, B0); PG8_MMA(1, 1, At, B1); PG8_BAR; PG8_SCHED;
	s_mov_b32 m0, s78
	v_lshl_add_u64 v[144:145], v[144:145], 0, s[14:15]
	ds_read_b128 v[186:189], v151 offset:49152
	ds_read_b128 v[190:193], v151 offset:50176
	ds_read_b128 v[194:197], v151 offset:51200
	ds_read_b128 v[198:201], v151 offset:52224
	ds_read_b128 v[202:205], v151 offset:53248
	ds_read_b128 v[206:209], v151 offset:54272
	ds_read_b128 v[210:213], v151 offset:55296
	ds_read_b128 v[214:217], v151 offset:56320
	global_load_lds_dwordx4 v[144:145], off
	v_lshl_add_u64 v[144:145], v[164:165], 0, s[14:15]
	s_mov_b32 m0, s47
	s_nop 0
	global_load_lds_dwordx4 v[144:145], off
	v_lshl_add_u64 v[144:145], s[34:35], 0, v[130:131]
	s_mov_b32 m0, s77
	s_nop 0
	global_load_lds_dwordx4 v[144:145], off
	v_lshl_add_u64 v[144:145], s[34:35], 0, v[134:135]
	s_mov_b32 m0, s46
	s_nop 0
	global_load_lds_dwordx4 v[144:145], off
	v_lshl_add_u64 v[144:145], v[218:219], 0, s[14:15]
	s_mov_b32 m0, s48
	s_nop 0
	global_load_lds_dwordx4 v[144:145], off
	v_lshl_add_u64 v[144:145], v[220:221], 0, s[14:15]
	s_mov_b32 m0, s49
	s_nop 0
	global_load_lds_dwordx4 v[144:145], off
	s_waitcnt vmcnt(8)
	s_waitcnt lgkmcnt(0)
	s_barrier
	s_setprio 1
	s_waitcnt lgkmcnt(0)
	v_mfma_f32_16x16x32_bf16 v[60:63], v[140:143], v[186:189], v[60:63]
	v_mfma_f32_16x16x32_bf16 v[60:63], v[152:155], v[190:193], v[60:63]
	v_mfma_f32_16x16x32_bf16 v[56:59], v[160:163], v[190:193], v[56:59]
	v_mfma_f32_16x16x32_bf16 v[56:59], v[156:159], v[186:189], v[56:59]
	v_mfma_f32_16x16x32_bf16 v[40:43], v[156:159], v[194:197], v[40:43]
	v_mfma_f32_16x16x32_bf16 v[40:43], v[160:163], v[198:201], v[40:43]
	v_mfma_f32_16x16x32_bf16 v[44:47], v[152:155], v[198:201], v[44:47]
	v_mfma_f32_16x16x32_bf16 v[44:47], v[140:143], v[194:197], v[44:47]
	v_mfma_f32_16x16x32_bf16 v[28:31], v[140:143], v[202:205], v[28:31]
	v_mfma_f32_16x16x32_bf16 v[28:31], v[152:155], v[206:209], v[28:31]
	v_mfma_f32_16x16x32_bf16 v[24:27], v[160:163], v[206:209], v[24:27]
	v_mfma_f32_16x16x32_bf16 v[24:27], v[156:159], v[202:205], v[24:27]
	v_mfma_f32_16x16x32_bf16 v[8:11], v[156:159], v[210:213], v[8:11]
	v_mfma_f32_16x16x32_bf16 v[8:11], v[160:163], v[214:217], v[8:11]
	v_mfma_f32_16x16x32_bf16 v[12:15], v[152:155], v[214:217], v[12:15]
	v_mfma_f32_16x16x32_bf16 v[12:15], v[140:143], v[210:213], v[12:15]
	s_setprio 0
	s_setprio 1
	v_mfma_f32_16x16x32_bf16 v[52:55], v[170:173], v[186:189], v[52:55]
	v_mfma_f32_16x16x32_bf16 v[52:55], v[174:177], v[190:193], v[52:55]
	v_mfma_f32_16x16x32_bf16 v[48:51], v[182:185], v[190:193], v[48:51]
	v_mfma_f32_16x16x32_bf16 v[48:51], v[178:181], v[186:189], v[48:51]
	v_mfma_f32_16x16x32_bf16 v[32:35], v[178:181], v[194:197], v[32:35]
	v_mfma_f32_16x16x32_bf16 v[32:35], v[182:185], v[198:201], v[32:35]
	v_mfma_f32_16x16x32_bf16 v[36:39], v[174:177], v[198:201], v[36:39]
	v_mfma_f32_16x16x32_bf16 v[36:39], v[170:173], v[194:197], v[36:39]
	v_mfma_f32_16x16x32_bf16 v[20:23], v[170:173], v[202:205], v[20:23]
	v_mfma_f32_16x16x32_bf16 v[20:23], v[174:177], v[206:209], v[20:23]
	v_mfma_f32_16x16x32_bf16 v[16:19], v[182:185], v[206:209], v[16:19]
	v_mfma_f32_16x16x32_bf16 v[16:19], v[178:181], v[202:205], v[16:19]
	v_mfma_f32_16x16x32_bf16 v[0:3], v[178:181], v[210:213], v[0:3]
	v_mfma_f32_16x16x32_bf16 v[0:3], v[182:185], v[214:217], v[0:3]
	v_mfma_f32_16x16x32_bf16 v[4:7], v[174:177], v[214:217], v[4:7]
	v_mfma_f32_16x16x32_bf16 v[4:7], v[170:173], v[210:213], v[4:7]
	s_setprio 0
	s_barrier
	s_movk_i32 s46, 0x100
	s_andn2_b64 vcc, exec, s[4:5]
	s_mov_b64 s[34:35], -1
	s_mov_b64 s[4:5], 0
	s_cbranch_vccz .LBB0_461
	s_and_b64 vcc, exec, s[16:17]
	s_cbranch_vccz .LBB0_464
	s_barrier

; #define PG8_STAGE(bufoff, gbase, voff) do { _Pragma("unroll") for (int _i = 0; _i < 2; ++_i) \
;         __builtin_amdgcn_global_load_lds((const unsigned*)((const char*)(gbase) + (voff)[_i]), (LAS unsigned*)(lds + (bufoff) + ldsw + _i * 8192), 16, 0, 0); } while (0)
; #define PG8_LDA(dst, b, h) do { _Pragma("unroll") for (int m = 0; m < 4; ++m) _Pragma("unroll") for (int k = 0; k < 2; ++k) dst[m][k] = *(const LAS bf16x8*)(lds + PG8_SA(b, h) + aoff + m * 2048 + k * 1024); } while (0)
; #define PG8_LDB(dst, b, h) do { _Pragma("unroll") for (int n = 0; n < 2; ++n) _Pragma("unroll") for (int k = 0; k < 2; ++k) dst[n][k] = *(const LAS bf16x8*)(lds + PG8_SB(b, h) + boff + n * 2048 + k * 1024); } while (0)
; #define PG8_MMA(ai, bj, At, Bt) do { __builtin_amdgcn_s_setprio(1); _Pragma("unroll") for (int m = 0; m < 4; ++m) _Pragma("unroll") for (int n = 0; n < 2; ++n) _Pragma("unroll") for (int k = 0; k < 2; ++k) \
;         acc[ai][bj][m][n] = __builtin_amdgcn_mfma_f32_16x16x32_bf16(Bt[n][k], At[m][k], acc[ai][bj][m][n], 0, 0, 0); __builtin_amdgcn_s_setprio(0); } while (0)
; #define PG8_WAIT_V(n) asm volatile("s_waitcnt vmcnt(" #n ")" ::: "memory")
; #define PG8_WAIT_L(n) asm volatile("s_waitcnt lgkmcnt(" #n ")" ::: "memory")
; #define PG8_BAR __builtin_amdgcn_s_barrier()
; #define PG8_SCHED __builtin_amdgcn_sched_barrier(0)
; DI void gemm_phase(LAS unsigned char* lds, const Gemm g, const StaticOrder& S, const Epi& E) {
;     ...
;             const bool last = (t == nt - 2);
;             const char* a1 = cA + (size_t)(t + 1) * kstep;
;             const char* a2 = last ? nA : cA + (size_t)(t + 2) * kstep; const char* b2 = last ? nB : cB + (size_t)(t + 2) * kstep;
;             const char* a3 = a2 + kstep; const char* b3 = b2 + kstep;
;             PG8_LDB(B0, 0, 0); PG8_LDB(B1, 0, 1); PG8_SCHED; PG8_LDA(At, 0, 0); PG8_STAGE(PG8_SA(1, 1), a1 + hsA, voffA);
;             PG8_WAIT_V(8); PG8_WAIT_L(0); PG8_BAR; PG8_MMA(0, 0, At, B0); PG8_MMA(0, 1, At, B1); PG8_BAR; PG8_SCHED;
;             PG8_LDA(At, 0, 1); PG8_STAGE(PG8_SB(0, 0), b2, voffB); PG8_STAGE(PG8_SB(0, 1), b2 + hsB, voffB); PG8_STAGE(PG8_SA(0, 0), a2, voffA);
;             PG8_WAIT_V(8); PG8_WAIT_L(0); PG8_BAR; PG8_MMA(1, 0, At, B0); PG8_MMA(1, 1, At, B1); PG8_BAR; PG8_SCHED;
.LBB0_525:
	ds_read_b128 v[148:151], v142
	ds_read_b128 v[152:155], v142 offset:1024
	ds_read_b128 v[156:159], v142 offset:2048
	ds_read_b128 v[160:163], v142 offset:3072
	ds_read_b128 v[170:173], v143
	ds_read_b128 v[174:177], v143 offset:1024
	ds_read_b128 v[178:181], v143 offset:2048
	ds_read_b128 v[182:185], v143 offset:3072
	s_add_u32 s16, s14, 0xd03b0080
	s_addc_u32 s17, s15, -1
	s_cmp_lg_u32 s29, 28
	s_cselect_b32 s16, s16, 0
	s_cselect_b32 s17, s17, 0
	s_add_u32 s18, s6, s16
	s_addc_u32 s19, s7, s17
	s_add_u32 s16, s2, s16
	s_addc_u32 s17, s3, s17
	s_mov_b32 m0, s30
	v_lshl_add_u64 v[164:165], v[136:137], 0, s[14:15]
	ds_read_b128 v[186:189], v144
	ds_read_b128 v[190:193], v144 offset:1024
	ds_read_b128 v[194:197], v144 offset:2048
	ds_read_b128 v[198:201], v144 offset:3072
	ds_read_b128 v[202:205], v144 offset:4096
	ds_read_b128 v[206:209], v144 offset:5120
	ds_read_b128 v[210:213], v144 offset:6144
	ds_read_b128 v[214:217], v144 offset:7168
	global_load_lds_dwordx4 v[164:165], off
	v_lshl_add_u64 v[164:165], v[138:139], 0, s[14:15]
	s_mov_b32 m0, s31
	s_nop 0
	global_load_lds_dwordx4 v[164:165], off
	s_waitcnt vmcnt(8)
	s_waitcnt lgkmcnt(0)
	s_barrier
	s_setprio 1
	s_waitcnt lgkmcnt(0)
	v_mfma_f32_16x16x32_bf16 v[124:127], v[148:151], v[186:189], v[124:127]
	v_mfma_f32_16x16x32_bf16 v[124:127], v[152:155], v[190:193], v[124:127]
	v_mfma_f32_16x16x32_bf16 v[120:123], v[160:163], v[190:193], v[120:123]
	v_mfma_f32_16x16x32_bf16 v[120:123], v[156:159], v[186:189], v[120:123]
	v_mfma_f32_16x16x32_bf16 v[104:107], v[156:159], v[194:197], v[104:107]
	v_mfma_f32_16x16x32_bf16 v[104:107], v[160:163], v[198:201], v[104:107]
	v_mfma_f32_16x16x32_bf16 v[108:111], v[152:155], v[198:201], v[108:111]
	v_mfma_f32_16x16x32_bf16 v[108:111], v[148:151], v[194:197], v[108:111]
	v_mfma_f32_16x16x32_bf16 v[92:95], v[148:151], v[202:205], v[92:95]
	v_mfma_f32_16x16x32_bf16 v[92:95], v[152:155], v[206:209], v[92:95]
	v_mfma_f32_16x16x32_bf16 v[88:91], v[160:163], v[206:209], v[88:91]
	v_mfma_f32_16x16x32_bf16 v[88:91], v[156:159], v[202:205], v[88:91]
	v_mfma_f32_16x16x32_bf16 v[72:75], v[156:159], v[210:213], v[72:75]
	v_mfma_f32_16x16x32_bf16 v[72:75], v[160:163], v[214:217], v[72:75]
	v_mfma_f32_16x16x32_bf16 v[76:79], v[152:155], v[214:217], v[76:79]
	v_mfma_f32_16x16x32_bf16 v[76:79], v[148:151], v[210:213], v[76:79]
	s_setprio 0
	s_setprio 1
	v_mfma_f32_16x16x32_bf16 v[116:119], v[170:173], v[186:189], v[116:119]
	v_mfma_f32_16x16x32_bf16 v[116:119], v[174:177], v[190:193], v[116:119]
	v_mfma_f32_16x16x32_bf16 v[112:115], v[182:185], v[190:193], v[112:115]
	v_mfma_f32_16x16x32_bf16 v[112:115], v[178:181], v[186:189], v[112:115]
	v_mfma_f32_16x16x32_bf16 v[96:99], v[178:181], v[194:197], v[96:99]
	v_mfma_f32_16x16x32_bf16 v[96:99], v[182:185], v[198:201], v[96:99]
	v_mfma_f32_16x16x32_bf16 v[100:103], v[174:177], v[198:201], v[100:103]
	v_mfma_f32_16x16x32_bf16 v[100:103], v[170:173], v[194:197], v[100:103]
	v_mfma_f32_16x16x32_bf16 v[84:87], v[170:173], v[202:205], v[84:87]
	v_mfma_f32_16x16x32_bf16 v[84:87], v[174:177], v[206:209], v[84:87]
	v_mfma_f32_16x16x32_bf16 v[80:83], v[182:185], v[206:209], v[80:83]
	v_mfma_f32_16x16x32_bf16 v[80:83], v[178:181], v[202:205], v[80:83]
	v_mfma_f32_16x16x32_bf16 v[64:67], v[178:181], v[210:213], v[64:67]
	v_mfma_f32_16x16x32_bf16 v[64:67], v[182:185], v[214:217], v[64:67]
	v_mfma_f32_16x16x32_bf16 v[68:71], v[174:177], v[214:217], v[68:71]
	v_mfma_f32_16x16x32_bf16 v[68:71], v[170:173], v[210:213], v[68:71]
	s_setprio 0
	s_barrier
	s_mov_b32 m0, s33
	v_lshl_add_u64 v[164:165], s[16:17], 0, v[130:131]
	s_add_u32 s46, s16, 0x80000
	ds_read_b128 v[186:189], v144 offset:16384
	ds_read_b128 v[190:193], v144 offset:17408
	ds_read_b128 v[194:197], v144 offset:18432
	ds_read_b128 v[198:201], v144 offset:19456
	ds_read_b128 v[202:205], v144 offset:20480
	ds_read_b128 v[206:209], v144 offset:21504
	ds_read_b128 v[210:213], v144 offset:22528
	ds_read_b128 v[214:217], v144 offset:23552
	global_load_lds_dwordx4 v[164:165], off
	v_lshl_add_u64 v[218:219], s[16:17], 0, v[134:135]
	s_mov_b32 m0, s34
	s_addc_u32 s47, s17, 0
	global_load_lds_dwordx4 v[218:219], off
	v_lshl_add_u64 v[220:221], s[46:47], 0, v[130:131]
	s_mov_b32 m0, s35
	v_lshl_add_u64 v[222:223], s[18:19], 0, v[132:133]
	global_load_lds_dwordx4 v[220:221], off
	v_lshl_add_u64 v[220:221], s[46:47], 0, v[134:135]
	s_mov_b32 m0, s40
	s_nop 0
	global_load_lds_dwordx4 v[220:221], off
	v_lshl_add_u64 v[220:221], s[18:19], 0, v[128:129]
	s_mov_b32 m0, s22
	s_nop 0
	global_load_lds_dwordx4 v[220:221], off
	s_mov_b32 m0, s23
	s_nop 0
	global_load_lds_dwordx4 v[222:223], off
	s_waitcnt vmcnt(8)
	s_waitcnt lgkmcnt(0)
	s_barrier
; #define PG8_STAGE(bufoff, gbase, voff) do { _Pragma("unroll") for (int _i = 0; _i < 2; ++_i) \
;         __builtin_amdgcn_global_load_lds((const unsigned*)((const char*)(gbase) + (voff)[_i]), (LAS unsigned*)(lds + (bufoff) + ldsw + _i * 8192), 16, 0, 0); } while (0)
; #define PG8_LDA(dst, b, h) do { _Pragma("unroll") for (int m = 0; m < 4; ++m) _Pragma("unroll") for (int k = 0; k < 2; ++k) dst[m][k] = *(const LAS bf16x8*)(lds + PG8_SA(b, h) + aoff + m * 2048 + k * 1024); } while (0)
; #define PG8_LDB(dst, b, h) do { _Pragma("unroll") for (int n = 0; n < 2; ++n) _Pragma("unroll") for (int k = 0; k < 2; ++k) dst[n][k] = *(const LAS bf16x8*)(lds + PG8_SB(b, h) + boff + n * 2048 + k * 1024); } while (0)
; #define PG8_MMA(ai, bj, At, Bt) do { __builtin_amdgcn_s_setprio(1); _Pragma("unroll") for (int m = 0; m < 4; ++m) _Pragma("unroll") for (int n = 0; n < 2; ++n) _Pragma("unroll") for (int k = 0; k < 2; ++k) \
;         acc[ai][bj][m][n] = __builtin_amdgcn_mfma_f32_16x16x32_bf16(Bt[n][k], At[m][k], acc[ai][bj][m][n], 0, 0, 0); __builtin_amdgcn_s_setprio(0); } while (0)
; #define PG8_WAIT_V(n) asm volatile("s_waitcnt vmcnt(" #n ")" ::: "memory")
; #define PG8_WAIT_L(n) asm volatile("s_waitcnt lgkmcnt(" #n ")" ::: "memory")
; #define PG8_BAR __builtin_amdgcn_s_barrier()
; #define PG8_SCHED __builtin_amdgcn_sched_barrier(0)
; DI void gemm_phase(LAS unsigned char* lds, const Gemm g, const StaticOrder& S, const Epi& E) {
;     ...
;             PG8_WAIT_V(8); PG8_WAIT_L(0); PG8_BAR; PG8_MMA(1, 0, At, B0); PG8_MMA(1, 1, At, B1); PG8_BAR; PG8_SCHED;
;             PG8_LDB(B0, 1, 0); PG8_LDB(B1, 1, 1); PG8_SCHED; PG8_LDA(At, 1, 0); PG8_STAGE(PG8_SA(0, 1), a2 + hsA, voffA);
;             PG8_WAIT_V(8); PG8_WAIT_L(0); PG8_BAR; PG8_MMA(0, 0, At, B0); PG8_MMA(0, 1, At, B1); PG8_BAR; PG8_SCHED;
	s_setprio 1
	s_waitcnt lgkmcnt(0)
	v_mfma_f32_16x16x32_bf16 v[60:63], v[148:151], v[186:189], v[60:63]
	v_mfma_f32_16x16x32_bf16 v[60:63], v[152:155], v[190:193], v[60:63]
	v_mfma_f32_16x16x32_bf16 v[56:59], v[160:163], v[190:193], v[56:59]
	v_mfma_f32_16x16x32_bf16 v[56:59], v[156:159], v[186:189], v[56:59]
	v_mfma_f32_16x16x32_bf16 v[40:43], v[156:159], v[194:197], v[40:43]
	v_mfma_f32_16x16x32_bf16 v[40:43], v[160:163], v[198:201], v[40:43]
	v_mfma_f32_16x16x32_bf16 v[44:47], v[152:155], v[198:201], v[44:47]
	v_mfma_f32_16x16x32_bf16 v[44:47], v[148:151], v[194:197], v[44:47]
	v_mfma_f32_16x16x32_bf16 v[28:31], v[148:151], v[202:205], v[28:31]
	v_mfma_f32_16x16x32_bf16 v[28:31], v[152:155], v[206:209], v[28:31]
	v_mfma_f32_16x16x32_bf16 v[24:27], v[160:163], v[206:209], v[24:27]
	v_mfma_f32_16x16x32_bf16 v[24:27], v[156:159], v[202:205], v[24:27]
	v_mfma_f32_16x16x32_bf16 v[8:11], v[156:159], v[210:213], v[8:11]
	v_mfma_f32_16x16x32_bf16 v[8:11], v[160:163], v[214:217], v[8:11]
	v_mfma_f32_16x16x32_bf16 v[12:15], v[152:155], v[214:217], v[12:15]
	v_mfma_f32_16x16x32_bf16 v[12:15], v[148:151], v[210:213], v[12:15]
	s_setprio 0
	s_setprio 1
	v_mfma_f32_16x16x32_bf16 v[52:55], v[170:173], v[186:189], v[52:55]
	v_mfma_f32_16x16x32_bf16 v[52:55], v[174:177], v[190:193], v[52:55]
	v_mfma_f32_16x16x32_bf16 v[48:51], v[182:185], v[190:193], v[48:51]
	v_mfma_f32_16x16x32_bf16 v[48:51], v[178:181], v[186:189], v[48:51]
	v_mfma_f32_16x16x32_bf16 v[32:35], v[178:181], v[194:197], v[32:35]
	v_mfma_f32_16x16x32_bf16 v[32:35], v[182:185], v[198:201], v[32:35]
	v_mfma_f32_16x16x32_bf16 v[36:39], v[174:177], v[198:201], v[36:39]
	v_mfma_f32_16x16x32_bf16 v[36:39], v[170:173], v[194:197], v[36:39]
	v_mfma_f32_16x16x32_bf16 v[20:23], v[170:173], v[202:205], v[20:23]
	v_mfma_f32_16x16x32_bf16 v[20:23], v[174:177], v[206:209], v[20:23]
	v_mfma_f32_16x16x32_bf16 v[16:19], v[182:185], v[206:209], v[16:19]
	v_mfma_f32_16x16x32_bf16 v[16:19], v[178:181], v[202:205], v[16:19]
	v_mfma_f32_16x16x32_bf16 v[0:3], v[178:181], v[210:213], v[0:3]
	v_mfma_f32_16x16x32_bf16 v[0:3], v[182:185], v[214:217], v[0:3]
	v_mfma_f32_16x16x32_bf16 v[4:7], v[174:177], v[214:217], v[4:7]
	v_mfma_f32_16x16x32_bf16 v[4:7], v[170:173], v[210:213], v[4:7]
	s_setprio 0
	s_barrier
	ds_read_b128 v[148:151], v145
	ds_read_b128 v[152:155], v145 offset:1024
	ds_read_b128 v[156:159], v145 offset:2048
	ds_read_b128 v[160:163], v145 offset:3072
	ds_read_b128 v[170:173], v146
	ds_read_b128 v[174:177], v146 offset:1024
	ds_read_b128 v[178:181], v146 offset:2048
	ds_read_b128 v[182:185], v146 offset:3072
	s_add_u32 s18, s18, 0x40000
	s_addc_u32 s19, s19, 0
	s_mov_b32 m0, s24
	v_lshl_add_u64 v[224:225], s[18:19], 0, v[128:129]
	ds_read_b128 v[186:189], v144 offset:32768
	ds_read_b128 v[190:193], v144 offset:33792
	ds_read_b128 v[194:197], v144 offset:34816
	ds_read_b128 v[198:201], v144 offset:35840
	ds_read_b128 v[202:205], v144 offset:36864
	ds_read_b128 v[206:209], v144 offset:37888
	ds_read_b128 v[210:213], v144 offset:38912
	ds_read_b128 v[214:217], v144 offset:39936
	global_load_lds_dwordx4 v[224:225], off
	v_lshl_add_u64 v[224:225], s[18:19], 0, v[132:133]
	s_mov_b32 m0, s25
	s_nop 0
	global_load_lds_dwordx4 v[224:225], off
	s_waitcnt vmcnt(8)
	s_waitcnt lgkmcnt(0)
	s_barrier
	s_setprio 1
	s_waitcnt lgkmcnt(0)
	v_mfma_f32_16x16x32_bf16 v[124:127], v[148:151], v[186:189], v[124:127]
	v_mfma_f32_16x16x32_bf16 v[124:127], v[152:155], v[190:193], v[124:127]
	v_mfma_f32_16x16x32_bf16 v[120:123], v[160:163], v[190:193], v[120:123]
	v_mfma_f32_16x16x32_bf16 v[120:123], v[156:159], v[186:189], v[120:123]
	v_mfma_f32_16x16x32_bf16 v[104:107], v[156:159], v[194:197], v[104:107]
	v_mfma_f32_16x16x32_bf16 v[104:107], v[160:163], v[198:201], v[104:107]
	v_mfma_f32_16x16x32_bf16 v[108:111], v[152:155], v[198:201], v[108:111]
	v_mfma_f32_16x16x32_bf16 v[108:111], v[148:151], v[194:197], v[108:111]
	v_mfma_f32_16x16x32_bf16 v[92:95], v[148:151], v[202:205], v[92:95]
	v_mfma_f32_16x16x32_bf16 v[92:95], v[152:155], v[206:209], v[92:95]
	v_mfma_f32_16x16x32_bf16 v[88:91], v[160:163], v[206:209], v[88:91]
	v_mfma_f32_16x16x32_bf16 v[88:91], v[156:159], v[202:205], v[88:91]
	v_mfma_f32_16x16x32_bf16 v[72:75], v[156:159], v[210:213], v[72:75]
	v_mfma_f32_16x16x32_bf16 v[72:75], v[160:163], v[214:217], v[72:75]
	v_mfma_f32_16x16x32_bf16 v[76:79], v[152:155], v[214:217], v[76:79]
	v_mfma_f32_16x16x32_bf16 v[76:79], v[148:151], v[210:213], v[76:79]
	s_setprio 0
	s_setprio 1
	v_mfma_f32_16x16x32_bf16 v[116:119], v[170:173], v[186:189], v[116:119]
	v_mfma_f32_16x16x32_bf16 v[116:119], v[174:177], v[190:193], v[116:119]
	v_mfma_f32_16x16x32_bf16 v[112:115], v[182:185], v[190:193], v[112:115]
	v_mfma_f32_16x16x32_bf16 v[112:115], v[178:181], v[186:189], v[112:115]
	v_mfma_f32_16x16x32_bf16 v[96:99], v[178:181], v[194:197], v[96:99]
	v_mfma_f32_16x16x32_bf16 v[96:99], v[182:185], v[198:201], v[96:99]
	v_mfma_f32_16x16x32_bf16 v[100:103], v[174:177], v[198:201], v[100:103]
	v_mfma_f32_16x16x32_bf16 v[100:103], v[170:173], v[194:197], v[100:103]
	v_mfma_f32_16x16x32_bf16 v[84:87], v[170:173], v[202:205], v[84:87]
	v_mfma_f32_16x16x32_bf16 v[84:87], v[174:177], v[206:209], v[84:87]
	v_mfma_f32_16x16x32_bf16 v[80:83], v[182:185], v[206:209], v[80:83]
	v_mfma_f32_16x16x32_bf16 v[80:83], v[178:181], v[202:205], v[80:83]
	v_mfma_f32_16x16x32_bf16 v[64:67], v[178:181], v[210:213], v[64:67]
	v_mfma_f32_16x16x32_bf16 v[64:67], v[182:185], v[214:217], v[64:67]
	v_mfma_f32_16x16x32_bf16 v[68:71], v[174:177], v[214:217], v[68:71]
	v_mfma_f32_16x16x32_bf16 v[68:71], v[170:173], v[210:213], v[68:71]
	s_setprio 0
	s_barrier
; #define PG8_STAGE(bufoff, gbase, voff) do { _Pragma("unroll") for (int _i = 0; _i < 2; ++_i) \
;         __builtin_amdgcn_global_load_lds((const unsigned*)((const char*)(gbase) + (voff)[_i]), (LAS unsigned*)(lds + (bufoff) + ldsw + _i * 8192), 16, 0, 0); } while (0)
; #define PG8_LDA(dst, b, h) do { _Pragma("unroll") for (int m = 0; m < 4; ++m) _Pragma("unroll") for (int k = 0; k < 2; ++k) dst[m][k] = *(const LAS bf16x8*)(lds + PG8_SA(b, h) + aoff + m * 2048 + k * 1024); } while (0)
; #define PG8_MMA(ai, bj, At, Bt) do { __builtin_amdgcn_s_setprio(1); _Pragma("unroll") for (int m = 0; m < 4; ++m) _Pragma("unroll") for (int n = 0; n < 2; ++n) _Pragma("unroll") for (int k = 0; k < 2; ++k) \
;         acc[ai][bj][m][n] = __builtin_amdgcn_mfma_f32_16x16x32_bf16(Bt[n][k], At[m][k], acc[ai][bj][m][n], 0, 0, 0); __builtin_amdgcn_s_setprio(0); } while (0)
; #define PG8_WAIT_V(n) asm volatile("s_waitcnt vmcnt(" #n ")" ::: "memory")
; #define PG8_WAIT_L(n) asm volatile("s_waitcnt lgkmcnt(" #n ")" ::: "memory")
; #define PG8_BAR __builtin_amdgcn_s_barrier()
; #define PG8_SCHED __builtin_amdgcn_sched_barrier(0)
; DI void gemm_phase(LAS unsigned char* lds, const Gemm g, const StaticOrder& S, const Epi& E) {
;     ...
;             PG8_LDA(At, 1, 1); PG8_STAGE(PG8_SB(1, 0), b3, voffB); PG8_STAGE(PG8_SB(1, 1), b3 + hsB, voffB); PG8_STAGE(PG8_SA(1, 0), a3, voffA);
;             PG8_WAIT_V(8); PG8_WAIT_L(0); PG8_BAR; PG8_MMA(1, 0, At, B0); PG8_MMA(1, 1, At, B1); PG8_BAR; PG8_SCHED;
;         }
	s_mov_b32 m0, s41
	v_lshl_add_u64 v[164:165], v[164:165], 0, s[10:11]
	s_add_u32 s16, s16, 0x80080
	ds_read_b128 v[186:189], v144 offset:49152
	ds_read_b128 v[190:193], v144 offset:50176
	ds_read_b128 v[194:197], v144 offset:51200
	ds_read_b128 v[198:201], v144 offset:52224
	ds_read_b128 v[202:205], v144 offset:53248
	ds_read_b128 v[206:209], v144 offset:54272
	ds_read_b128 v[210:213], v144 offset:55296
	ds_read_b128 v[214:217], v144 offset:56320
	global_load_lds_dwordx4 v[164:165], off
	v_lshl_add_u64 v[164:165], v[218:219], 0, s[10:11]
	s_mov_b32 m0, s42
	s_addc_u32 s17, s17, 0
	global_load_lds_dwordx4 v[164:165], off
	v_lshl_add_u64 v[164:165], s[16:17], 0, v[130:131]
	s_mov_b32 m0, s43
	s_nop 0
	global_load_lds_dwordx4 v[164:165], off
	v_lshl_add_u64 v[164:165], s[16:17], 0, v[134:135]
	s_mov_b32 m0, s48
	s_nop 0
	global_load_lds_dwordx4 v[164:165], off
	v_lshl_add_u64 v[164:165], v[220:221], 0, s[10:11]
	s_mov_b32 m0, s27
	s_nop 0
	global_load_lds_dwordx4 v[164:165], off
	v_lshl_add_u64 v[164:165], v[222:223], 0, s[10:11]
	s_mov_b32 m0, s28
	s_nop 0
	global_load_lds_dwordx4 v[164:165], off
	s_waitcnt vmcnt(8)
	s_waitcnt lgkmcnt(0)
	s_barrier
	s_setprio 1
	s_waitcnt lgkmcnt(0)
	v_mfma_f32_16x16x32_bf16 v[60:63], v[148:151], v[186:189], v[60:63]
	v_mfma_f32_16x16x32_bf16 v[60:63], v[152:155], v[190:193], v[60:63]
	v_mfma_f32_16x16x32_bf16 v[56:59], v[160:163], v[190:193], v[56:59]
	v_mfma_f32_16x16x32_bf16 v[56:59], v[156:159], v[186:189], v[56:59]
	v_mfma_f32_16x16x32_bf16 v[40:43], v[156:159], v[194:197], v[40:43]
	v_mfma_f32_16x16x32_bf16 v[40:43], v[160:163], v[198:201], v[40:43]
	v_mfma_f32_16x16x32_bf16 v[44:47], v[152:155], v[198:201], v[44:47]
	v_mfma_f32_16x16x32_bf16 v[44:47], v[148:151], v[194:197], v[44:47]
	v_mfma_f32_16x16x32_bf16 v[28:31], v[148:151], v[202:205], v[28:31]
	v_mfma_f32_16x16x32_bf16 v[28:31], v[152:155], v[206:209], v[28:31]
	v_mfma_f32_16x16x32_bf16 v[24:27], v[160:163], v[206:209], v[24:27]
	v_mfma_f32_16x16x32_bf16 v[24:27], v[156:159], v[202:205], v[24:27]
	v_mfma_f32_16x16x32_bf16 v[8:11], v[156:159], v[210:213], v[8:11]
	v_mfma_f32_16x16x32_bf16 v[8:11], v[160:163], v[214:217], v[8:11]
	v_mfma_f32_16x16x32_bf16 v[12:15], v[152:155], v[214:217], v[12:15]
	v_mfma_f32_16x16x32_bf16 v[12:15], v[148:151], v[210:213], v[12:15]
	s_setprio 0
	s_setprio 1
	v_mfma_f32_16x16x32_bf16 v[52:55], v[170:173], v[186:189], v[52:55]
	v_mfma_f32_16x16x32_bf16 v[52:55], v[174:177], v[190:193], v[52:55]
	v_mfma_f32_16x16x32_bf16 v[48:51], v[182:185], v[190:193], v[48:51]
	v_mfma_f32_16x16x32_bf16 v[48:51], v[178:181], v[186:189], v[48:51]
	v_mfma_f32_16x16x32_bf16 v[32:35], v[178:181], v[194:197], v[32:35]
	v_mfma_f32_16x16x32_bf16 v[32:35], v[182:185], v[198:201], v[32:35]
	v_mfma_f32_16x16x32_bf16 v[36:39], v[174:177], v[198:201], v[36:39]
	v_mfma_f32_16x16x32_bf16 v[36:39], v[170:173], v[194:197], v[36:39]
	v_mfma_f32_16x16x32_bf16 v[20:23], v[170:173], v[202:205], v[20:23]
	v_mfma_f32_16x16x32_bf16 v[20:23], v[174:177], v[206:209], v[20:23]
	v_mfma_f32_16x16x32_bf16 v[16:19], v[182:185], v[206:209], v[16:19]
	v_mfma_f32_16x16x32_bf16 v[16:19], v[178:181], v[202:205], v[16:19]
	v_mfma_f32_16x16x32_bf16 v[0:3], v[178:181], v[210:213], v[0:3]
	v_mfma_f32_16x16x32_bf16 v[0:3], v[182:185], v[214:217], v[0:3]
	v_mfma_f32_16x16x32_bf16 v[4:7], v[174:177], v[214:217], v[4:7]
	v_mfma_f32_16x16x32_bf16 v[4:7], v[170:173], v[210:213], v[4:7]
	s_setprio 0
	s_barrier
	s_add_i32 s29, s29, 2
	s_add_u32 s14, s14, 0x100
	s_addc_u32 s15, s15, 0
	s_cmp_gt_u32 s29, 29
	s_cbranch_scc0 .LBB0_525
	s_cmpk_lt_u32 s5, 0x100
	s_cbranch_scc0 .LBB0_528
	s_barrier

; #define PG8_STAGE(bufoff, gbase, voff) do { _Pragma("unroll") for (int _i = 0; _i < 2; ++_i) \
;         __builtin_amdgcn_global_load_lds((const unsigned*)((const char*)(gbase) + (voff)[_i]), (LAS unsigned*)(lds + (bufoff) + ldsw + _i * 8192), 16, 0, 0); } while (0)
; #define PG8_LDA(dst, b, h) do { _Pragma("unroll") for (int m = 0; m < 4; ++m) _Pragma("unroll") for (int k = 0; k < 2; ++k) dst[m][k] = *(const LAS bf16x8*)(lds + PG8_SA(b, h) + aoff + m * 2048 + k * 1024); } while (0)
; #define PG8_LDB(dst, b, h) do { _Pragma("unroll") for (int n = 0; n < 2; ++n) _Pragma("unroll") for (int k = 0; k < 2; ++k) dst[n][k] = *(const LAS bf16x8*)(lds + PG8_SB(b, h) + boff + n * 2048 + k * 1024); } while (0)
; #define PG8_MMA(ai, bj, At, Bt) do { __builtin_amdgcn_s_setprio(1); _Pragma("unroll") for (int m = 0; m < 4; ++m) _Pragma("unroll") for (int n = 0; n < 2; ++n) _Pragma("unroll") for (int k = 0; k < 2; ++k) \
;         acc[ai][bj][m][n] = __builtin_amdgcn_mfma_f32_16x16x32_bf16(Bt[n][k], At[m][k], acc[ai][bj][m][n], 0, 0, 0); __builtin_amdgcn_s_setprio(0); } while (0)
; #define PG8_WAIT_V(n) asm volatile("s_waitcnt vmcnt(" #n ")" ::: "memory")
; #define PG8_WAIT_L(n) asm volatile("s_waitcnt lgkmcnt(" #n ")" ::: "memory")
; #define PG8_BAR __builtin_amdgcn_s_barrier()
; #define PG8_SCHED __builtin_amdgcn_sched_barrier(0)
; DI void gemm_phase(LAS unsigned char* lds, const Gemm g, const StaticOrder& S, const Epi& E) {
;     ...
;             const bool last = (t == nt - 2);
;             const char* a1 = cA + (size_t)(t + 1) * kstep;
;             const char* a2 = last ? nA : cA + (size_t)(t + 2) * kstep; const char* b2 = last ? nB : cB + (size_t)(t + 2) * kstep;
;             const char* a3 = a2 + kstep; const char* b3 = b2 + kstep;
;             PG8_LDB(B0, 0, 0); PG8_LDB(B1, 0, 1); PG8_SCHED; PG8_LDA(At, 0, 0); PG8_STAGE(PG8_SA(1, 1), a1 + hsA, voffA);
;             PG8_WAIT_V(8); PG8_WAIT_L(0); PG8_BAR; PG8_MMA(0, 0, At, B0); PG8_MMA(0, 1, At, B1); PG8_BAR; PG8_SCHED;
;             PG8_LDA(At, 0, 1); PG8_STAGE(PG8_SB(0, 0), b2, voffB); PG8_STAGE(PG8_SB(0, 1), b2 + hsB, voffB); PG8_STAGE(PG8_SA(0, 0), a2, voffA);
;             PG8_WAIT_V(8); PG8_WAIT_L(0); PG8_BAR; PG8_MMA(1, 0, At, B0); PG8_MMA(1, 1, At, B1); PG8_BAR; PG8_SCHED;
.LBB0_531:
	s_add_i32 s1, s21, 0x100
	s_and_b64 s[12:13], s[14:15], exec
	s_cselect_b32 s1, 0, s1
	s_cselect_b32 s12, 0, 0
	s_add_u32 s16, s4, s1
	s_addc_u32 s17, s5, s12
	s_add_u32 s18, s2, s1
	ds_read_b128 v[144:147], v138
	ds_read_b128 v[148:151], v138 offset:1024
	ds_read_b128 v[152:155], v138 offset:2048
	ds_read_b128 v[156:159], v138 offset:3072
	ds_read_b128 v[160:163], v139
	ds_read_b128 v[170:173], v139 offset:1024
	ds_read_b128 v[174:177], v139 offset:2048
	ds_read_b128 v[178:181], v139 offset:3072
	s_addc_u32 s19, s3, s12
	s_add_u32 s1, s62, s21
	s_addc_u32 s12, s63, 0
	s_add_u32 s24, s1, 0x2e9b0080
	s_addc_u32 s25, s12, 0
	s_add_u32 s20, s18, 0x10000
	s_addc_u32 s21, s19, 0
	s_add_u32 s14, s16, 0x10000
	s_addc_u32 s15, s17, 0
	s_add_u32 s22, s18, 0x10080
	s_addc_u32 s23, s19, 0
	s_mov_b32 m0, s35
	v_lshl_add_u64 v[164:165], s[24:25], 0, v[128:129]
	ds_read_b128 v[182:185], v140
	ds_read_b128 v[186:189], v140 offset:1024
	ds_read_b128 v[190:193], v140 offset:2048
	ds_read_b128 v[194:197], v140 offset:3072
	ds_read_b128 v[198:201], v140 offset:4096
	ds_read_b128 v[202:205], v140 offset:5120
	ds_read_b128 v[206:209], v140 offset:6144
	ds_read_b128 v[210:213], v140 offset:7168
	global_load_lds_dwordx4 v[164:165], off
	v_lshl_add_u64 v[164:165], s[24:25], 0, v[132:133]
	s_mov_b32 m0, s40
	s_nop 0
	global_load_lds_dwordx4 v[164:165], off
	s_waitcnt vmcnt(8)
	s_waitcnt lgkmcnt(0)
	s_barrier
	s_setprio 1
	s_waitcnt lgkmcnt(0)
	v_mfma_f32_16x16x32_bf16 v[124:127], v[144:147], v[182:185], v[124:127]
	v_mfma_f32_16x16x32_bf16 v[124:127], v[148:151], v[186:189], v[124:127]
	v_mfma_f32_16x16x32_bf16 v[120:123], v[156:159], v[186:189], v[120:123]
	v_mfma_f32_16x16x32_bf16 v[120:123], v[152:155], v[182:185], v[120:123]
	v_mfma_f32_16x16x32_bf16 v[104:107], v[152:155], v[190:193], v[104:107]
	v_mfma_f32_16x16x32_bf16 v[104:107], v[156:159], v[194:197], v[104:107]
	v_mfma_f32_16x16x32_bf16 v[112:115], v[148:151], v[194:197], v[112:115]
	v_mfma_f32_16x16x32_bf16 v[112:115], v[144:147], v[190:193], v[112:115]
	v_mfma_f32_16x16x32_bf16 v[96:99], v[144:147], v[198:201], v[96:99]
	v_mfma_f32_16x16x32_bf16 v[96:99], v[148:151], v[202:205], v[96:99]
	v_mfma_f32_16x16x32_bf16 v[88:91], v[156:159], v[202:205], v[88:91]
	v_mfma_f32_16x16x32_bf16 v[88:91], v[152:155], v[198:201], v[88:91]
	v_mfma_f32_16x16x32_bf16 v[72:75], v[152:155], v[206:209], v[72:75]
	v_mfma_f32_16x16x32_bf16 v[72:75], v[156:159], v[210:213], v[72:75]
	v_mfma_f32_16x16x32_bf16 v[80:83], v[148:151], v[210:213], v[80:83]
	v_mfma_f32_16x16x32_bf16 v[80:83], v[144:147], v[206:209], v[80:83]
	s_setprio 0
	s_setprio 1
	v_mfma_f32_16x16x32_bf16 v[116:119], v[160:163], v[182:185], v[116:119]
	v_mfma_f32_16x16x32_bf16 v[116:119], v[170:173], v[186:189], v[116:119]
	v_mfma_f32_16x16x32_bf16 v[108:111], v[178:181], v[186:189], v[108:111]
	v_mfma_f32_16x16x32_bf16 v[108:111], v[174:177], v[182:185], v[108:111]
	v_mfma_f32_16x16x32_bf16 v[92:95], v[174:177], v[190:193], v[92:95]
	v_mfma_f32_16x16x32_bf16 v[92:95], v[178:181], v[194:197], v[92:95]
	v_mfma_f32_16x16x32_bf16 v[100:103], v[170:173], v[194:197], v[100:103]
	v_mfma_f32_16x16x32_bf16 v[100:103], v[160:163], v[190:193], v[100:103]
	v_mfma_f32_16x16x32_bf16 v[84:87], v[160:163], v[198:201], v[84:87]
	v_mfma_f32_16x16x32_bf16 v[84:87], v[170:173], v[202:205], v[84:87]
	v_mfma_f32_16x16x32_bf16 v[76:79], v[178:181], v[202:205], v[76:79]
	v_mfma_f32_16x16x32_bf16 v[76:79], v[174:177], v[198:201], v[76:79]
	v_mfma_f32_16x16x32_bf16 v[64:67], v[174:177], v[206:209], v[64:67]
	v_mfma_f32_16x16x32_bf16 v[64:67], v[178:181], v[210:213], v[64:67]
	v_mfma_f32_16x16x32_bf16 v[68:71], v[170:173], v[210:213], v[68:71]
	v_mfma_f32_16x16x32_bf16 v[68:71], v[160:163], v[206:209], v[68:71]
	s_setprio 0
	s_barrier
	s_mov_b32 m0, s41
	v_lshl_add_u64 v[164:165], s[18:19], 0, v[130:131]
	ds_read_b128 v[182:185], v140 offset:16384
	ds_read_b128 v[186:189], v140 offset:17408
	ds_read_b128 v[190:193], v140 offset:18432
	ds_read_b128 v[194:197], v140 offset:19456
	ds_read_b128 v[198:201], v140 offset:20480
	ds_read_b128 v[202:205], v140 offset:21504
	ds_read_b128 v[206:209], v140 offset:22528
	ds_read_b128 v[210:213], v140 offset:23552
	global_load_lds_dwordx4 v[164:165], off
	v_lshl_add_u64 v[214:215], s[18:19], 0, v[134:135]
	s_mov_b32 m0, s42
	v_lshl_add_u64 v[216:217], s[20:21], 0, v[130:131]
	global_load_lds_dwordx4 v[214:215], off
	s_mov_b32 m0, s43
	v_lshl_add_u64 v[218:219], s[16:17], 0, v[132:133]
	global_load_lds_dwordx4 v[216:217], off
	v_lshl_add_u64 v[216:217], s[20:21], 0, v[134:135]
	s_mov_b32 m0, s48
	s_nop 0
	global_load_lds_dwordx4 v[216:217], off
	v_lshl_add_u64 v[216:217], s[16:17], 0, v[128:129]
	s_mov_b32 m0, s27
	s_nop 0
	global_load_lds_dwordx4 v[216:217], off
	s_mov_b32 m0, s28
	s_nop 0
	global_load_lds_dwordx4 v[218:219], off
	s_waitcnt vmcnt(8)
	s_waitcnt lgkmcnt(0)
	s_barrier
; #define PG8_STAGE(bufoff, gbase, voff) do { _Pragma("unroll") for (int _i = 0; _i < 2; ++_i) \
;         __builtin_amdgcn_global_load_lds((const unsigned*)((const char*)(gbase) + (voff)[_i]), (LAS unsigned*)(lds + (bufoff) + ldsw + _i * 8192), 16, 0, 0); } while (0)
; #define PG8_LDA(dst, b, h) do { _Pragma("unroll") for (int m = 0; m < 4; ++m) _Pragma("unroll") for (int k = 0; k < 2; ++k) dst[m][k] = *(const LAS bf16x8*)(lds + PG8_SA(b, h) + aoff + m * 2048 + k * 1024); } while (0)
; #define PG8_LDB(dst, b, h) do { _Pragma("unroll") for (int n = 0; n < 2; ++n) _Pragma("unroll") for (int k = 0; k < 2; ++k) dst[n][k] = *(const LAS bf16x8*)(lds + PG8_SB(b, h) + boff + n * 2048 + k * 1024); } while (0)
; #define PG8_MMA(ai, bj, At, Bt) do { __builtin_amdgcn_s_setprio(1); _Pragma("unroll") for (int m = 0; m < 4; ++m) _Pragma("unroll") for (int n = 0; n < 2; ++n) _Pragma("unroll") for (int k = 0; k < 2; ++k) \
;         acc[ai][bj][m][n] = __builtin_amdgcn_mfma_f32_16x16x32_bf16(Bt[n][k], At[m][k], acc[ai][bj][m][n], 0, 0, 0); __builtin_amdgcn_s_setprio(0); } while (0)
; #define PG8_WAIT_V(n) asm volatile("s_waitcnt vmcnt(" #n ")" ::: "memory")
; #define PG8_WAIT_L(n) asm volatile("s_waitcnt lgkmcnt(" #n ")" ::: "memory")
; #define PG8_BAR __builtin_amdgcn_s_barrier()
; #define PG8_SCHED __builtin_amdgcn_sched_barrier(0)
; DI void gemm_phase(LAS unsigned char* lds, const Gemm g, const StaticOrder& S, const Epi& E) {
;     ...
;             PG8_WAIT_V(8); PG8_WAIT_L(0); PG8_BAR; PG8_MMA(1, 0, At, B0); PG8_MMA(1, 1, At, B1); PG8_BAR; PG8_SCHED;
;             PG8_LDB(B0, 1, 0); PG8_LDB(B1, 1, 1); PG8_SCHED; PG8_LDA(At, 1, 0); PG8_STAGE(PG8_SA(0, 1), a2 + hsA, voffA);
;             PG8_WAIT_V(8); PG8_WAIT_L(0); PG8_BAR; PG8_MMA(0, 0, At, B0); PG8_MMA(0, 1, At, B1); PG8_BAR; PG8_SCHED;
	s_setprio 1
	s_waitcnt lgkmcnt(0)
	v_mfma_f32_16x16x32_bf16 v[60:63], v[144:147], v[182:185], v[60:63]
	v_mfma_f32_16x16x32_bf16 v[60:63], v[148:151], v[186:189], v[60:63]
	v_mfma_f32_16x16x32_bf16 v[56:59], v[156:159], v[186:189], v[56:59]
	v_mfma_f32_16x16x32_bf16 v[56:59], v[152:155], v[182:185], v[56:59]
	v_mfma_f32_16x16x32_bf16 v[40:43], v[152:155], v[190:193], v[40:43]
	v_mfma_f32_16x16x32_bf16 v[40:43], v[156:159], v[194:197], v[40:43]
	v_mfma_f32_16x16x32_bf16 v[48:51], v[148:151], v[194:197], v[48:51]
	v_mfma_f32_16x16x32_bf16 v[48:51], v[144:147], v[190:193], v[48:51]
	v_mfma_f32_16x16x32_bf16 v[32:35], v[144:147], v[198:201], v[32:35]
	v_mfma_f32_16x16x32_bf16 v[32:35], v[148:151], v[202:205], v[32:35]
	v_mfma_f32_16x16x32_bf16 v[24:27], v[156:159], v[202:205], v[24:27]
	v_mfma_f32_16x16x32_bf16 v[24:27], v[152:155], v[198:201], v[24:27]
	v_mfma_f32_16x16x32_bf16 v[8:11], v[152:155], v[206:209], v[8:11]
	v_mfma_f32_16x16x32_bf16 v[8:11], v[156:159], v[210:213], v[8:11]
	v_mfma_f32_16x16x32_bf16 v[16:19], v[148:151], v[210:213], v[16:19]
	v_mfma_f32_16x16x32_bf16 v[16:19], v[144:147], v[206:209], v[16:19]
	s_setprio 0
	s_setprio 1
	v_mfma_f32_16x16x32_bf16 v[52:55], v[160:163], v[182:185], v[52:55]
	v_mfma_f32_16x16x32_bf16 v[52:55], v[170:173], v[186:189], v[52:55]
	v_mfma_f32_16x16x32_bf16 v[44:47], v[178:181], v[186:189], v[44:47]
	v_mfma_f32_16x16x32_bf16 v[44:47], v[174:177], v[182:185], v[44:47]
	v_mfma_f32_16x16x32_bf16 v[28:31], v[174:177], v[190:193], v[28:31]
	v_mfma_f32_16x16x32_bf16 v[28:31], v[178:181], v[194:197], v[28:31]
	v_mfma_f32_16x16x32_bf16 v[36:39], v[170:173], v[194:197], v[36:39]
	v_mfma_f32_16x16x32_bf16 v[36:39], v[160:163], v[190:193], v[36:39]
	v_mfma_f32_16x16x32_bf16 v[20:23], v[160:163], v[198:201], v[20:23]
	v_mfma_f32_16x16x32_bf16 v[20:23], v[170:173], v[202:205], v[20:23]
	v_mfma_f32_16x16x32_bf16 v[12:15], v[178:181], v[202:205], v[12:15]
	v_mfma_f32_16x16x32_bf16 v[12:15], v[174:177], v[198:201], v[12:15]
	v_mfma_f32_16x16x32_bf16 v[0:3], v[174:177], v[206:209], v[0:3]
	v_mfma_f32_16x16x32_bf16 v[0:3], v[178:181], v[210:213], v[0:3]
	v_mfma_f32_16x16x32_bf16 v[4:7], v[170:173], v[210:213], v[4:7]
	v_mfma_f32_16x16x32_bf16 v[4:7], v[160:163], v[206:209], v[4:7]
	s_setprio 0
	s_barrier
	ds_read_b128 v[144:147], v141
	ds_read_b128 v[148:151], v141 offset:1024
	ds_read_b128 v[152:155], v141 offset:2048
	ds_read_b128 v[156:159], v141 offset:3072
	ds_read_b128 v[160:163], v142
	ds_read_b128 v[170:173], v142 offset:1024
	ds_read_b128 v[174:177], v142 offset:2048
	ds_read_b128 v[178:181], v142 offset:3072
	s_mov_b32 m0, s29
	v_lshl_add_u64 v[220:221], s[14:15], 0, v[128:129]
	ds_read_b128 v[182:185], v140 offset:32768
	ds_read_b128 v[186:189], v140 offset:33792
	ds_read_b128 v[190:193], v140 offset:34816
	ds_read_b128 v[194:197], v140 offset:35840
	ds_read_b128 v[198:201], v140 offset:36864
	ds_read_b128 v[202:205], v140 offset:37888
	ds_read_b128 v[206:209], v140 offset:38912
	ds_read_b128 v[210:213], v140 offset:39936
	global_load_lds_dwordx4 v[220:221], off
	v_lshl_add_u64 v[220:221], s[14:15], 0, v[132:133]
	s_mov_b32 m0, s30
	s_nop 0
	global_load_lds_dwordx4 v[220:221], off
	s_waitcnt vmcnt(8)
	s_waitcnt lgkmcnt(0)
	s_barrier
	s_setprio 1
	s_waitcnt lgkmcnt(0)
	v_mfma_f32_16x16x32_bf16 v[124:127], v[144:147], v[182:185], v[124:127]
	v_mfma_f32_16x16x32_bf16 v[124:127], v[148:151], v[186:189], v[124:127]
	v_mfma_f32_16x16x32_bf16 v[120:123], v[156:159], v[186:189], v[120:123]
	v_mfma_f32_16x16x32_bf16 v[120:123], v[152:155], v[182:185], v[120:123]
	v_mfma_f32_16x16x32_bf16 v[104:107], v[152:155], v[190:193], v[104:107]
	v_mfma_f32_16x16x32_bf16 v[104:107], v[156:159], v[194:197], v[104:107]
	v_mfma_f32_16x16x32_bf16 v[112:115], v[148:151], v[194:197], v[112:115]
	v_mfma_f32_16x16x32_bf16 v[112:115], v[144:147], v[190:193], v[112:115]
	v_mfma_f32_16x16x32_bf16 v[96:99], v[144:147], v[198:201], v[96:99]
	v_mfma_f32_16x16x32_bf16 v[96:99], v[148:151], v[202:205], v[96:99]
	v_mfma_f32_16x16x32_bf16 v[88:91], v[156:159], v[202:205], v[88:91]
	v_mfma_f32_16x16x32_bf16 v[88:91], v[152:155], v[198:201], v[88:91]
	v_mfma_f32_16x16x32_bf16 v[72:75], v[152:155], v[206:209], v[72:75]
	v_mfma_f32_16x16x32_bf16 v[72:75], v[156:159], v[210:213], v[72:75]
	v_mfma_f32_16x16x32_bf16 v[80:83], v[148:151], v[210:213], v[80:83]
	v_mfma_f32_16x16x32_bf16 v[80:83], v[144:147], v[206:209], v[80:83]
	s_setprio 0
	s_setprio 1
	v_mfma_f32_16x16x32_bf16 v[116:119], v[160:163], v[182:185], v[116:119]
	v_mfma_f32_16x16x32_bf16 v[116:119], v[170:173], v[186:189], v[116:119]
	v_mfma_f32_16x16x32_bf16 v[108:111], v[178:181], v[186:189], v[108:111]
	v_mfma_f32_16x16x32_bf16 v[108:111], v[174:177], v[182:185], v[108:111]
	v_mfma_f32_16x16x32_bf16 v[92:95], v[174:177], v[190:193], v[92:95]
	v_mfma_f32_16x16x32_bf16 v[92:95], v[178:181], v[194:197], v[92:95]
	v_mfma_f32_16x16x32_bf16 v[100:103], v[170:173], v[194:197], v[100:103]
	v_mfma_f32_16x16x32_bf16 v[100:103], v[160:163], v[190:193], v[100:103]
	v_mfma_f32_16x16x32_bf16 v[84:87], v[160:163], v[198:201], v[84:87]
	v_mfma_f32_16x16x32_bf16 v[84:87], v[170:173], v[202:205], v[84:87]
	v_mfma_f32_16x16x32_bf16 v[76:79], v[178:181], v[202:205], v[76:79]
	v_mfma_f32_16x16x32_bf16 v[76:79], v[174:177], v[198:201], v[76:79]
	v_mfma_f32_16x16x32_bf16 v[64:67], v[174:177], v[206:209], v[64:67]
	v_mfma_f32_16x16x32_bf16 v[64:67], v[178:181], v[210:213], v[64:67]
	v_mfma_f32_16x16x32_bf16 v[68:71], v[170:173], v[210:213], v[68:71]
	v_mfma_f32_16x16x32_bf16 v[68:71], v[160:163], v[206:209], v[68:71]
	s_setprio 0
	s_barrier
; #define PG8_STAGE(bufoff, gbase, voff) do { _Pragma("unroll") for (int _i = 0; _i < 2; ++_i) \
;         __builtin_amdgcn_global_load_lds((const unsigned*)((const char*)(gbase) + (voff)[_i]), (LAS unsigned*)(lds + (bufoff) + ldsw + _i * 8192), 16, 0, 0); } while (0)
; #define PG8_LDA(dst, b, h) do { _Pragma("unroll") for (int m = 0; m < 4; ++m) _Pragma("unroll") for (int k = 0; k < 2; ++k) dst[m][k] = *(const LAS bf16x8*)(lds + PG8_SA(b, h) + aoff + m * 2048 + k * 1024); } while (0)
; #define PG8_MMA(ai, bj, At, Bt) do { __builtin_amdgcn_s_setprio(1); _Pragma("unroll") for (int m = 0; m < 4; ++m) _Pragma("unroll") for (int n = 0; n < 2; ++n) _Pragma("unroll") for (int k = 0; k < 2; ++k) \
;         acc[ai][bj][m][n] = __builtin_amdgcn_mfma_f32_16x16x32_bf16(Bt[n][k], At[m][k], acc[ai][bj][m][n], 0, 0, 0); __builtin_amdgcn_s_setprio(0); } while (0)
; #define PG8_WAIT_V(n) asm volatile("s_waitcnt vmcnt(" #n ")" ::: "memory")
; #define PG8_WAIT_L(n) asm volatile("s_waitcnt lgkmcnt(" #n ")" ::: "memory")
; #define PG8_BAR __builtin_amdgcn_s_barrier()
; #define PG8_SCHED __builtin_amdgcn_sched_barrier(0)
; DI void gemm_phase(LAS unsigned char* lds, const Gemm g, const StaticOrder& S, const Epi& E) {
;     ...
;             PG8_LDA(At, 1, 1); PG8_STAGE(PG8_SB(1, 0), b3, voffB); PG8_STAGE(PG8_SB(1, 1), b3 + hsB, voffB); PG8_STAGE(PG8_SA(1, 0), a3, voffA);
;             PG8_WAIT_V(8); PG8_WAIT_L(0); PG8_BAR; PG8_MMA(1, 0, At, B0); PG8_MMA(1, 1, At, B1); PG8_BAR; PG8_SCHED;
;         }
	s_mov_b32 m0, s49
	v_lshl_add_u64 v[164:165], v[164:165], 0, s[6:7]
	ds_read_b128 v[182:185], v140 offset:49152
	ds_read_b128 v[186:189], v140 offset:50176
	ds_read_b128 v[190:193], v140 offset:51200
	ds_read_b128 v[194:197], v140 offset:52224
	ds_read_b128 v[198:201], v140 offset:53248
	ds_read_b128 v[202:205], v140 offset:54272
	ds_read_b128 v[206:209], v140 offset:55296
	ds_read_b128 v[210:213], v140 offset:56320
	global_load_lds_dwordx4 v[164:165], off
	v_lshl_add_u64 v[164:165], v[214:215], 0, s[6:7]
	s_mov_b32 m0, s54
	s_nop 0
	global_load_lds_dwordx4 v[164:165], off
	v_lshl_add_u64 v[164:165], s[22:23], 0, v[130:131]
	s_mov_b32 m0, s55
	s_nop 0
	global_load_lds_dwordx4 v[164:165], off
	v_lshl_add_u64 v[164:165], s[22:23], 0, v[134:135]
	s_mov_b32 m0, s56
	s_nop 0
	global_load_lds_dwordx4 v[164:165], off
	v_lshl_add_u64 v[164:165], v[216:217], 0, s[6:7]
	s_mov_b32 m0, s33
	s_nop 0
	global_load_lds_dwordx4 v[164:165], off
	v_lshl_add_u64 v[164:165], v[218:219], 0, s[6:7]
	s_mov_b32 m0, s34
	s_nop 0
	global_load_lds_dwordx4 v[164:165], off
	s_waitcnt vmcnt(8)
	s_waitcnt lgkmcnt(0)
	s_barrier
	s_setprio 1
	s_waitcnt lgkmcnt(0)
	v_mfma_f32_16x16x32_bf16 v[60:63], v[144:147], v[182:185], v[60:63]
	v_mfma_f32_16x16x32_bf16 v[60:63], v[148:151], v[186:189], v[60:63]
	v_mfma_f32_16x16x32_bf16 v[56:59], v[156:159], v[186:189], v[56:59]
	v_mfma_f32_16x16x32_bf16 v[56:59], v[152:155], v[182:185], v[56:59]
	v_mfma_f32_16x16x32_bf16 v[40:43], v[152:155], v[190:193], v[40:43]
	v_mfma_f32_16x16x32_bf16 v[40:43], v[156:159], v[194:197], v[40:43]
	v_mfma_f32_16x16x32_bf16 v[48:51], v[148:151], v[194:197], v[48:51]
	v_mfma_f32_16x16x32_bf16 v[48:51], v[144:147], v[190:193], v[48:51]
	v_mfma_f32_16x16x32_bf16 v[32:35], v[144:147], v[198:201], v[32:35]
	v_mfma_f32_16x16x32_bf16 v[32:35], v[148:151], v[202:205], v[32:35]
	v_mfma_f32_16x16x32_bf16 v[24:27], v[156:159], v[202:205], v[24:27]
	v_mfma_f32_16x16x32_bf16 v[24:27], v[152:155], v[198:201], v[24:27]
	v_mfma_f32_16x16x32_bf16 v[8:11], v[152:155], v[206:209], v[8:11]
	v_mfma_f32_16x16x32_bf16 v[8:11], v[156:159], v[210:213], v[8:11]
	v_mfma_f32_16x16x32_bf16 v[16:19], v[148:151], v[210:213], v[16:19]
	v_mfma_f32_16x16x32_bf16 v[16:19], v[144:147], v[206:209], v[16:19]
	s_setprio 0
	s_setprio 1
	v_mfma_f32_16x16x32_bf16 v[52:55], v[160:163], v[182:185], v[52:55]
	v_mfma_f32_16x16x32_bf16 v[52:55], v[170:173], v[186:189], v[52:55]
	v_mfma_f32_16x16x32_bf16 v[44:47], v[178:181], v[186:189], v[44:47]
	v_mfma_f32_16x16x32_bf16 v[44:47], v[174:177], v[182:185], v[44:47]
	v_mfma_f32_16x16x32_bf16 v[28:31], v[174:177], v[190:193], v[28:31]
	v_mfma_f32_16x16x32_bf16 v[28:31], v[178:181], v[194:197], v[28:31]
	v_mfma_f32_16x16x32_bf16 v[36:39], v[170:173], v[194:197], v[36:39]
	v_mfma_f32_16x16x32_bf16 v[36:39], v[160:163], v[190:193], v[36:39]
	v_mfma_f32_16x16x32_bf16 v[20:23], v[160:163], v[198:201], v[20:23]
	v_mfma_f32_16x16x32_bf16 v[20:23], v[170:173], v[202:205], v[20:23]
	v_mfma_f32_16x16x32_bf16 v[12:15], v[178:181], v[202:205], v[12:15]
	v_mfma_f32_16x16x32_bf16 v[12:15], v[174:177], v[198:201], v[12:15]
	v_mfma_f32_16x16x32_bf16 v[0:3], v[174:177], v[206:209], v[0:3]
	v_mfma_f32_16x16x32_bf16 v[0:3], v[178:181], v[210:213], v[0:3]
	v_mfma_f32_16x16x32_bf16 v[4:7], v[170:173], v[210:213], v[4:7]
	v_mfma_f32_16x16x32_bf16 v[4:7], v[160:163], v[206:209], v[4:7]
	s_setprio 0
	s_barrier
	s_andn2_b64 vcc, exec, s[10:11]
	s_mov_b64 s[14:15], -1
	s_mov_b64 s[10:11], 0
	s_movk_i32 s21, 0x100
	s_cbranch_vccz .LBB0_531
	s_cmpk_lt_u32 s26, 0x100
	s_cbranch_scc0 .LBB0_534
	s_barrier

; #define PG8_STAGE(bufoff, gbase, voff) do { _Pragma("unroll") for (int _i = 0; _i < 2; ++_i) \
;         __builtin_amdgcn_global_load_lds((const unsigned*)((const char*)(gbase) + (voff)[_i]), (LAS unsigned*)(lds + (bufoff) + ldsw + _i * 8192), 16, 0, 0); } while (0)
; #define PG8_LDA(dst, b, h) do { _Pragma("unroll") for (int m = 0; m < 4; ++m) _Pragma("unroll") for (int k = 0; k < 2; ++k) dst[m][k] = *(const LAS bf16x8*)(lds + PG8_SA(b, h) + aoff + m * 2048 + k * 1024); } while (0)
; #define PG8_LDB(dst, b, h) do { _Pragma("unroll") for (int n = 0; n < 2; ++n) _Pragma("unroll") for (int k = 0; k < 2; ++k) dst[n][k] = *(const LAS bf16x8*)(lds + PG8_SB(b, h) + boff + n * 2048 + k * 1024); } while (0)
; #define PG8_MMA(ai, bj, At, Bt) do { __builtin_amdgcn_s_setprio(1); _Pragma("unroll") for (int m = 0; m < 4; ++m) _Pragma("unroll") for (int n = 0; n < 2; ++n) _Pragma("unroll") for (int k = 0; k < 2; ++k) \
;         acc[ai][bj][m][n] = __builtin_amdgcn_mfma_f32_16x16x32_bf16(Bt[n][k], At[m][k], acc[ai][bj][m][n], 0, 0, 0); __builtin_amdgcn_s_setprio(0); } while (0)
; #define PG8_WAIT_V(n) asm volatile("s_waitcnt vmcnt(" #n ")" ::: "memory")
; #define PG8_WAIT_L(n) asm volatile("s_waitcnt lgkmcnt(" #n ")" ::: "memory")
; #define PG8_BAR __builtin_amdgcn_s_barrier()
; #define PG8_SCHED __builtin_amdgcn_sched_barrier(0)
; DI void gemm_phase(LAS unsigned char* lds, const Gemm g, const StaticOrder& S, const Epi& E) {
;     ...
;             const bool last = (t == nt - 2);
;             const char* a1 = cA + (size_t)(t + 1) * kstep;
;             const char* a2 = last ? nA : cA + (size_t)(t + 2) * kstep; const char* b2 = last ? nB : cB + (size_t)(t + 2) * kstep;
;             const char* a3 = a2 + kstep; const char* b3 = b2 + kstep;
;             PG8_LDB(B0, 0, 0); PG8_LDB(B1, 0, 1); PG8_SCHED; PG8_LDA(At, 0, 0); PG8_STAGE(PG8_SA(1, 1), a1 + hsA, voffA);
;             PG8_WAIT_V(8); PG8_WAIT_L(0); PG8_BAR; PG8_MMA(0, 0, At, B0); PG8_MMA(0, 1, At, B1); PG8_BAR; PG8_SCHED;
;             PG8_LDA(At, 0, 1); PG8_STAGE(PG8_SB(0, 0), b2, voffB); PG8_STAGE(PG8_SB(0, 1), b2 + hsB, voffB); PG8_STAGE(PG8_SA(0, 0), a2, voffA);
;             PG8_WAIT_V(8); PG8_WAIT_L(0); PG8_BAR; PG8_MMA(1, 0, At, B0); PG8_MMA(1, 1, At, B1); PG8_BAR; PG8_SCHED;
.LBB0_571:
	ds_read_b128 v[156:159], v152
	ds_read_b128 v[160:163], v152 offset:1024
	ds_read_b128 v[170:173], v152 offset:2048
	ds_read_b128 v[174:177], v152 offset:3072
	ds_read_b128 v[178:181], v153
	ds_read_b128 v[182:185], v153 offset:1024
	ds_read_b128 v[186:189], v153 offset:2048
	ds_read_b128 v[190:193], v153 offset:3072
	s_add_u32 s56, s54, 0x100
	s_addc_u32 s57, s55, 0
	s_add_u32 s27, s78, s54
	s_addc_u32 s46, s79, s55
	s_cmp_eq_u32 s80, 28
	s_cselect_b32 s69, s76, s46
	s_cselect_b32 s46, 0, s56
	s_cselect_b32 s68, s77, s27
	s_cselect_b32 s27, 0, s57
	s_add_u32 s66, s6, s46
	s_addc_u32 s67, s7, s27
	s_mov_b32 m0, s74
	v_lshl_add_u64 v[164:165], v[146:147], 0, s[54:55]
	ds_read_b128 v[194:197], v154
	ds_read_b128 v[198:201], v154 offset:1024
	ds_read_b128 v[202:205], v154 offset:2048
	ds_read_b128 v[206:209], v154 offset:3072
	ds_read_b128 v[210:213], v154 offset:4096
	ds_read_b128 v[214:217], v154 offset:5120
	ds_read_b128 v[218:221], v154 offset:6144
	ds_read_b128 v[222:225], v154 offset:7168
	global_load_lds_dwordx4 v[164:165], off
	v_lshl_add_u64 v[164:165], v[148:149], 0, s[54:55]
	s_mov_b32 m0, s75
	s_nop 0
	global_load_lds_dwordx4 v[164:165], off
	s_waitcnt vmcnt(8)
	s_waitcnt lgkmcnt(0)
	s_barrier
	s_setprio 1
	s_waitcnt lgkmcnt(0)
	v_mfma_f32_16x16x32_bf16 v[124:127], v[156:159], v[194:197], v[124:127]
	v_mfma_f32_16x16x32_bf16 v[124:127], v[160:163], v[198:201], v[124:127]
	v_mfma_f32_16x16x32_bf16 v[120:123], v[174:177], v[198:201], v[120:123]
	v_mfma_f32_16x16x32_bf16 v[120:123], v[170:173], v[194:197], v[120:123]
	v_mfma_f32_16x16x32_bf16 v[104:107], v[170:173], v[202:205], v[104:107]
	v_mfma_f32_16x16x32_bf16 v[104:107], v[174:177], v[206:209], v[104:107]
	v_mfma_f32_16x16x32_bf16 v[108:111], v[160:163], v[206:209], v[108:111]
	v_mfma_f32_16x16x32_bf16 v[108:111], v[156:159], v[202:205], v[108:111]
	v_mfma_f32_16x16x32_bf16 v[92:95], v[156:159], v[210:213], v[92:95]
	v_mfma_f32_16x16x32_bf16 v[92:95], v[160:163], v[214:217], v[92:95]
	v_mfma_f32_16x16x32_bf16 v[88:91], v[174:177], v[214:217], v[88:91]
	v_mfma_f32_16x16x32_bf16 v[88:91], v[170:173], v[210:213], v[88:91]
	v_mfma_f32_16x16x32_bf16 v[72:75], v[170:173], v[218:221], v[72:75]
	v_mfma_f32_16x16x32_bf16 v[72:75], v[174:177], v[222:225], v[72:75]
	v_mfma_f32_16x16x32_bf16 v[76:79], v[160:163], v[222:225], v[76:79]
	v_mfma_f32_16x16x32_bf16 v[76:79], v[156:159], v[218:221], v[76:79]
	s_setprio 0
	s_setprio 1
	v_mfma_f32_16x16x32_bf16 v[116:119], v[178:181], v[194:197], v[116:119]
	v_mfma_f32_16x16x32_bf16 v[116:119], v[182:185], v[198:201], v[116:119]
	v_mfma_f32_16x16x32_bf16 v[112:115], v[190:193], v[198:201], v[112:115]
	v_mfma_f32_16x16x32_bf16 v[112:115], v[186:189], v[194:197], v[112:115]
	v_mfma_f32_16x16x32_bf16 v[96:99], v[186:189], v[202:205], v[96:99]
	v_mfma_f32_16x16x32_bf16 v[96:99], v[190:193], v[206:209], v[96:99]
	v_mfma_f32_16x16x32_bf16 v[100:103], v[182:185], v[206:209], v[100:103]
	v_mfma_f32_16x16x32_bf16 v[100:103], v[178:181], v[202:205], v[100:103]
	v_mfma_f32_16x16x32_bf16 v[84:87], v[178:181], v[210:213], v[84:87]
	v_mfma_f32_16x16x32_bf16 v[84:87], v[182:185], v[214:217], v[84:87]
	v_mfma_f32_16x16x32_bf16 v[80:83], v[190:193], v[214:217], v[80:83]
	v_mfma_f32_16x16x32_bf16 v[80:83], v[186:189], v[210:213], v[80:83]
	v_mfma_f32_16x16x32_bf16 v[64:67], v[186:189], v[218:221], v[64:67]
	v_mfma_f32_16x16x32_bf16 v[64:67], v[190:193], v[222:225], v[64:67]
	v_mfma_f32_16x16x32_bf16 v[68:71], v[182:185], v[222:225], v[68:71]
	v_mfma_f32_16x16x32_bf16 v[68:71], v[178:181], v[218:221], v[68:71]
	s_setprio 0
	s_barrier
	s_add_i32 s27, s13, s41
	v_lshl_add_u64 v[164:165], s[66:67], 0, v[130:131]
	s_mov_b32 m0, s27
	ds_read_b128 v[194:197], v154 offset:16384
	ds_read_b128 v[198:201], v154 offset:17408
	ds_read_b128 v[202:205], v154 offset:18432
	ds_read_b128 v[206:209], v154 offset:19456
	ds_read_b128 v[210:213], v154 offset:20480
	ds_read_b128 v[214:217], v154 offset:21504
	ds_read_b128 v[218:221], v154 offset:22528
	ds_read_b128 v[222:225], v154 offset:23552
	global_load_lds_dwordx4 v[164:165], off
	s_add_i32 m0, s27, 0x2000
	s_add_u32 s46, s66, 0x80000
	v_lshl_add_u64 v[226:227], s[66:67], 0, v[134:135]
	s_addc_u32 s47, s67, 0
	s_add_i32 s27, s73, s41
	global_load_lds_dwordx4 v[226:227], off
	v_lshl_add_u64 v[228:229], s[46:47], 0, v[130:131]
	s_mov_b32 m0, s27
	v_lshl_add_u64 v[230:231], s[68:69], 0, v[132:133]
	global_load_lds_dwordx4 v[228:229], off
	v_lshl_add_u64 v[228:229], s[46:47], 0, v[134:135]
	s_add_i32 m0, s27, 0x2000
	s_nop 0
	global_load_lds_dwordx4 v[228:229], off
	v_lshl_add_u64 v[228:229], s[68:69], 0, v[128:129]
	s_mov_b32 m0, s35
	s_nop 0
	global_load_lds_dwordx4 v[228:229], off
	s_mov_b32 m0, s42
	s_nop 0
	global_load_lds_dwordx4 v[230:231], off
	s_waitcnt vmcnt(8)
	s_waitcnt lgkmcnt(0)
	s_barrier
; #define PG8_STAGE(bufoff, gbase, voff) do { _Pragma("unroll") for (int _i = 0; _i < 2; ++_i) \
;         __builtin_amdgcn_global_load_lds((const unsigned*)((const char*)(gbase) + (voff)[_i]), (LAS unsigned*)(lds + (bufoff) + ldsw + _i * 8192), 16, 0, 0); } while (0)
; #define PG8_LDA(dst, b, h) do { _Pragma("unroll") for (int m = 0; m < 4; ++m) _Pragma("unroll") for (int k = 0; k < 2; ++k) dst[m][k] = *(const LAS bf16x8*)(lds + PG8_SA(b, h) + aoff + m * 2048 + k * 1024); } while (0)
; #define PG8_LDB(dst, b, h) do { _Pragma("unroll") for (int n = 0; n < 2; ++n) _Pragma("unroll") for (int k = 0; k < 2; ++k) dst[n][k] = *(const LAS bf16x8*)(lds + PG8_SB(b, h) + boff + n * 2048 + k * 1024); } while (0)
; #define PG8_MMA(ai, bj, At, Bt) do { __builtin_amdgcn_s_setprio(1); _Pragma("unroll") for (int m = 0; m < 4; ++m) _Pragma("unroll") for (int n = 0; n < 2; ++n) _Pragma("unroll") for (int k = 0; k < 2; ++k) \
;         acc[ai][bj][m][n] = __builtin_amdgcn_mfma_f32_16x16x32_bf16(Bt[n][k], At[m][k], acc[ai][bj][m][n], 0, 0, 0); __builtin_amdgcn_s_setprio(0); } while (0)
; #define PG8_WAIT_V(n) asm volatile("s_waitcnt vmcnt(" #n ")" ::: "memory")
; #define PG8_WAIT_L(n) asm volatile("s_waitcnt lgkmcnt(" #n ")" ::: "memory")
; #define PG8_BAR __builtin_amdgcn_s_barrier()
; #define PG8_SCHED __builtin_amdgcn_sched_barrier(0)
; DI void gemm_phase(LAS unsigned char* lds, const Gemm g, const StaticOrder& S, const Epi& E) {
;     ...
;             PG8_WAIT_V(8); PG8_WAIT_L(0); PG8_BAR; PG8_MMA(1, 0, At, B0); PG8_MMA(1, 1, At, B1); PG8_BAR; PG8_SCHED;
;             PG8_LDB(B0, 1, 0); PG8_LDB(B1, 1, 1); PG8_SCHED; PG8_LDA(At, 1, 0); PG8_STAGE(PG8_SA(0, 1), a2 + hsA, voffA);
;             PG8_WAIT_V(8); PG8_WAIT_L(0); PG8_BAR; PG8_MMA(0, 0, At, B0); PG8_MMA(0, 1, At, B1); PG8_BAR; PG8_SCHED;
	s_setprio 1
	s_waitcnt lgkmcnt(0)
	v_mfma_f32_16x16x32_bf16 v[60:63], v[156:159], v[194:197], v[60:63]
	v_mfma_f32_16x16x32_bf16 v[60:63], v[160:163], v[198:201], v[60:63]
	v_mfma_f32_16x16x32_bf16 v[56:59], v[174:177], v[198:201], v[56:59]
	v_mfma_f32_16x16x32_bf16 v[56:59], v[170:173], v[194:197], v[56:59]
	v_mfma_f32_16x16x32_bf16 v[40:43], v[170:173], v[202:205], v[40:43]
	v_mfma_f32_16x16x32_bf16 v[40:43], v[174:177], v[206:209], v[40:43]
	v_mfma_f32_16x16x32_bf16 v[44:47], v[160:163], v[206:209], v[44:47]
	v_mfma_f32_16x16x32_bf16 v[44:47], v[156:159], v[202:205], v[44:47]
	v_mfma_f32_16x16x32_bf16 v[28:31], v[156:159], v[210:213], v[28:31]
	v_mfma_f32_16x16x32_bf16 v[28:31], v[160:163], v[214:217], v[28:31]
	v_mfma_f32_16x16x32_bf16 v[24:27], v[174:177], v[214:217], v[24:27]
	v_mfma_f32_16x16x32_bf16 v[24:27], v[170:173], v[210:213], v[24:27]
	v_mfma_f32_16x16x32_bf16 v[8:11], v[170:173], v[218:221], v[8:11]
	v_mfma_f32_16x16x32_bf16 v[8:11], v[174:177], v[222:225], v[8:11]
	v_mfma_f32_16x16x32_bf16 v[12:15], v[160:163], v[222:225], v[12:15]
	v_mfma_f32_16x16x32_bf16 v[12:15], v[156:159], v[218:221], v[12:15]
	s_setprio 0
	s_setprio 1
	v_mfma_f32_16x16x32_bf16 v[52:55], v[178:181], v[194:197], v[52:55]
	v_mfma_f32_16x16x32_bf16 v[52:55], v[182:185], v[198:201], v[52:55]
	v_mfma_f32_16x16x32_bf16 v[48:51], v[190:193], v[198:201], v[48:51]
	v_mfma_f32_16x16x32_bf16 v[48:51], v[186:189], v[194:197], v[48:51]
	v_mfma_f32_16x16x32_bf16 v[32:35], v[186:189], v[202:205], v[32:35]
	v_mfma_f32_16x16x32_bf16 v[32:35], v[190:193], v[206:209], v[32:35]
	v_mfma_f32_16x16x32_bf16 v[36:39], v[182:185], v[206:209], v[36:39]
	v_mfma_f32_16x16x32_bf16 v[36:39], v[178:181], v[202:205], v[36:39]
	v_mfma_f32_16x16x32_bf16 v[20:23], v[178:181], v[210:213], v[20:23]
	v_mfma_f32_16x16x32_bf16 v[20:23], v[182:185], v[214:217], v[20:23]
	v_mfma_f32_16x16x32_bf16 v[16:19], v[190:193], v[214:217], v[16:19]
	v_mfma_f32_16x16x32_bf16 v[16:19], v[186:189], v[210:213], v[16:19]
	v_mfma_f32_16x16x32_bf16 v[0:3], v[186:189], v[218:221], v[0:3]
	v_mfma_f32_16x16x32_bf16 v[0:3], v[190:193], v[222:225], v[0:3]
	v_mfma_f32_16x16x32_bf16 v[4:7], v[182:185], v[222:225], v[4:7]
	v_mfma_f32_16x16x32_bf16 v[4:7], v[178:181], v[218:221], v[4:7]
	s_setprio 0
	s_barrier
	s_add_i32 s27, 0, 0x18000
	v_add_u32_e32 v155, s27, v151
	s_add_i32 s54, 0, 0x1c000
	ds_read_b128 v[156:159], v155
	ds_read_b128 v[160:163], v155 offset:1024
	ds_read_b128 v[170:173], v155 offset:2048
	ds_read_b128 v[174:177], v155 offset:3072
	v_add_u32_e32 v155, s54, v151
	ds_read_b128 v[178:181], v155
	ds_read_b128 v[182:185], v155 offset:1024
	ds_read_b128 v[186:189], v155 offset:2048
	ds_read_b128 v[190:193], v155 offset:3072
	s_add_u32 s46, s68, 0x40000
	s_addc_u32 s47, s69, 0
	s_mov_b32 m0, s43
	v_lshl_add_u64 v[232:233], s[46:47], 0, v[128:129]
	ds_read_b128 v[194:197], v154 offset:32768
	ds_read_b128 v[198:201], v154 offset:33792
	ds_read_b128 v[202:205], v154 offset:34816
	ds_read_b128 v[206:209], v154 offset:35840
	ds_read_b128 v[210:213], v154 offset:36864
	ds_read_b128 v[214:217], v154 offset:37888
	ds_read_b128 v[218:221], v154 offset:38912
	ds_read_b128 v[222:225], v154 offset:39936
	global_load_lds_dwordx4 v[232:233], off
	v_lshl_add_u64 v[232:233], s[46:47], 0, v[132:133]
	s_mov_b32 m0, s48
	s_nop 0
	global_load_lds_dwordx4 v[232:233], off
	s_waitcnt vmcnt(8)
	s_waitcnt lgkmcnt(0)
	s_barrier
	s_setprio 1
	s_waitcnt lgkmcnt(0)
	v_mfma_f32_16x16x32_bf16 v[124:127], v[156:159], v[194:197], v[124:127]
	v_mfma_f32_16x16x32_bf16 v[124:127], v[160:163], v[198:201], v[124:127]
	v_mfma_f32_16x16x32_bf16 v[120:123], v[174:177], v[198:201], v[120:123]
	v_mfma_f32_16x16x32_bf16 v[120:123], v[170:173], v[194:197], v[120:123]
	v_mfma_f32_16x16x32_bf16 v[104:107], v[170:173], v[202:205], v[104:107]
	v_mfma_f32_16x16x32_bf16 v[104:107], v[174:177], v[206:209], v[104:107]
	v_mfma_f32_16x16x32_bf16 v[108:111], v[160:163], v[206:209], v[108:111]
	v_mfma_f32_16x16x32_bf16 v[108:111], v[156:159], v[202:205], v[108:111]
	v_mfma_f32_16x16x32_bf16 v[92:95], v[156:159], v[210:213], v[92:95]
	v_mfma_f32_16x16x32_bf16 v[92:95], v[160:163], v[214:217], v[92:95]
	v_mfma_f32_16x16x32_bf16 v[88:91], v[174:177], v[214:217], v[88:91]
	v_mfma_f32_16x16x32_bf16 v[88:91], v[170:173], v[210:213], v[88:91]
	v_mfma_f32_16x16x32_bf16 v[72:75], v[170:173], v[218:221], v[72:75]
	v_mfma_f32_16x16x32_bf16 v[72:75], v[174:177], v[222:225], v[72:75]
	v_mfma_f32_16x16x32_bf16 v[76:79], v[160:163], v[222:225], v[76:79]
	v_mfma_f32_16x16x32_bf16 v[76:79], v[156:159], v[218:221], v[76:79]
	s_setprio 0
	s_setprio 1
	v_mfma_f32_16x16x32_bf16 v[116:119], v[178:181], v[194:197], v[116:119]
	v_mfma_f32_16x16x32_bf16 v[116:119], v[182:185], v[198:201], v[116:119]
	v_mfma_f32_16x16x32_bf16 v[112:115], v[190:193], v[198:201], v[112:115]
	v_mfma_f32_16x16x32_bf16 v[112:115], v[186:189], v[194:197], v[112:115]
	v_mfma_f32_16x16x32_bf16 v[96:99], v[186:189], v[202:205], v[96:99]
	v_mfma_f32_16x16x32_bf16 v[96:99], v[190:193], v[206:209], v[96:99]
	v_mfma_f32_16x16x32_bf16 v[100:103], v[182:185], v[206:209], v[100:103]
	v_mfma_f32_16x16x32_bf16 v[100:103], v[178:181], v[202:205], v[100:103]
	v_mfma_f32_16x16x32_bf16 v[84:87], v[178:181], v[210:213], v[84:87]
	v_mfma_f32_16x16x32_bf16 v[84:87], v[182:185], v[214:217], v[84:87]
	v_mfma_f32_16x16x32_bf16 v[80:83], v[190:193], v[214:217], v[80:83]
	v_mfma_f32_16x16x32_bf16 v[80:83], v[186:189], v[210:213], v[80:83]
	v_mfma_f32_16x16x32_bf16 v[64:67], v[186:189], v[218:221], v[64:67]
	v_mfma_f32_16x16x32_bf16 v[64:67], v[190:193], v[222:225], v[64:67]
	v_mfma_f32_16x16x32_bf16 v[68:71], v[182:185], v[222:225], v[68:71]
	v_mfma_f32_16x16x32_bf16 v[68:71], v[178:181], v[218:221], v[68:71]
	s_setprio 0
	s_barrier
; #define PG8_STAGE(bufoff, gbase, voff) do { _Pragma("unroll") for (int _i = 0; _i < 2; ++_i) \
;         __builtin_amdgcn_global_load_lds((const unsigned*)((const char*)(gbase) + (voff)[_i]), (LAS unsigned*)(lds + (bufoff) + ldsw + _i * 8192), 16, 0, 0); } while (0)
; #define PG8_LDA(dst, b, h) do { _Pragma("unroll") for (int m = 0; m < 4; ++m) _Pragma("unroll") for (int k = 0; k < 2; ++k) dst[m][k] = *(const LAS bf16x8*)(lds + PG8_SA(b, h) + aoff + m * 2048 + k * 1024); } while (0)
; #define PG8_MMA(ai, bj, At, Bt) do { __builtin_amdgcn_s_setprio(1); _Pragma("unroll") for (int m = 0; m < 4; ++m) _Pragma("unroll") for (int n = 0; n < 2; ++n) _Pragma("unroll") for (int k = 0; k < 2; ++k) \
;         acc[ai][bj][m][n] = __builtin_amdgcn_mfma_f32_16x16x32_bf16(Bt[n][k], At[m][k], acc[ai][bj][m][n], 0, 0, 0); __builtin_amdgcn_s_setprio(0); } while (0)
; #define PG8_WAIT_V(n) asm volatile("s_waitcnt vmcnt(" #n ")" ::: "memory")
; #define PG8_WAIT_L(n) asm volatile("s_waitcnt lgkmcnt(" #n ")" ::: "memory")
; #define PG8_BAR __builtin_amdgcn_s_barrier()
; #define PG8_SCHED __builtin_amdgcn_sched_barrier(0)
; DI void gemm_phase(LAS unsigned char* lds, const Gemm g, const StaticOrder& S, const Epi& E) {
;     ...
;             PG8_LDA(At, 1, 1); PG8_STAGE(PG8_SB(1, 0), b3, voffB); PG8_STAGE(PG8_SB(1, 1), b3 + hsB, voffB); PG8_STAGE(PG8_SA(1, 0), a3, voffA);
;             PG8_WAIT_V(8); PG8_WAIT_L(0); PG8_BAR; PG8_MMA(1, 0, At, B0); PG8_MMA(1, 1, At, B1); PG8_BAR; PG8_SCHED;
;         }
	s_add_i32 s46, s27, s41
	v_lshl_add_u64 v[164:165], v[164:165], 0, s[16:17]
	s_mov_b32 m0, s46
	ds_read_b128 v[194:197], v154 offset:49152
	ds_read_b128 v[198:201], v154 offset:50176
	ds_read_b128 v[202:205], v154 offset:51200
	ds_read_b128 v[206:209], v154 offset:52224
	ds_read_b128 v[210:213], v154 offset:53248
	ds_read_b128 v[214:217], v154 offset:54272
	ds_read_b128 v[218:221], v154 offset:55296
	ds_read_b128 v[222:225], v154 offset:56320
	global_load_lds_dwordx4 v[164:165], off
	s_add_i32 m0, s46, 0x2000
	s_add_u32 s46, s66, 0x80080
	v_lshl_add_u64 v[164:165], v[226:227], 0, s[16:17]
	s_addc_u32 s47, s67, 0
	s_add_i32 s54, s54, s41
	global_load_lds_dwordx4 v[164:165], off
	v_lshl_add_u64 v[164:165], s[46:47], 0, v[130:131]
	s_mov_b32 m0, s54
	s_nop 0
	global_load_lds_dwordx4 v[164:165], off
	v_lshl_add_u64 v[164:165], s[46:47], 0, v[134:135]
	s_add_i32 m0, s54, 0x2000
	s_nop 0
	global_load_lds_dwordx4 v[164:165], off
	v_lshl_add_u64 v[164:165], v[228:229], 0, s[16:17]
	s_mov_b32 m0, s71
	s_nop 0
	global_load_lds_dwordx4 v[164:165], off
	v_lshl_add_u64 v[164:165], v[230:231], 0, s[16:17]
	s_mov_b32 m0, s72
	s_nop 0
	global_load_lds_dwordx4 v[164:165], off
	s_waitcnt vmcnt(8)
	s_waitcnt lgkmcnt(0)
	s_barrier
	s_setprio 1
	s_waitcnt lgkmcnt(0)
	v_mfma_f32_16x16x32_bf16 v[60:63], v[156:159], v[194:197], v[60:63]
	v_mfma_f32_16x16x32_bf16 v[60:63], v[160:163], v[198:201], v[60:63]
	v_mfma_f32_16x16x32_bf16 v[56:59], v[174:177], v[198:201], v[56:59]
	v_mfma_f32_16x16x32_bf16 v[56:59], v[170:173], v[194:197], v[56:59]
	v_mfma_f32_16x16x32_bf16 v[40:43], v[170:173], v[202:205], v[40:43]
	v_mfma_f32_16x16x32_bf16 v[40:43], v[174:177], v[206:209], v[40:43]
	v_mfma_f32_16x16x32_bf16 v[44:47], v[160:163], v[206:209], v[44:47]
	v_mfma_f32_16x16x32_bf16 v[44:47], v[156:159], v[202:205], v[44:47]
	v_mfma_f32_16x16x32_bf16 v[28:31], v[156:159], v[210:213], v[28:31]
	v_mfma_f32_16x16x32_bf16 v[28:31], v[160:163], v[214:217], v[28:31]
	v_mfma_f32_16x16x32_bf16 v[24:27], v[174:177], v[214:217], v[24:27]
	v_mfma_f32_16x16x32_bf16 v[24:27], v[170:173], v[210:213], v[24:27]
	v_mfma_f32_16x16x32_bf16 v[8:11], v[170:173], v[218:221], v[8:11]
	v_mfma_f32_16x16x32_bf16 v[8:11], v[174:177], v[222:225], v[8:11]
	v_mfma_f32_16x16x32_bf16 v[12:15], v[160:163], v[222:225], v[12:15]
	v_mfma_f32_16x16x32_bf16 v[12:15], v[156:159], v[218:221], v[12:15]
	s_setprio 0
	s_setprio 1
	v_mfma_f32_16x16x32_bf16 v[52:55], v[178:181], v[194:197], v[52:55]
	v_mfma_f32_16x16x32_bf16 v[52:55], v[182:185], v[198:201], v[52:55]
	v_mfma_f32_16x16x32_bf16 v[48:51], v[190:193], v[198:201], v[48:51]
	v_mfma_f32_16x16x32_bf16 v[48:51], v[186:189], v[194:197], v[48:51]
	v_mfma_f32_16x16x32_bf16 v[32:35], v[186:189], v[202:205], v[32:35]
	v_mfma_f32_16x16x32_bf16 v[32:35], v[190:193], v[206:209], v[32:35]
	v_mfma_f32_16x16x32_bf16 v[36:39], v[182:185], v[206:209], v[36:39]
	v_mfma_f32_16x16x32_bf16 v[36:39], v[178:181], v[202:205], v[36:39]
	v_mfma_f32_16x16x32_bf16 v[20:23], v[178:181], v[210:213], v[20:23]
	v_mfma_f32_16x16x32_bf16 v[20:23], v[182:185], v[214:217], v[20:23]
	v_mfma_f32_16x16x32_bf16 v[16:19], v[190:193], v[214:217], v[16:19]
	v_mfma_f32_16x16x32_bf16 v[16:19], v[186:189], v[210:213], v[16:19]
	v_mfma_f32_16x16x32_bf16 v[0:3], v[186:189], v[218:221], v[0:3]
	v_mfma_f32_16x16x32_bf16 v[0:3], v[190:193], v[222:225], v[0:3]
	v_mfma_f32_16x16x32_bf16 v[4:7], v[182:185], v[222:225], v[4:7]
	v_mfma_f32_16x16x32_bf16 v[4:7], v[178:181], v[218:221], v[4:7]
	s_setprio 0
	s_barrier
	s_add_i32 s80, s80, 2
	s_cmp_gt_u32 s80, 29
	s_mov_b64 s[54:55], s[56:57]
	s_cbranch_scc0 .LBB0_571
	s_and_b64 vcc, exec, s[18:19]
	s_cbranch_vccz .LBB0_574
	s_barrier

; #define PG8_STAGE(bufoff, gbase, voff) do { _Pragma("unroll") for (int _i = 0; _i < 2; ++_i) \
;         __builtin_amdgcn_global_load_lds((const unsigned*)((const char*)(gbase) + (voff)[_i]), (LAS unsigned*)(lds + (bufoff) + ldsw + _i * 8192), 16, 0, 0); } while (0)
; #define PG8_LDA(dst, b, h) do { _Pragma("unroll") for (int m = 0; m < 4; ++m) _Pragma("unroll") for (int k = 0; k < 2; ++k) dst[m][k] = *(const LAS bf16x8*)(lds + PG8_SA(b, h) + aoff + m * 2048 + k * 1024); } while (0)
; #define PG8_LDB(dst, b, h) do { _Pragma("unroll") for (int n = 0; n < 2; ++n) _Pragma("unroll") for (int k = 0; k < 2; ++k) dst[n][k] = *(const LAS bf16x8*)(lds + PG8_SB(b, h) + boff + n * 2048 + k * 1024); } while (0)
; #define PG8_MMA(ai, bj, At, Bt) do { __builtin_amdgcn_s_setprio(1); _Pragma("unroll") for (int m = 0; m < 4; ++m) _Pragma("unroll") for (int n = 0; n < 2; ++n) _Pragma("unroll") for (int k = 0; k < 2; ++k) \
;         acc[ai][bj][m][n] = __builtin_amdgcn_mfma_f32_16x16x32_bf16(Bt[n][k], At[m][k], acc[ai][bj][m][n], 0, 0, 0); __builtin_amdgcn_s_setprio(0); } while (0)
; #define PG8_WAIT_V(n) asm volatile("s_waitcnt vmcnt(" #n ")" ::: "memory")
; #define PG8_WAIT_L(n) asm volatile("s_waitcnt lgkmcnt(" #n ")" ::: "memory")
; #define PG8_BAR __builtin_amdgcn_s_barrier()
; #define PG8_SCHED __builtin_amdgcn_sched_barrier(0)
; DI void gemm_phase(LAS unsigned char* lds, const Gemm g, const StaticOrder& S, const Epi& E) {
;     ...
;             PG8_LDB(B0, 0, 0); PG8_LDB(B1, 0, 1); PG8_SCHED; PG8_LDA(At, 0, 0); PG8_STAGE(PG8_SA(1, 1), a1 + hsA, voffA);
;             PG8_WAIT_V(8); PG8_WAIT_L(0); PG8_BAR; PG8_MMA(0, 0, At, B0); PG8_MMA(0, 1, At, B1); PG8_BAR; PG8_SCHED;
;             PG8_LDA(At, 0, 1); PG8_STAGE(PG8_SB(0, 0), b2, voffB); PG8_STAGE(PG8_SB(0, 1), b2 + hsB, voffB); PG8_STAGE(PG8_SA(0, 0), a2, voffA);
;             PG8_WAIT_V(8); PG8_WAIT_L(0); PG8_BAR; PG8_MMA(1, 0, At, B0); PG8_MMA(1, 1, At, B1); PG8_BAR; PG8_SCHED;
.LBB0_593:
	s_add_i32 s46, s34, 0x100
	s_add_u32 s47, s20, s34
	s_addc_u32 s54, s21, 0
	s_add_u32 s34, s47, 0x100
	s_addc_u32 s35, s54, 0
	s_and_b64 s[30:31], s[30:31], exec
	s_cselect_b32 s31, 0, s46
	s_cselect_b32 s35, s19, s35
	s_cselect_b32 s34, s23, s34
	s_cselect_b32 s30, 0, 0
	s_add_u32 s56, s4, s31
	s_addc_u32 s57, s5, s30
	s_add_u32 s68, s47, 0x10080
	ds_read_b128 v[78:81], v75
	ds_read_b128 v[82:85], v75 offset:1024
	ds_read_b128 v[86:89], v75 offset:2048
	ds_read_b128 v[90:93], v75 offset:3072
	s_addc_u32 s69, s54, 0
	s_add_u32 s66, s56, 0x10000
	s_addc_u32 s67, s57, 0
	s_add_u32 s30, s34, 0x10000
	s_addc_u32 s31, s35, 0
	s_add_u32 s54, s56, 0x10080
	s_addc_u32 s55, s57, 0
	s_mov_b32 m0, s70
	v_lshl_add_u64 v[126:127], s[68:69], 0, v[64:65]
	ds_read_b128 v[94:97], v76
	ds_read_b128 v[98:101], v76 offset:1024
	ds_read_b128 v[102:105], v76 offset:2048
	ds_read_b128 v[106:109], v76 offset:3072
	ds_read_b128 v[110:113], v76 offset:4096
	ds_read_b128 v[114:117], v76 offset:5120
	ds_read_b128 v[118:121], v76 offset:6144
	ds_read_b128 v[122:125], v76 offset:7168
	global_load_lds_dwordx4 v[126:127], off
	v_lshl_add_u64 v[126:127], s[68:69], 0, v[68:69]
	s_mov_b32 m0, s71
	s_nop 0
	global_load_lds_dwordx4 v[126:127], off
	s_waitcnt vmcnt(8)
	s_waitcnt lgkmcnt(0)
	s_barrier
	s_setprio 1
	s_waitcnt lgkmcnt(0)
	v_mfma_f32_16x16x32_bf16 v[60:63], v[78:81], v[94:97], v[60:63]
	v_mfma_f32_16x16x32_bf16 v[60:63], v[82:85], v[98:101], v[60:63]
	v_mfma_f32_16x16x32_bf16 v[56:59], v[90:93], v[98:101], v[56:59]
	v_mfma_f32_16x16x32_bf16 v[56:59], v[86:89], v[94:97], v[56:59]
	v_mfma_f32_16x16x32_bf16 v[48:51], v[86:89], v[102:105], v[48:51]
	v_mfma_f32_16x16x32_bf16 v[48:51], v[90:93], v[106:109], v[48:51]
	v_mfma_f32_16x16x32_bf16 v[52:55], v[82:85], v[106:109], v[52:55]
	v_mfma_f32_16x16x32_bf16 v[52:55], v[78:81], v[102:105], v[52:55]
	v_mfma_f32_16x16x32_bf16 v[44:47], v[78:81], v[110:113], v[44:47]
	v_mfma_f32_16x16x32_bf16 v[44:47], v[82:85], v[114:117], v[44:47]
	v_mfma_f32_16x16x32_bf16 v[40:43], v[90:93], v[114:117], v[40:43]
	v_mfma_f32_16x16x32_bf16 v[40:43], v[86:89], v[110:113], v[40:43]
	v_mfma_f32_16x16x32_bf16 v[32:35], v[86:89], v[118:121], v[32:35]
	v_mfma_f32_16x16x32_bf16 v[32:35], v[90:93], v[122:125], v[32:35]
	v_mfma_f32_16x16x32_bf16 v[36:39], v[82:85], v[122:125], v[36:39]
	v_mfma_f32_16x16x32_bf16 v[36:39], v[78:81], v[118:121], v[36:39]
	s_setprio 0
	s_setprio 1
	s_setprio 0
	s_barrier
	s_mov_b32 m0, s13
	v_lshl_add_u64 v[126:127], s[56:57], 0, v[66:67]
	ds_read_b128 v[94:97], v76 offset:16384
	ds_read_b128 v[98:101], v76 offset:17408
	ds_read_b128 v[102:105], v76 offset:18432
	ds_read_b128 v[106:109], v76 offset:19456
	ds_read_b128 v[110:113], v76 offset:20480
	ds_read_b128 v[114:117], v76 offset:21504
	ds_read_b128 v[118:121], v76 offset:22528
	ds_read_b128 v[122:125], v76 offset:23552
	global_load_lds_dwordx4 v[126:127], off
	v_lshl_add_u64 v[128:129], s[56:57], 0, v[70:71]
	s_mov_b32 m0, s72
	v_lshl_add_u64 v[130:131], s[66:67], 0, v[66:67]
	global_load_lds_dwordx4 v[128:129], off
	s_mov_b32 m0, s1
	v_lshl_add_u64 v[132:133], s[34:35], 0, v[68:69]
	global_load_lds_dwordx4 v[130:131], off
	v_lshl_add_u64 v[130:131], s[66:67], 0, v[70:71]
	s_mov_b32 m0, s12
	s_nop 0
	global_load_lds_dwordx4 v[130:131], off
	v_lshl_add_u64 v[130:131], s[34:35], 0, v[64:65]
	s_mov_b32 m0, s0
	s_nop 0
	global_load_lds_dwordx4 v[130:131], off
	s_mov_b32 m0, s33
	s_nop 0
	global_load_lds_dwordx4 v[132:133], off
	s_waitcnt vmcnt(8)
	s_waitcnt lgkmcnt(0)
	s_barrier
	s_setprio 1
	s_waitcnt lgkmcnt(0)
	v_mfma_f32_16x16x32_bf16 v[28:31], v[78:81], v[94:97], v[28:31]
	v_mfma_f32_16x16x32_bf16 v[28:31], v[82:85], v[98:101], v[28:31]
	v_mfma_f32_16x16x32_bf16 v[24:27], v[90:93], v[98:101], v[24:27]
	v_mfma_f32_16x16x32_bf16 v[24:27], v[86:89], v[94:97], v[24:27]
	v_mfma_f32_16x16x32_bf16 v[16:19], v[86:89], v[102:105], v[16:19]
	v_mfma_f32_16x16x32_bf16 v[16:19], v[90:93], v[106:109], v[16:19]
	v_mfma_f32_16x16x32_bf16 v[20:23], v[82:85], v[106:109], v[20:23]
	v_mfma_f32_16x16x32_bf16 v[20:23], v[78:81], v[102:105], v[20:23]
	v_mfma_f32_16x16x32_bf16 v[12:15], v[78:81], v[110:113], v[12:15]
	v_mfma_f32_16x16x32_bf16 v[12:15], v[82:85], v[114:117], v[12:15]
	v_mfma_f32_16x16x32_bf16 v[8:11], v[90:93], v[114:117], v[8:11]
	v_mfma_f32_16x16x32_bf16 v[8:11], v[86:89], v[110:113], v[8:11]
	v_mfma_f32_16x16x32_bf16 v[0:3], v[86:89], v[118:121], v[0:3]
	v_mfma_f32_16x16x32_bf16 v[0:3], v[90:93], v[122:125], v[0:3]
	v_mfma_f32_16x16x32_bf16 v[4:7], v[82:85], v[122:125], v[4:7]
	v_mfma_f32_16x16x32_bf16 v[4:7], v[78:81], v[118:121], v[4:7]
	s_setprio 0
	s_setprio 1
	s_setprio 0
	s_barrier
; #define PG8_STAGE(bufoff, gbase, voff) do { _Pragma("unroll") for (int _i = 0; _i < 2; ++_i) \
;         __builtin_amdgcn_global_load_lds((const unsigned*)((const char*)(gbase) + (voff)[_i]), (LAS unsigned*)(lds + (bufoff) + ldsw + _i * 8192), 16, 0, 0); } while (0)
; #define PG8_LDA(dst, b, h) do { _Pragma("unroll") for (int m = 0; m < 4; ++m) _Pragma("unroll") for (int k = 0; k < 2; ++k) dst[m][k] = *(const LAS bf16x8*)(lds + PG8_SA(b, h) + aoff + m * 2048 + k * 1024); } while (0)
; #define PG8_LDB(dst, b, h) do { _Pragma("unroll") for (int n = 0; n < 2; ++n) _Pragma("unroll") for (int k = 0; k < 2; ++k) dst[n][k] = *(const LAS bf16x8*)(lds + PG8_SB(b, h) + boff + n * 2048 + k * 1024); } while (0)
; #define PG8_MMA(ai, bj, At, Bt) do { __builtin_amdgcn_s_setprio(1); _Pragma("unroll") for (int m = 0; m < 4; ++m) _Pragma("unroll") for (int n = 0; n < 2; ++n) _Pragma("unroll") for (int k = 0; k < 2; ++k) \
;         acc[ai][bj][m][n] = __builtin_amdgcn_mfma_f32_16x16x32_bf16(Bt[n][k], At[m][k], acc[ai][bj][m][n], 0, 0, 0); __builtin_amdgcn_s_setprio(0); } while (0)
; #define PG8_WAIT_V(n) asm volatile("s_waitcnt vmcnt(" #n ")" ::: "memory")
; #define PG8_WAIT_L(n) asm volatile("s_waitcnt lgkmcnt(" #n ")" ::: "memory")
; #define PG8_BAR __builtin_amdgcn_s_barrier()
; #define PG8_SCHED __builtin_amdgcn_sched_barrier(0)
; DI void gemm_phase(LAS unsigned char* lds, const Gemm g, const StaticOrder& S, const Epi& E) {
;     ...
;             PG8_LDB(B0, 1, 0); PG8_LDB(B1, 1, 1); PG8_SCHED; PG8_LDA(At, 1, 0); PG8_STAGE(PG8_SA(0, 1), a2 + hsA, voffA);
;             PG8_WAIT_V(8); PG8_WAIT_L(0); PG8_BAR; PG8_MMA(0, 0, At, B0); PG8_MMA(0, 1, At, B1); PG8_BAR; PG8_SCHED;
;             PG8_LDA(At, 1, 1); PG8_STAGE(PG8_SB(1, 0), b3, voffB); PG8_STAGE(PG8_SB(1, 1), b3 + hsB, voffB); PG8_STAGE(PG8_SA(1, 0), a3, voffA);
;             PG8_WAIT_V(8); PG8_WAIT_L(0); PG8_BAR; PG8_MMA(1, 0, At, B0); PG8_MMA(1, 1, At, B1); PG8_BAR; PG8_SCHED;
;         }
	ds_read_b128 v[78:81], v77
	ds_read_b128 v[82:85], v77 offset:1024
	ds_read_b128 v[86:89], v77 offset:2048
	ds_read_b128 v[90:93], v77 offset:3072
	s_mov_b32 m0, s40
	v_lshl_add_u64 v[134:135], s[30:31], 0, v[64:65]
	ds_read_b128 v[94:97], v76 offset:32768
	ds_read_b128 v[98:101], v76 offset:33792
	ds_read_b128 v[102:105], v76 offset:34816
	ds_read_b128 v[106:109], v76 offset:35840
	ds_read_b128 v[110:113], v76 offset:36864
	ds_read_b128 v[114:117], v76 offset:37888
	ds_read_b128 v[118:121], v76 offset:38912
	ds_read_b128 v[122:125], v76 offset:39936
	global_load_lds_dwordx4 v[134:135], off
	v_lshl_add_u64 v[134:135], s[30:31], 0, v[68:69]
	s_mov_b32 m0, s41
	s_nop 0
	global_load_lds_dwordx4 v[134:135], off
	s_waitcnt vmcnt(8)
	s_waitcnt lgkmcnt(0)
	s_barrier
	s_setprio 1
	s_waitcnt lgkmcnt(0)
	v_mfma_f32_16x16x32_bf16 v[60:63], v[78:81], v[94:97], v[60:63]
	v_mfma_f32_16x16x32_bf16 v[60:63], v[82:85], v[98:101], v[60:63]
	v_mfma_f32_16x16x32_bf16 v[56:59], v[90:93], v[98:101], v[56:59]
	v_mfma_f32_16x16x32_bf16 v[56:59], v[86:89], v[94:97], v[56:59]
	v_mfma_f32_16x16x32_bf16 v[48:51], v[86:89], v[102:105], v[48:51]
	v_mfma_f32_16x16x32_bf16 v[48:51], v[90:93], v[106:109], v[48:51]
	v_mfma_f32_16x16x32_bf16 v[52:55], v[82:85], v[106:109], v[52:55]
	v_mfma_f32_16x16x32_bf16 v[52:55], v[78:81], v[102:105], v[52:55]
	v_mfma_f32_16x16x32_bf16 v[44:47], v[78:81], v[110:113], v[44:47]
	v_mfma_f32_16x16x32_bf16 v[44:47], v[82:85], v[114:117], v[44:47]
	v_mfma_f32_16x16x32_bf16 v[40:43], v[90:93], v[114:117], v[40:43]
	v_mfma_f32_16x16x32_bf16 v[40:43], v[86:89], v[110:113], v[40:43]
	v_mfma_f32_16x16x32_bf16 v[32:35], v[86:89], v[118:121], v[32:35]
	v_mfma_f32_16x16x32_bf16 v[32:35], v[90:93], v[122:125], v[32:35]
	v_mfma_f32_16x16x32_bf16 v[36:39], v[82:85], v[122:125], v[36:39]
	v_mfma_f32_16x16x32_bf16 v[36:39], v[78:81], v[118:121], v[36:39]
	s_setprio 0
	s_setprio 1
	s_setprio 0
	s_barrier
	s_mov_b32 m0, s73
	v_lshl_add_u64 v[126:127], v[126:127], 0, s[10:11]
	ds_read_b128 v[94:97], v76 offset:49152
	ds_read_b128 v[98:101], v76 offset:50176
	ds_read_b128 v[102:105], v76 offset:51200
	ds_read_b128 v[106:109], v76 offset:52224
	ds_read_b128 v[110:113], v76 offset:53248
	ds_read_b128 v[114:117], v76 offset:54272
	ds_read_b128 v[118:121], v76 offset:55296
	ds_read_b128 v[122:125], v76 offset:56320
	global_load_lds_dwordx4 v[126:127], off
	v_lshl_add_u64 v[126:127], v[128:129], 0, s[10:11]
	s_mov_b32 m0, s74
	s_nop 0
	global_load_lds_dwordx4 v[126:127], off
	v_lshl_add_u64 v[126:127], s[54:55], 0, v[66:67]
	s_mov_b32 m0, s49
	s_nop 0
	global_load_lds_dwordx4 v[126:127], off
	v_lshl_add_u64 v[126:127], s[54:55], 0, v[70:71]
	s_mov_b32 m0, s58
	s_nop 0
	global_load_lds_dwordx4 v[126:127], off
	v_lshl_add_u64 v[126:127], v[130:131], 0, s[10:11]
	s_mov_b32 m0, s43
	s_nop 0
	global_load_lds_dwordx4 v[126:127], off
	v_lshl_add_u64 v[126:127], v[132:133], 0, s[10:11]
	s_mov_b32 m0, s48
	s_nop 0
	global_load_lds_dwordx4 v[126:127], off
	s_waitcnt vmcnt(8)
	s_waitcnt lgkmcnt(0)
	s_barrier
	s_setprio 1
	s_waitcnt lgkmcnt(0)
	v_mfma_f32_16x16x32_bf16 v[28:31], v[78:81], v[94:97], v[28:31]
	v_mfma_f32_16x16x32_bf16 v[28:31], v[82:85], v[98:101], v[28:31]
	v_mfma_f32_16x16x32_bf16 v[24:27], v[90:93], v[98:101], v[24:27]
	v_mfma_f32_16x16x32_bf16 v[24:27], v[86:89], v[94:97], v[24:27]
	v_mfma_f32_16x16x32_bf16 v[16:19], v[86:89], v[102:105], v[16:19]
	v_mfma_f32_16x16x32_bf16 v[16:19], v[90:93], v[106:109], v[16:19]
	v_mfma_f32_16x16x32_bf16 v[20:23], v[82:85], v[106:109], v[20:23]
	v_mfma_f32_16x16x32_bf16 v[20:23], v[78:81], v[102:105], v[20:23]
	v_mfma_f32_16x16x32_bf16 v[12:15], v[78:81], v[110:113], v[12:15]
	v_mfma_f32_16x16x32_bf16 v[12:15], v[82:85], v[114:117], v[12:15]
	v_mfma_f32_16x16x32_bf16 v[8:11], v[90:93], v[114:117], v[8:11]
	v_mfma_f32_16x16x32_bf16 v[8:11], v[86:89], v[110:113], v[8:11]
	v_mfma_f32_16x16x32_bf16 v[0:3], v[86:89], v[118:121], v[0:3]
	v_mfma_f32_16x16x32_bf16 v[0:3], v[90:93], v[122:125], v[0:3]
	v_mfma_f32_16x16x32_bf16 v[4:7], v[82:85], v[122:125], v[4:7]
	v_mfma_f32_16x16x32_bf16 v[4:7], v[78:81], v[118:121], v[4:7]
	s_setprio 0
	s_setprio 1
	s_setprio 0
	s_barrier
	s_andn2_b64 vcc, exec, s[28:29]
	s_mov_b64 s[30:31], -1
	s_mov_b64 s[28:29], 0
	s_movk_i32 s34, 0x100
	s_cbranch_vccz .LBB0_593
	s_and_b64 vcc, exec, s[14:15]
	s_cbranch_vccz .LBB0_597
	s_barrier
	s_andn2_b64 vcc, exec, s[16:17]
	s_cbranch_vccz .LBB0_598

; #define LAS __attribute__((address_space(3)))
; #define MFMA32(a, b, c) __builtin_amdgcn_mfma_f32_32x32x16_bf16((a), (b), (c), 0, 0, 0)
; DI void mla_unit(const Params& p, LAS unsigned char* lds, int b, int h, int qb, int tid) {
;     ...
;                     const bf16x8 a = *(LAS const bf16x8*)(buf + (32 * sub + c) * 400 + st * 32 + hi * 16);
;                     s = MFMA32(a, qf[st], s);
;                 }
;                 if (kbase + 31 > qw0) {
;                     int dbase = qpos - kbase - 4 * hi;
;                     asm volatile("" : "+v"(dbase));
; #pragma unroll
;                     for (int i = 0; i < 16; ++i) if ((dbase - ((i & 3) + 8 * (i >> 2))) < 0) s[i] = -1e30f;
;     ...
;                     LAS const unsigned char* ap = buf + 25600 + (32 * db + c) * 136 + (32 * sub + 4 * hi) * 2;
;                     const bf16x8 v0 = cat4(*(LAS const bf16x4*)(ap), *(LAS const bf16x4*)(ap + 16));
;                     const bf16x8 v1 = cat4(*(LAS const bf16x4*)(ap + 32), *(LAS const bf16x4*)(ap + 48));
.LBB0_627:
	s_bitcmp1_b32 s2, 0
	s_cselect_b32 s2, 0xa800, 0
	s_add_i32 s46, s2, 0
	v_add3_u32 v168, v148, v178, s46
	v_add3_u32 v181, v153, v177, s46
	v_add_u32_e32 v242, 0x6000, v181
	v_add_u32_e32 v243, 0x7000, v181
	v_add_u32_e32 v244, 0x8000, v181
	v_add_u32_e32 v245, 0x9000, v181
	ds_read_b128 v[182:185], v168
	ds_read_b128 v[186:189], v168 offset:32
	ds_read_b128 v[190:193], v168 offset:64
	ds_read_b128 v[194:197], v168 offset:96
	ds_read_b128 v[198:201], v168 offset:128
	ds_read_b128 v[202:205], v168 offset:160
	s_waitcnt lgkmcnt(5)
	v_mfma_f32_32x32x16_bf16 v[64:79], v[182:185], v[80:83], 0
	ds_read_b128 v[182:185], v168 offset:192
	s_waitcnt lgkmcnt(5)
	v_mfma_f32_32x32x16_bf16 v[64:79], v[186:189], v[84:87], v[64:79]
	ds_read_b128 v[186:189], v168 offset:224
	s_waitcnt lgkmcnt(5)
	v_mfma_f32_32x32x16_bf16 v[64:79], v[190:193], v[88:91], v[64:79]
	ds_read_b128 v[190:193], v168 offset:256
	s_waitcnt lgkmcnt(5)
	v_mfma_f32_32x32x16_bf16 v[64:79], v[194:197], v[92:95], v[64:79]
	ds_read_b128 v[194:197], v168 offset:288
	s_waitcnt lgkmcnt(5)
	v_mfma_f32_32x32x16_bf16 v[64:79], v[198:201], v[96:99], v[64:79]
	ds_read_b128 v[198:201], v168 offset:320
	s_waitcnt lgkmcnt(5)
	v_mfma_f32_32x32x16_bf16 v[64:79], v[202:205], v[100:103], v[64:79]
	ds_read_b128 v[202:205], v168 offset:352
	s_waitcnt lgkmcnt(5)
	v_mfma_f32_32x32x16_bf16 v[64:79], v[182:185], v[104:107], v[64:79]
	ds_read2_b64 v[206:209], v242 offset0:128 offset1:130
	s_waitcnt lgkmcnt(5)
	v_mfma_f32_32x32x16_bf16 v[64:79], v[186:189], v[108:111], v[64:79]
	ds_read2_b64 v[210:213], v242 offset0:132 offset1:134
	s_waitcnt lgkmcnt(5)
	v_mfma_f32_32x32x16_bf16 v[64:79], v[190:193], v[112:115], v[64:79]
	ds_read2_b64 v[214:217], v243 offset0:164 offset1:166
	s_waitcnt lgkmcnt(5)
	v_mfma_f32_32x32x16_bf16 v[64:79], v[194:197], v[116:119], v[64:79]
	ds_read2_b64 v[218:221], v243 offset0:160 offset1:162
	s_waitcnt lgkmcnt(5)
	v_mfma_f32_32x32x16_bf16 v[64:79], v[198:201], v[120:123], v[64:79]
	ds_read2_b64 v[222:225], v244 offset0:192 offset1:194
	s_waitcnt lgkmcnt(5)
	v_mfma_f32_32x32x16_bf16 v[64:79], v[202:205], v[124:127], v[64:79]
	ds_read2_b64 v[226:229], v244 offset0:196 offset1:198
	ds_read2_b64 v[230:233], v245 offset0:228 offset1:230
	ds_read2_b64 v[236:239], v245 offset0:224 offset1:226
	s_add_i32 s2, s80, 31
	s_cmp_le_i32 s2, s58
	s_nop 5
	s_cbranch_scc1 .Lmla_nomask_0
	v_mov_b32_e32 v240, v179
	s_nop 0
	v_cmp_gt_i32_e64 s[30:31], 26, v240
	v_cmp_gt_i32_e64 s[34:35], 27, v240
	v_cmp_gt_i32_e64 s[28:29], 25, v240
	s_and_b64 s[30:31], s[34:35], s[30:31]
	v_cmp_gt_i32_e64 s[26:27], 24, v240
	s_and_b64 s[28:29], s[30:31], s[28:29]
	v_cmp_gt_i32_e64 s[24:25], 19, v240
	s_and_b64 s[26:27], s[28:29], s[26:27]
	v_cmp_gt_i32_e64 s[22:23], 18, v240
	s_and_b64 s[24:25], s[26:27], s[24:25]
	v_cmp_gt_i32_e64 s[20:21], 17, v240
	s_and_b64 s[22:23], s[24:25], s[22:23]
	v_cmp_gt_i32_e64 s[18:19], 16, v240
	s_and_b64 s[20:21], s[22:23], s[20:21]
	v_cmp_gt_i32_e64 s[16:17], 11, v240
	s_and_b64 s[18:19], s[20:21], s[18:19]
	v_cmp_gt_i32_e64 s[14:15], 10, v240
	s_and_b64 s[16:17], s[18:19], s[16:17]
	v_cmp_gt_i32_e64 s[10:11], 9, v240
	s_and_b64 s[14:15], s[16:17], s[14:15]
	v_cmp_gt_i32_e64 s[8:9], 8, v240
	s_and_b64 s[10:11], s[14:15], s[10:11]
	v_cmp_gt_i32_e64 s[6:7], 3, v240
	s_and_b64 s[8:9], s[10:11], s[8:9]
	v_cmp_gt_i32_e64 s[4:5], 2, v240
	s_and_b64 s[6:7], s[8:9], s[6:7]
	v_cmp_gt_i32_e64 s[2:3], 1, v240
	s_and_b64 s[4:5], s[6:7], s[4:5]
	v_cmp_gt_i32_e32 vcc, 0, v240
	s_and_b64 s[2:3], s[4:5], s[2:3]
	s_and_b64 vcc, s[2:3], vcc
	s_nop 1
	v_cndmask_b32_e64 v79, v79, v170, s[34:35]
	v_cndmask_b32_e64 v78, v78, v170, s[30:31]
	v_cndmask_b32_e64 v77, v77, v170, s[28:29]
	v_cndmask_b32_e64 v76, v76, v170, s[26:27]
	v_cndmask_b32_e64 v75, v75, v170, s[24:25]
	v_cndmask_b32_e64 v74, v74, v170, s[22:23]
	v_cndmask_b32_e64 v73, v73, v170, s[20:21]
	v_cndmask_b32_e64 v72, v72, v170, s[18:19]
	v_cndmask_b32_e64 v71, v71, v170, s[16:17]
	v_cndmask_b32_e64 v70, v70, v170, s[14:15]
	v_cndmask_b32_e64 v69, v69, v170, s[10:11]
	v_cndmask_b32_e64 v68, v68, v170, s[8:9]
	v_cndmask_b32_e64 v67, v67, v170, s[6:7]
	v_cndmask_b32_e64 v66, v66, v170, s[4:5]
	v_cndmask_b32_e64 v65, v65, v170, s[2:3]
	v_cndmask_b32_e32 v64, v64, v170, vcc

; #define LAS __attribute__((address_space(3)))
; DI float fexp2(float x) { return __builtin_amdgcn_exp2f(x); }
; #define MFMA32(a, b, c) __builtin_amdgcn_mfma_f32_32x32x16_bf16((a), (b), (c), 0, 0, 0)
; DI void mla_unit(const Params& p, LAS unsigned char* lds, int b, int h, int qb, int tid) {
;     ...
;                     const bf16x8 a = *(LAS const bf16x8*)(buf + (32 * sub + c) * 400 + st * 32 + hi * 16);
;                     s = MFMA32(a, qf[st], s);
;                 }
;                 if (kbase + 31 > qw0) {
;                     int dbase = qpos - kbase - 4 * hi;
;                     asm volatile("" : "+v"(dbase));
; #pragma unroll
;                     for (int i = 0; i < 16; ++i) if ((dbase - ((i & 3) + 8 * (i >> 2))) < 0) s[i] = -1e30f;
;     ...
;                 for (int i = 0; i < 16; ++i) { const float pv = fexp2(s[i] - m); s[i] = pv; ps += pv; }
;                 l += ps;
;                 const bf16x8 pb0 = packp(s, 0), pb1 = packp(s, 1);
; #pragma unroll
;                 for (int db = 0; db < 4; ++db) {
;                     LAS const unsigned char* ap = buf + 25600 + (32 * db + c) * 136 + (32 * sub + 4 * hi) * 2;
;                     const bf16x8 v0 = cat4(*(LAS const bf16x4*)(ap), *(LAS const bf16x4*)(ap + 16));
;                     const bf16x8 v1 = cat4(*(LAS const bf16x4*)(ap + 32), *(LAS const bf16x4*)(ap + 48));
;                     o[db] = MFMA32(v0, pb0, o[db]); o[db] = MFMA32(v1, pb1, o[db]);
.Lmla_norescale_0:
	v_sub_f32_e32 v64, v64, v180
	v_sub_f32_e32 v65, v65, v180
	v_sub_f32_e32 v66, v66, v180
	v_sub_f32_e32 v67, v67, v180
	v_sub_f32_e32 v68, v68, v180
	v_sub_f32_e32 v69, v69, v180
	v_sub_f32_e32 v70, v70, v180
	v_sub_f32_e32 v71, v71, v180
	v_sub_f32_e32 v72, v72, v180
	v_sub_f32_e32 v73, v73, v180
	v_sub_f32_e32 v74, v74, v180
	v_sub_f32_e32 v75, v75, v180
	v_sub_f32_e32 v76, v76, v180
	v_sub_f32_e32 v77, v77, v180
	v_sub_f32_e32 v78, v78, v180
	v_sub_f32_e32 v79, v79, v180
	v_exp_f32_e32 v64, v64
	v_exp_f32_e32 v65, v65
	v_exp_f32_e32 v66, v66
	v_exp_f32_e32 v67, v67
	v_exp_f32_e32 v68, v68
	v_exp_f32_e32 v69, v69
	v_exp_f32_e32 v70, v70
	v_exp_f32_e32 v71, v71
	v_exp_f32_e32 v72, v72
	v_exp_f32_e32 v73, v73
	v_exp_f32_e32 v74, v74
	v_exp_f32_e32 v75, v75
	v_exp_f32_e32 v76, v76
	v_exp_f32_e32 v77, v77
	v_exp_f32_e32 v78, v78
	v_exp_f32_e32 v79, v79
	v_add_f32_e32 v240, v64, v65
	v_add_f32_e32 v241, v66, v67
	v_cvt_pk_bf16_f32 v198, v64, v65
	v_cvt_pk_bf16_f32 v199, v66, v67
	v_cvt_pk_bf16_f32 v200, v68, v69
	v_cvt_pk_bf16_f32 v201, v70, v71
	v_cvt_pk_bf16_f32 v202, v72, v73
	v_cvt_pk_bf16_f32 v203, v74, v75
	v_cvt_pk_bf16_f32 v204, v76, v77
	v_cvt_pk_bf16_f32 v205, v78, v79
	v_add_f32_e32 v246, v68, v69
	v_add_f32_e32 v247, v70, v71
	s_waitcnt lgkmcnt(7)
	v_mfma_f32_32x32x16_bf16 v[48:63], v[206:209], v[198:201], v[48:63]
	ds_read_b128 v[182:185], v168 offset:12800
	v_add_f32_e32 v240, v240, v72
	v_add_f32_e32 v241, v241, v73
	s_waitcnt lgkmcnt(7)
	v_mfma_f32_32x32x16_bf16 v[48:63], v[210:213], v[202:205], v[48:63]
	ds_read_b128 v[186:189], v168 offset:12832
	v_add_f32_e32 v246, v246, v74
	v_add_f32_e32 v247, v247, v75
	s_waitcnt lgkmcnt(7)
	v_mfma_f32_32x32x16_bf16 v[32:47], v[214:217], v[202:205], v[32:47]
	ds_read_b128 v[190:193], v168 offset:12864
	v_add_f32_e32 v240, v240, v76
	v_add_f32_e32 v241, v241, v77
	s_waitcnt lgkmcnt(7)
	v_mfma_f32_32x32x16_bf16 v[32:47], v[218:221], v[198:201], v[32:47]
	ds_read_b128 v[194:197], v168 offset:12896
	v_add_f32_e32 v246, v246, v78
	v_add_f32_e32 v247, v247, v79
	s_waitcnt lgkmcnt(7)
	v_mfma_f32_32x32x16_bf16 v[16:31], v[222:225], v[198:201], v[16:31]
	v_add_f32_e32 v240, v240, v241
	s_waitcnt lgkmcnt(6)
	v_mfma_f32_32x32x16_bf16 v[16:31], v[226:229], v[202:205], v[16:31]
	v_add_f32_e32 v246, v246, v247
	s_waitcnt lgkmcnt(5)
	v_mfma_f32_32x32x16_bf16 v[0:15], v[230:233], v[202:205], v[0:15]
	v_add_f32_e32 v240, v240, v246
	s_waitcnt lgkmcnt(4)
	v_mfma_f32_32x32x16_bf16 v[0:15], v[236:239], v[198:201], v[0:15]
	v_fma_f32 v155, v155, v166, v240
	ds_read_b128 v[198:201], v168 offset:12928
	ds_read_b128 v[202:205], v168 offset:12960
	s_waitcnt lgkmcnt(5)
	v_mfma_f32_32x32x16_bf16 v[64:79], v[182:185], v[80:83], 0
	ds_read_b128 v[182:185], v168 offset:12992
	s_waitcnt lgkmcnt(5)
	v_mfma_f32_32x32x16_bf16 v[64:79], v[186:189], v[84:87], v[64:79]
	ds_read_b128 v[186:189], v168 offset:13024
	s_waitcnt lgkmcnt(5)
	v_mfma_f32_32x32x16_bf16 v[64:79], v[190:193], v[88:91], v[64:79]
	ds_read_b128 v[190:193], v168 offset:13056
	s_waitcnt lgkmcnt(5)
	v_mfma_f32_32x32x16_bf16 v[64:79], v[194:197], v[92:95], v[64:79]
	ds_read_b128 v[194:197], v168 offset:13088
	s_waitcnt lgkmcnt(5)
	v_mfma_f32_32x32x16_bf16 v[64:79], v[198:201], v[96:99], v[64:79]
	ds_read_b128 v[198:201], v168 offset:13120
	s_waitcnt lgkmcnt(5)
	v_mfma_f32_32x32x16_bf16 v[64:79], v[202:205], v[100:103], v[64:79]
	ds_read_b128 v[202:205], v168 offset:13152
	s_waitcnt lgkmcnt(5)
	v_mfma_f32_32x32x16_bf16 v[64:79], v[182:185], v[104:107], v[64:79]
	ds_read2_b64 v[206:209], v242 offset0:136 offset1:138
	s_waitcnt lgkmcnt(5)
	v_mfma_f32_32x32x16_bf16 v[64:79], v[186:189], v[108:111], v[64:79]
	ds_read2_b64 v[210:213], v242 offset0:140 offset1:142
	s_waitcnt lgkmcnt(5)
	v_mfma_f32_32x32x16_bf16 v[64:79], v[190:193], v[112:115], v[64:79]
	ds_read2_b64 v[214:217], v243 offset0:172 offset1:174
	s_waitcnt lgkmcnt(5)
	v_mfma_f32_32x32x16_bf16 v[64:79], v[194:197], v[116:119], v[64:79]
	ds_read2_b64 v[218:221], v243 offset0:168 offset1:170
	s_waitcnt lgkmcnt(5)
	v_mfma_f32_32x32x16_bf16 v[64:79], v[198:201], v[120:123], v[64:79]
	ds_read2_b64 v[222:225], v244 offset0:200 offset1:202
	s_waitcnt lgkmcnt(5)
	v_mfma_f32_32x32x16_bf16 v[64:79], v[202:205], v[124:127], v[64:79]
	ds_read2_b64 v[226:229], v244 offset0:204 offset1:206
	ds_read2_b64 v[230:233], v245 offset0:236 offset1:238
	ds_read2_b64 v[236:239], v245 offset0:232 offset1:234
	s_add_i32 s2, s80, 63
	s_cmp_le_i32 s2, s58
	s_nop 5
	s_cbranch_scc1 .Lmla_nomask_1
	v_subrev_u32_e32 v240, 32, v179
	s_nop 0
	v_cmp_gt_i32_e64 s[30:31], 26, v240
	v_cmp_gt_i32_e64 s[34:35], 27, v240
	v_cmp_gt_i32_e64 s[28:29], 25, v240
	s_and_b64 s[30:31], s[34:35], s[30:31]
	v_cmp_gt_i32_e64 s[26:27], 24, v240
	s_and_b64 s[28:29], s[30:31], s[28:29]
	v_cmp_gt_i32_e64 s[24:25], 19, v240
	s_and_b64 s[26:27], s[28:29], s[26:27]
	v_cmp_gt_i32_e64 s[22:23], 18, v240
	s_and_b64 s[24:25], s[26:27], s[24:25]
	v_cmp_gt_i32_e64 s[20:21], 17, v240
	s_and_b64 s[22:23], s[24:25], s[22:23]
	v_cmp_gt_i32_e64 s[18:19], 16, v240
	s_and_b64 s[20:21], s[22:23], s[20:21]
	v_cmp_gt_i32_e64 s[16:17], 11, v240
	s_and_b64 s[18:19], s[20:21], s[18:19]
	v_cmp_gt_i32_e64 s[14:15], 10, v240
	s_and_b64 s[16:17], s[18:19], s[16:17]
	v_cmp_gt_i32_e64 s[10:11], 9, v240
	s_and_b64 s[14:15], s[16:17], s[14:15]
	v_cmp_gt_i32_e64 s[8:9], 8, v240
	s_and_b64 s[10:11], s[14:15], s[10:11]
	v_cmp_gt_i32_e64 s[6:7], 3, v240
	s_and_b64 s[8:9], s[10:11], s[8:9]
	v_cmp_gt_i32_e64 s[4:5], 2, v240
	s_and_b64 s[6:7], s[8:9], s[6:7]
	v_cmp_gt_i32_e64 s[2:3], 1, v240
	s_and_b64 s[4:5], s[6:7], s[4:5]
	v_cmp_gt_i32_e32 vcc, 0, v240
	s_and_b64 s[2:3], s[4:5], s[2:3]
	s_and_b64 vcc, s[2:3], vcc
	s_nop 1
	v_cndmask_b32_e64 v79, v79, v170, s[34:35]
	v_cndmask_b32_e64 v78, v78, v170, s[30:31]
	v_cndmask_b32_e64 v77, v77, v170, s[28:29]
	v_cndmask_b32_e64 v76, v76, v170, s[26:27]
	v_cndmask_b32_e64 v75, v75, v170, s[24:25]
	v_cndmask_b32_e64 v74, v74, v170, s[22:23]
	v_cndmask_b32_e64 v73, v73, v170, s[20:21]
	v_cndmask_b32_e64 v72, v72, v170, s[18:19]
	v_cndmask_b32_e64 v71, v71, v170, s[16:17]
	v_cndmask_b32_e64 v70, v70, v170, s[14:15]
	v_cndmask_b32_e64 v69, v69, v170, s[10:11]
	v_cndmask_b32_e64 v68, v68, v170, s[8:9]
	v_cndmask_b32_e64 v67, v67, v170, s[6:7]
	v_cndmask_b32_e64 v66, v66, v170, s[4:5]
	v_cndmask_b32_e64 v65, v65, v170, s[2:3]
	v_cndmask_b32_e32 v64, v64, v170, vcc

; #define LAS __attribute__((address_space(3)))
; DI float xhalf_sum(float v) { unsigned a = __builtin_bit_cast(unsigned, v), b = a; swap32(a, b); return __builtin_bit_cast(float, a) + __builtin_bit_cast(float, b); }
; DI float fexp2(float x) { return __builtin_amdgcn_exp2f(x); }
; DI float frcp(float x) { return __builtin_amdgcn_rcpf(x); }
; #define MFMA32(a, b, c) __builtin_amdgcn_mfma_f32_32x32x16_bf16((a), (b), (c), 0, 0, 0)
; DI void mla_unit(const Params& p, LAS unsigned char* lds, int b, int h, int qb, int tid) {
;     ...
;                 for (int i = 0; i < 16; ++i) { const float pv = fexp2(s[i] - m); s[i] = pv; ps += pv; }
;                 l += ps;
;                 const bf16x8 pb0 = packp(s, 0), pb1 = packp(s, 1);
; #pragma unroll
;                 for (int db = 0; db < 4; ++db) {
;                     LAS const unsigned char* ap = buf + 25600 + (32 * db + c) * 136 + (32 * sub + 4 * hi) * 2;
;                     const bf16x8 v0 = cat4(*(LAS const bf16x4*)(ap), *(LAS const bf16x4*)(ap + 16));
;                     const bf16x8 v1 = cat4(*(LAS const bf16x4*)(ap + 32), *(LAS const bf16x4*)(ap + 48));
;                     o[db] = MFMA32(v0, pb0, o[db]); o[db] = MFMA32(v1, pb1, o[db]);
;     ...
;     const float lt = xhalf_sum(l), inv = frcp(lt);
.Lmla_norescale_1:
	v_sub_f32_e32 v64, v64, v180
	v_sub_f32_e32 v65, v65, v180
	v_sub_f32_e32 v66, v66, v180
	v_sub_f32_e32 v67, v67, v180
	v_sub_f32_e32 v68, v68, v180
	v_sub_f32_e32 v69, v69, v180
	v_sub_f32_e32 v70, v70, v180
	v_sub_f32_e32 v71, v71, v180
	v_sub_f32_e32 v72, v72, v180
	v_sub_f32_e32 v73, v73, v180
	v_sub_f32_e32 v74, v74, v180
	v_sub_f32_e32 v75, v75, v180
	v_sub_f32_e32 v76, v76, v180
	v_sub_f32_e32 v77, v77, v180
	v_sub_f32_e32 v78, v78, v180
	v_sub_f32_e32 v79, v79, v180
	v_exp_f32_e32 v64, v64
	v_exp_f32_e32 v65, v65
	v_exp_f32_e32 v66, v66
	v_exp_f32_e32 v67, v67
	v_exp_f32_e32 v68, v68
	v_exp_f32_e32 v69, v69
	v_exp_f32_e32 v70, v70
	v_exp_f32_e32 v71, v71
	v_exp_f32_e32 v72, v72
	v_exp_f32_e32 v73, v73
	v_exp_f32_e32 v74, v74
	v_exp_f32_e32 v75, v75
	v_exp_f32_e32 v76, v76
	v_exp_f32_e32 v77, v77
	v_exp_f32_e32 v78, v78
	v_exp_f32_e32 v79, v79
	v_add_f32_e32 v240, v64, v65
	v_add_f32_e32 v241, v66, v67
	v_cvt_pk_bf16_f32 v198, v64, v65
	v_cvt_pk_bf16_f32 v199, v66, v67
	v_cvt_pk_bf16_f32 v200, v68, v69
	v_cvt_pk_bf16_f32 v201, v70, v71
	v_cvt_pk_bf16_f32 v202, v72, v73
	v_cvt_pk_bf16_f32 v203, v74, v75
	v_cvt_pk_bf16_f32 v204, v76, v77
	v_cvt_pk_bf16_f32 v205, v78, v79
	v_add_f32_e32 v246, v68, v69
	v_add_f32_e32 v247, v70, v71
	s_waitcnt lgkmcnt(7)
	v_mfma_f32_32x32x16_bf16 v[48:63], v[206:209], v[198:201], v[48:63]
	v_add_f32_e32 v240, v240, v72
	v_add_f32_e32 v241, v241, v73
	s_waitcnt lgkmcnt(6)
	v_mfma_f32_32x32x16_bf16 v[48:63], v[210:213], v[202:205], v[48:63]
	v_add_f32_e32 v246, v246, v74
	v_add_f32_e32 v247, v247, v75
	s_waitcnt lgkmcnt(5)
	v_mfma_f32_32x32x16_bf16 v[32:47], v[214:217], v[202:205], v[32:47]
	v_add_f32_e32 v240, v240, v76
	v_add_f32_e32 v241, v241, v77
	s_waitcnt lgkmcnt(4)
	v_mfma_f32_32x32x16_bf16 v[32:47], v[218:221], v[198:201], v[32:47]
	v_add_f32_e32 v246, v246, v78
	v_add_f32_e32 v247, v247, v79
	s_waitcnt lgkmcnt(3)
	v_mfma_f32_32x32x16_bf16 v[16:31], v[222:225], v[198:201], v[16:31]
	v_add_f32_e32 v240, v240, v241
	s_waitcnt lgkmcnt(2)
	v_mfma_f32_32x32x16_bf16 v[16:31], v[226:229], v[202:205], v[16:31]
	v_add_f32_e32 v246, v246, v247
	s_waitcnt lgkmcnt(1)
	v_mfma_f32_32x32x16_bf16 v[0:15], v[230:233], v[202:205], v[0:15]
	v_add_f32_e32 v240, v240, v246
	s_waitcnt lgkmcnt(0)
	v_mfma_f32_32x32x16_bf16 v[0:15], v[236:239], v[198:201], v[0:15]
	v_fma_f32 v155, v155, v166, v240
	s_andn2_b64 vcc, exec, s[76:77]
	s_cbranch_vccz .LBB0_623
	s_branch .LBB0_624

; #define LAS __attribute__((address_space(3)))
; DI void nsa_unit(const Params& p, LAS unsigned char* lds, unsigned char* ldsg, int bg, int qt, int tid) {
;     ...
;     const int lane = tid & 63, w = __builtin_amdgcn_readfirstlane(tid >> 6), c = lane & 31, hi = lane >> 5;
;     const int b = bg >> 1, g = bg & 1, q0 = qt * 32;
;     const int head = c & 7, qi = c >> 3, tw0 = q0 + 4 * w, t = tw0 + qi, hh = g * 8 + head;
;     const size_t tokb = (size_t)b * S_, tok = tokb + t;
;     const float sc2 = 0.125f * LOG2E, slope2 = exp2f(-0.5f * (float)(hh + 1)) * LOG2E;
;     LAS unsigned* SEL = (LAS unsigned*)(lds + NSA_SEL);
;     LAS unsigned* UNI = (LAS unsigned*)(lds + NSA_UNI);
;     LAS int* NL = (LAS int*)(lds + NSA_NL);
;     LAS int* LIST = (LAS int*)(lds + NSA_LIST);
;     LAS float* IMPw = (LAS float*)(lds + NSA_IMP + w * 2048);
;     __syncthreads();
;     const int nct = (q0 / 16 + 1 + 31) >> 5;
; __global__ void __launch_bounds__(NTHREADS, 2) fwd_megakernel(Params p) {
;     ...
;     for (int u = bid, rnd = 0; u < 2048; u += G, ++rnd) {
;         PHASE_IDS;
;         const int bg = (u + rnd) & 7, qt = 255 - (u >> 3);
.LBB0_691:
	v_mov_b32_e32 v66, v167
	s_add_i32 s2, s12, s54
	s_and_b32 s87, s2, 1
	v_and_b32_e32 v108, 7, v66
	v_lshl_or_b32 v19, s87, 3, v108
	s_and_b32 s48, s2, 7
	s_lshl_b32 s2, s12, 2
	v_add_u32_e32 v0, 1, v19
	s_andn2_b32 s2, s2, 31
	s_bitcmp1_b32 s12, 8
	s_cselect_b32 s3, 0x3e0, 0
	s_xor_b32 s2, s2, s3
	v_cvt_f32_ubyte0_e32 v22, v0
	s_sub_i32 s57, 0x1fe0, s2
	v_mul_f32_e32 v0, -0.5, v22
	s_mov_b32 s2, 0xc2fc0000
	v_cmp_gt_f32_e32 vcc, s2, v0
	s_lshr_b32 s2, s57, 4
	s_add_i32 s2, s2, 32
	s_lshr_b32 s16, s2, 5
	s_and_b32 s56, s69, 0xffffffe0
	s_xor_b32 s56, s56, s3
	s_lshl_b32 s19, s16, 8
	s_sub_i32 s18, 0x1fe0, s56
	v_readfirstlane_b32 s88, v66
	v_cmp_gt_i32_e64 s[2:3], s19, v66
	s_barrier
	s_and_saveexec_b64 s[10:11], s[2:3]
	s_cbranch_execz .LBB0_720
	v_lshlrev_b32_e32 v23, 4, v66
	v_lshlrev_b32_e32 v18, 3, v66
	s_lshl_b32 s17, s48, 9
	s_mov_b64 s[8:9], 0
	v_mov_b32_e32 v24, v18
	v_mov_b32_e32 v25, v23
	v_mov_b32_e32 v26, v66
	s_branch .LBB0_694

; #define PG8_STAGE(bufoff, gbase, voff) do { _Pragma("unroll") for (int _i = 0; _i < 2; ++_i) \
;         __builtin_amdgcn_global_load_lds((const unsigned*)((const char*)(gbase) + (voff)[_i]), (LAS unsigned*)(lds + (bufoff) + ldsw + _i * 8192), 16, 0, 0); } while (0)
; #define PG8_LDA(dst, b, h) do { _Pragma("unroll") for (int m = 0; m < 4; ++m) _Pragma("unroll") for (int k = 0; k < 2; ++k) dst[m][k] = *(const LAS bf16x8*)(lds + PG8_SA(b, h) + aoff + m * 2048 + k * 1024); } while (0)
; #define PG8_LDB(dst, b, h) do { _Pragma("unroll") for (int n = 0; n < 2; ++n) _Pragma("unroll") for (int k = 0; k < 2; ++k) dst[n][k] = *(const LAS bf16x8*)(lds + PG8_SB(b, h) + boff + n * 2048 + k * 1024); } while (0)
; #define PG8_MMA(ai, bj, At, Bt) do { __builtin_amdgcn_s_setprio(1); _Pragma("unroll") for (int m = 0; m < 4; ++m) _Pragma("unroll") for (int n = 0; n < 2; ++n) _Pragma("unroll") for (int k = 0; k < 2; ++k) \
;         acc[ai][bj][m][n] = __builtin_amdgcn_mfma_f32_16x16x32_bf16(Bt[n][k], At[m][k], acc[ai][bj][m][n], 0, 0, 0); __builtin_amdgcn_s_setprio(0); } while (0)
; #define PG8_WAIT_V(n) asm volatile("s_waitcnt vmcnt(" #n ")" ::: "memory")
; #define PG8_WAIT_L(n) asm volatile("s_waitcnt lgkmcnt(" #n ")" ::: "memory")
; #define PG8_BAR __builtin_amdgcn_s_barrier()
; #define PG8_SCHED __builtin_amdgcn_sched_barrier(0)
; DI void gemm_phase(LAS unsigned char* lds, const Gemm g, const StaticOrder& S, const Epi& E) {
;     ...
;             const bool last = (t == nt - 2);
;             const char* a1 = cA + (size_t)(t + 1) * kstep;
;             const char* a2 = last ? nA : cA + (size_t)(t + 2) * kstep; const char* b2 = last ? nB : cB + (size_t)(t + 2) * kstep;
;             const char* a3 = a2 + kstep; const char* b3 = b2 + kstep;
;             PG8_LDB(B0, 0, 0); PG8_LDB(B1, 0, 1); PG8_SCHED; PG8_LDA(At, 0, 0); PG8_STAGE(PG8_SA(1, 1), a1 + hsA, voffA);
;             PG8_WAIT_V(8); PG8_WAIT_L(0); PG8_BAR; PG8_MMA(0, 0, At, B0); PG8_MMA(0, 1, At, B1); PG8_BAR; PG8_SCHED;
;             PG8_LDA(At, 0, 1); PG8_STAGE(PG8_SB(0, 0), b2, voffB); PG8_STAGE(PG8_SB(0, 1), b2 + hsB, voffB); PG8_STAGE(PG8_SA(0, 0), a2, voffA);
;             PG8_WAIT_V(8); PG8_WAIT_L(0); PG8_BAR; PG8_MMA(1, 0, At, B0); PG8_MMA(1, 1, At, B1); PG8_BAR; PG8_SCHED;
.LBB0_936:
	ds_read_b128 v[144:147], v155
	ds_read_b128 v[148:151], v155 offset:1024
	ds_read_b128 v[160:163], v155 offset:2048
	ds_read_b128 v[170:173], v155 offset:3072
	ds_read_b128 v[174:177], v156
	ds_read_b128 v[178:181], v156 offset:1024
	ds_read_b128 v[182:185], v156 offset:2048
	ds_read_b128 v[186:189], v156 offset:3072
	s_add_u32 s34, s30, 0xfff80080
	s_addc_u32 s35, s31, -1
	s_cmp_eq_u32 s51, 28
	s_cselect_b32 s37, s21, s35
	s_cselect_b32 s36, s27, s34
	s_cselect_b32 s35, s19, s50
	s_cselect_b32 s34, s48, s49
	v_lshl_add_u64 v[164:165], s[30:31], 0, v[136:137]
	s_add_i32 m0, s13, 0xc000
	ds_read_b128 v[190:193], v157
	ds_read_b128 v[194:197], v157 offset:1024
	ds_read_b128 v[198:201], v157 offset:2048
	ds_read_b128 v[202:205], v157 offset:3072
	ds_read_b128 v[206:209], v157 offset:4096
	ds_read_b128 v[210:213], v157 offset:5120
	ds_read_b128 v[214:217], v157 offset:6144
	ds_read_b128 v[218:221], v157 offset:7168
	global_load_lds_dwordx4 v[164:165], off
	v_lshl_add_u64 v[164:165], s[30:31], 0, v[138:139]
	s_add_i32 m0, s13, 0xe000
	s_nop 0
	global_load_lds_dwordx4 v[164:165], off
	s_waitcnt vmcnt(8)
	s_waitcnt lgkmcnt(0)
	s_barrier
	s_setprio 1
	s_waitcnt lgkmcnt(0)
	v_mfma_f32_16x16x32_bf16 v[124:127], v[144:147], v[190:193], v[124:127]
	v_mfma_f32_16x16x32_bf16 v[124:127], v[148:151], v[194:197], v[124:127]
	v_mfma_f32_16x16x32_bf16 v[120:123], v[170:173], v[194:197], v[120:123]
	v_mfma_f32_16x16x32_bf16 v[120:123], v[160:163], v[190:193], v[120:123]
	v_mfma_f32_16x16x32_bf16 v[104:107], v[160:163], v[198:201], v[104:107]
	v_mfma_f32_16x16x32_bf16 v[104:107], v[170:173], v[202:205], v[104:107]
	v_mfma_f32_16x16x32_bf16 v[108:111], v[148:151], v[202:205], v[108:111]
	v_mfma_f32_16x16x32_bf16 v[108:111], v[144:147], v[198:201], v[108:111]
	v_mfma_f32_16x16x32_bf16 v[92:95], v[144:147], v[206:209], v[92:95]
	v_mfma_f32_16x16x32_bf16 v[92:95], v[148:151], v[210:213], v[92:95]
	v_mfma_f32_16x16x32_bf16 v[88:91], v[170:173], v[210:213], v[88:91]
	v_mfma_f32_16x16x32_bf16 v[88:91], v[160:163], v[206:209], v[88:91]
	v_mfma_f32_16x16x32_bf16 v[72:75], v[160:163], v[214:217], v[72:75]
	v_mfma_f32_16x16x32_bf16 v[72:75], v[170:173], v[218:221], v[72:75]
	v_mfma_f32_16x16x32_bf16 v[76:79], v[148:151], v[218:221], v[76:79]
	v_mfma_f32_16x16x32_bf16 v[76:79], v[144:147], v[214:217], v[76:79]
	s_setprio 0
	s_setprio 1
	v_mfma_f32_16x16x32_bf16 v[116:119], v[174:177], v[190:193], v[116:119]
	v_mfma_f32_16x16x32_bf16 v[116:119], v[178:181], v[194:197], v[116:119]
	v_mfma_f32_16x16x32_bf16 v[112:115], v[186:189], v[194:197], v[112:115]
	v_mfma_f32_16x16x32_bf16 v[112:115], v[182:185], v[190:193], v[112:115]
	v_mfma_f32_16x16x32_bf16 v[96:99], v[182:185], v[198:201], v[96:99]
	v_mfma_f32_16x16x32_bf16 v[96:99], v[186:189], v[202:205], v[96:99]
	v_mfma_f32_16x16x32_bf16 v[100:103], v[178:181], v[202:205], v[100:103]
	v_mfma_f32_16x16x32_bf16 v[100:103], v[174:177], v[198:201], v[100:103]
	v_mfma_f32_16x16x32_bf16 v[84:87], v[174:177], v[206:209], v[84:87]
	v_mfma_f32_16x16x32_bf16 v[84:87], v[178:181], v[210:213], v[84:87]
	v_mfma_f32_16x16x32_bf16 v[80:83], v[186:189], v[210:213], v[80:83]
	v_mfma_f32_16x16x32_bf16 v[80:83], v[182:185], v[206:209], v[80:83]
	v_mfma_f32_16x16x32_bf16 v[64:67], v[182:185], v[214:217], v[64:67]
	v_mfma_f32_16x16x32_bf16 v[64:67], v[186:189], v[218:221], v[64:67]
	v_mfma_f32_16x16x32_bf16 v[68:71], v[178:181], v[218:221], v[68:71]
	v_mfma_f32_16x16x32_bf16 v[68:71], v[174:177], v[214:217], v[68:71]
	s_setprio 0
	s_barrier
	s_add_i32 s46, s42, s12
	v_lshl_add_u64 v[164:165], s[34:35], 0, v[130:131]
	s_mov_b32 m0, s46
	ds_read_b128 v[190:193], v157 offset:16384
	ds_read_b128 v[194:197], v157 offset:17408
	ds_read_b128 v[198:201], v157 offset:18432
	ds_read_b128 v[202:205], v157 offset:19456
	ds_read_b128 v[206:209], v157 offset:20480
	ds_read_b128 v[210:213], v157 offset:21504
	ds_read_b128 v[214:217], v157 offset:22528
	ds_read_b128 v[218:221], v157 offset:23552
	global_load_lds_dwordx4 v[164:165], off
	s_add_i32 m0, s46, 0x2000
	s_add_u32 s46, s34, 0x80000
	v_lshl_add_u64 v[222:223], s[34:35], 0, v[134:135]
	s_addc_u32 s47, s35, 0
	s_add_i32 s52, s43, s12
	global_load_lds_dwordx4 v[222:223], off
	v_lshl_add_u64 v[224:225], s[46:47], 0, v[130:131]
	s_mov_b32 m0, s52
	v_lshl_add_u64 v[226:227], s[36:37], 0, v[132:133]
	global_load_lds_dwordx4 v[224:225], off
	v_lshl_add_u64 v[224:225], s[46:47], 0, v[134:135]
	s_add_i32 m0, s52, 0x2000
	s_nop 0
	global_load_lds_dwordx4 v[224:225], off
	v_lshl_add_u64 v[224:225], s[36:37], 0, v[128:129]
	s_mov_b32 m0, s13
	s_nop 0
	global_load_lds_dwordx4 v[224:225], off
	s_mov_b32 m0, s29
	s_nop 0
	global_load_lds_dwordx4 v[226:227], off
	s_waitcnt vmcnt(8)
	s_waitcnt lgkmcnt(0)
	s_barrier
; #define PG8_STAGE(bufoff, gbase, voff) do { _Pragma("unroll") for (int _i = 0; _i < 2; ++_i) \
;         __builtin_amdgcn_global_load_lds((const unsigned*)((const char*)(gbase) + (voff)[_i]), (LAS unsigned*)(lds + (bufoff) + ldsw + _i * 8192), 16, 0, 0); } while (0)
; #define PG8_LDA(dst, b, h) do { _Pragma("unroll") for (int m = 0; m < 4; ++m) _Pragma("unroll") for (int k = 0; k < 2; ++k) dst[m][k] = *(const LAS bf16x8*)(lds + PG8_SA(b, h) + aoff + m * 2048 + k * 1024); } while (0)
; #define PG8_LDB(dst, b, h) do { _Pragma("unroll") for (int n = 0; n < 2; ++n) _Pragma("unroll") for (int k = 0; k < 2; ++k) dst[n][k] = *(const LAS bf16x8*)(lds + PG8_SB(b, h) + boff + n * 2048 + k * 1024); } while (0)
; #define PG8_MMA(ai, bj, At, Bt) do { __builtin_amdgcn_s_setprio(1); _Pragma("unroll") for (int m = 0; m < 4; ++m) _Pragma("unroll") for (int n = 0; n < 2; ++n) _Pragma("unroll") for (int k = 0; k < 2; ++k) \
;         acc[ai][bj][m][n] = __builtin_amdgcn_mfma_f32_16x16x32_bf16(Bt[n][k], At[m][k], acc[ai][bj][m][n], 0, 0, 0); __builtin_amdgcn_s_setprio(0); } while (0)
; #define PG8_WAIT_V(n) asm volatile("s_waitcnt vmcnt(" #n ")" ::: "memory")
; #define PG8_WAIT_L(n) asm volatile("s_waitcnt lgkmcnt(" #n ")" ::: "memory")
; #define PG8_BAR __builtin_amdgcn_s_barrier()
; #define PG8_SCHED __builtin_amdgcn_sched_barrier(0)
; DI void gemm_phase(LAS unsigned char* lds, const Gemm g, const StaticOrder& S, const Epi& E) {
;     ...
;             PG8_WAIT_V(8); PG8_WAIT_L(0); PG8_BAR; PG8_MMA(1, 0, At, B0); PG8_MMA(1, 1, At, B1); PG8_BAR; PG8_SCHED;
;             PG8_LDB(B0, 1, 0); PG8_LDB(B1, 1, 1); PG8_SCHED; PG8_LDA(At, 1, 0); PG8_STAGE(PG8_SA(0, 1), a2 + hsA, voffA);
;             PG8_WAIT_V(8); PG8_WAIT_L(0); PG8_BAR; PG8_MMA(0, 0, At, B0); PG8_MMA(0, 1, At, B1); PG8_BAR; PG8_SCHED;
	s_setprio 1
	s_waitcnt lgkmcnt(0)
	v_mfma_f32_16x16x32_bf16 v[60:63], v[144:147], v[190:193], v[60:63]
	v_mfma_f32_16x16x32_bf16 v[60:63], v[148:151], v[194:197], v[60:63]
	v_mfma_f32_16x16x32_bf16 v[56:59], v[170:173], v[194:197], v[56:59]
	v_mfma_f32_16x16x32_bf16 v[56:59], v[160:163], v[190:193], v[56:59]
	v_mfma_f32_16x16x32_bf16 v[40:43], v[160:163], v[198:201], v[40:43]
	v_mfma_f32_16x16x32_bf16 v[40:43], v[170:173], v[202:205], v[40:43]
	v_mfma_f32_16x16x32_bf16 v[44:47], v[148:151], v[202:205], v[44:47]
	v_mfma_f32_16x16x32_bf16 v[44:47], v[144:147], v[198:201], v[44:47]
	v_mfma_f32_16x16x32_bf16 v[28:31], v[144:147], v[206:209], v[28:31]
	v_mfma_f32_16x16x32_bf16 v[28:31], v[148:151], v[210:213], v[28:31]
	v_mfma_f32_16x16x32_bf16 v[24:27], v[170:173], v[210:213], v[24:27]
	v_mfma_f32_16x16x32_bf16 v[24:27], v[160:163], v[206:209], v[24:27]
	v_mfma_f32_16x16x32_bf16 v[8:11], v[160:163], v[214:217], v[8:11]
	v_mfma_f32_16x16x32_bf16 v[8:11], v[170:173], v[218:221], v[8:11]
	v_mfma_f32_16x16x32_bf16 v[12:15], v[148:151], v[218:221], v[12:15]
	v_mfma_f32_16x16x32_bf16 v[12:15], v[144:147], v[214:217], v[12:15]
	s_setprio 0
	s_setprio 1
	v_mfma_f32_16x16x32_bf16 v[52:55], v[174:177], v[190:193], v[52:55]
	v_mfma_f32_16x16x32_bf16 v[52:55], v[178:181], v[194:197], v[52:55]
	v_mfma_f32_16x16x32_bf16 v[48:51], v[186:189], v[194:197], v[48:51]
	v_mfma_f32_16x16x32_bf16 v[48:51], v[182:185], v[190:193], v[48:51]
	v_mfma_f32_16x16x32_bf16 v[32:35], v[182:185], v[198:201], v[32:35]
	v_mfma_f32_16x16x32_bf16 v[32:35], v[186:189], v[202:205], v[32:35]
	v_mfma_f32_16x16x32_bf16 v[36:39], v[178:181], v[202:205], v[36:39]
	v_mfma_f32_16x16x32_bf16 v[36:39], v[174:177], v[198:201], v[36:39]
	v_mfma_f32_16x16x32_bf16 v[20:23], v[174:177], v[206:209], v[20:23]
	v_mfma_f32_16x16x32_bf16 v[20:23], v[178:181], v[210:213], v[20:23]
	v_mfma_f32_16x16x32_bf16 v[16:19], v[186:189], v[210:213], v[16:19]
	v_mfma_f32_16x16x32_bf16 v[16:19], v[182:185], v[206:209], v[16:19]
	v_mfma_f32_16x16x32_bf16 v[0:3], v[182:185], v[214:217], v[0:3]
	v_mfma_f32_16x16x32_bf16 v[0:3], v[186:189], v[218:221], v[0:3]
	v_mfma_f32_16x16x32_bf16 v[4:7], v[178:181], v[218:221], v[4:7]
	v_mfma_f32_16x16x32_bf16 v[4:7], v[174:177], v[214:217], v[4:7]
	s_setprio 0
	s_barrier
	s_add_i32 s46, 0, 0x18000
	v_add_u32_e32 v159, s46, v153
	s_add_i32 s47, 0, 0x1c000
	ds_read_b128 v[144:147], v159
	ds_read_b128 v[148:151], v159 offset:1024
	ds_read_b128 v[160:163], v159 offset:2048
	ds_read_b128 v[170:173], v159 offset:3072
	v_add_u32_e32 v159, s47, v153
	ds_read_b128 v[174:177], v159
	ds_read_b128 v[178:181], v159 offset:1024
	ds_read_b128 v[182:185], v159 offset:2048
	ds_read_b128 v[186:189], v159 offset:3072
	s_add_u32 s36, s36, 0x80000
	s_addc_u32 s37, s37, 0
	s_mov_b32 m0, s33
	v_lshl_add_u64 v[228:229], s[36:37], 0, v[128:129]
	ds_read_b128 v[190:193], v157 offset:32768
	ds_read_b128 v[194:197], v157 offset:33792
	ds_read_b128 v[198:201], v157 offset:34816
	ds_read_b128 v[202:205], v157 offset:35840
	ds_read_b128 v[206:209], v157 offset:36864
	ds_read_b128 v[210:213], v157 offset:37888
	ds_read_b128 v[214:217], v157 offset:38912
	ds_read_b128 v[218:221], v157 offset:39936
	global_load_lds_dwordx4 v[228:229], off
	v_lshl_add_u64 v[228:229], s[36:37], 0, v[132:133]
	s_mov_b32 m0, s38
	s_nop 0
	global_load_lds_dwordx4 v[228:229], off
	s_waitcnt vmcnt(8)
	s_waitcnt lgkmcnt(0)
	s_barrier
	s_setprio 1
	s_waitcnt lgkmcnt(0)
	v_mfma_f32_16x16x32_bf16 v[124:127], v[144:147], v[190:193], v[124:127]
	v_mfma_f32_16x16x32_bf16 v[124:127], v[148:151], v[194:197], v[124:127]
	v_mfma_f32_16x16x32_bf16 v[120:123], v[170:173], v[194:197], v[120:123]
	v_mfma_f32_16x16x32_bf16 v[120:123], v[160:163], v[190:193], v[120:123]
	v_mfma_f32_16x16x32_bf16 v[104:107], v[160:163], v[198:201], v[104:107]
	v_mfma_f32_16x16x32_bf16 v[104:107], v[170:173], v[202:205], v[104:107]
	v_mfma_f32_16x16x32_bf16 v[108:111], v[148:151], v[202:205], v[108:111]
	v_mfma_f32_16x16x32_bf16 v[108:111], v[144:147], v[198:201], v[108:111]
	v_mfma_f32_16x16x32_bf16 v[92:95], v[144:147], v[206:209], v[92:95]
	v_mfma_f32_16x16x32_bf16 v[92:95], v[148:151], v[210:213], v[92:95]
	v_mfma_f32_16x16x32_bf16 v[88:91], v[170:173], v[210:213], v[88:91]
	v_mfma_f32_16x16x32_bf16 v[88:91], v[160:163], v[206:209], v[88:91]
	v_mfma_f32_16x16x32_bf16 v[72:75], v[160:163], v[214:217], v[72:75]
	v_mfma_f32_16x16x32_bf16 v[72:75], v[170:173], v[218:221], v[72:75]
	v_mfma_f32_16x16x32_bf16 v[76:79], v[148:151], v[218:221], v[76:79]
	v_mfma_f32_16x16x32_bf16 v[76:79], v[144:147], v[214:217], v[76:79]
	s_setprio 0
	s_setprio 1
	v_mfma_f32_16x16x32_bf16 v[116:119], v[174:177], v[190:193], v[116:119]
	v_mfma_f32_16x16x32_bf16 v[116:119], v[178:181], v[194:197], v[116:119]
	v_mfma_f32_16x16x32_bf16 v[112:115], v[186:189], v[194:197], v[112:115]
	v_mfma_f32_16x16x32_bf16 v[112:115], v[182:185], v[190:193], v[112:115]
	v_mfma_f32_16x16x32_bf16 v[96:99], v[182:185], v[198:201], v[96:99]
	v_mfma_f32_16x16x32_bf16 v[96:99], v[186:189], v[202:205], v[96:99]
	v_mfma_f32_16x16x32_bf16 v[100:103], v[178:181], v[202:205], v[100:103]
	v_mfma_f32_16x16x32_bf16 v[100:103], v[174:177], v[198:201], v[100:103]
	v_mfma_f32_16x16x32_bf16 v[84:87], v[174:177], v[206:209], v[84:87]
	v_mfma_f32_16x16x32_bf16 v[84:87], v[178:181], v[210:213], v[84:87]
	v_mfma_f32_16x16x32_bf16 v[80:83], v[186:189], v[210:213], v[80:83]
	v_mfma_f32_16x16x32_bf16 v[80:83], v[182:185], v[206:209], v[80:83]
	v_mfma_f32_16x16x32_bf16 v[64:67], v[182:185], v[214:217], v[64:67]
	v_mfma_f32_16x16x32_bf16 v[64:67], v[186:189], v[218:221], v[64:67]
	v_mfma_f32_16x16x32_bf16 v[68:71], v[178:181], v[218:221], v[68:71]
	v_mfma_f32_16x16x32_bf16 v[68:71], v[174:177], v[214:217], v[68:71]
	s_setprio 0
	s_barrier
; #define PG8_STAGE(bufoff, gbase, voff) do { _Pragma("unroll") for (int _i = 0; _i < 2; ++_i) \
;         __builtin_amdgcn_global_load_lds((const unsigned*)((const char*)(gbase) + (voff)[_i]), (LAS unsigned*)(lds + (bufoff) + ldsw + _i * 8192), 16, 0, 0); } while (0)
; #define PG8_LDA(dst, b, h) do { _Pragma("unroll") for (int m = 0; m < 4; ++m) _Pragma("unroll") for (int k = 0; k < 2; ++k) dst[m][k] = *(const LAS bf16x8*)(lds + PG8_SA(b, h) + aoff + m * 2048 + k * 1024); } while (0)
; #define PG8_MMA(ai, bj, At, Bt) do { __builtin_amdgcn_s_setprio(1); _Pragma("unroll") for (int m = 0; m < 4; ++m) _Pragma("unroll") for (int n = 0; n < 2; ++n) _Pragma("unroll") for (int k = 0; k < 2; ++k) \
;         acc[ai][bj][m][n] = __builtin_amdgcn_mfma_f32_16x16x32_bf16(Bt[n][k], At[m][k], acc[ai][bj][m][n], 0, 0, 0); __builtin_amdgcn_s_setprio(0); } while (0)
; #define PG8_WAIT_V(n) asm volatile("s_waitcnt vmcnt(" #n ")" ::: "memory")
; #define PG8_WAIT_L(n) asm volatile("s_waitcnt lgkmcnt(" #n ")" ::: "memory")
; #define PG8_BAR __builtin_amdgcn_s_barrier()
; #define PG8_SCHED __builtin_amdgcn_sched_barrier(0)
; DI void gemm_phase(LAS unsigned char* lds, const Gemm g, const StaticOrder& S, const Epi& E) {
;     ...
;             PG8_LDA(At, 1, 1); PG8_STAGE(PG8_SB(1, 0), b3, voffB); PG8_STAGE(PG8_SB(1, 1), b3 + hsB, voffB); PG8_STAGE(PG8_SA(1, 0), a3, voffA);
;             PG8_WAIT_V(8); PG8_WAIT_L(0); PG8_BAR; PG8_MMA(1, 0, At, B0); PG8_MMA(1, 1, At, B1); PG8_BAR; PG8_SCHED;
;         }
	s_add_i32 s36, s46, s12
	v_lshl_add_u64 v[164:165], v[164:165], 0, s[14:15]
	s_mov_b32 m0, s36
	ds_read_b128 v[190:193], v157 offset:49152
	ds_read_b128 v[194:197], v157 offset:50176
	ds_read_b128 v[198:201], v157 offset:51200
	ds_read_b128 v[202:205], v157 offset:52224
	ds_read_b128 v[206:209], v157 offset:53248
	ds_read_b128 v[210:213], v157 offset:54272
	ds_read_b128 v[214:217], v157 offset:55296
	ds_read_b128 v[218:221], v157 offset:56320
	global_load_lds_dwordx4 v[164:165], off
	s_add_i32 m0, s36, 0x2000
	s_add_u32 s34, s34, 0x80080
	v_lshl_add_u64 v[164:165], v[222:223], 0, s[14:15]
	s_addc_u32 s35, s35, 0
	s_add_i32 s36, s47, s12
	global_load_lds_dwordx4 v[164:165], off
	v_lshl_add_u64 v[164:165], s[34:35], 0, v[130:131]
	s_mov_b32 m0, s36
	s_nop 0
	global_load_lds_dwordx4 v[164:165], off
	v_lshl_add_u64 v[164:165], s[34:35], 0, v[134:135]
	s_add_i32 m0, s36, 0x2000
	s_nop 0
	global_load_lds_dwordx4 v[164:165], off
	v_lshl_add_u64 v[164:165], v[224:225], 0, s[14:15]
	s_mov_b32 m0, s40
	s_nop 0
	global_load_lds_dwordx4 v[164:165], off
	v_lshl_add_u64 v[164:165], v[226:227], 0, s[14:15]
	s_mov_b32 m0, s41
	s_nop 0
	global_load_lds_dwordx4 v[164:165], off
	s_waitcnt vmcnt(8)
	s_waitcnt lgkmcnt(0)
	s_barrier
	s_setprio 1
	s_waitcnt lgkmcnt(0)
	v_mfma_f32_16x16x32_bf16 v[60:63], v[144:147], v[190:193], v[60:63]
	v_mfma_f32_16x16x32_bf16 v[60:63], v[148:151], v[194:197], v[60:63]
	v_mfma_f32_16x16x32_bf16 v[56:59], v[170:173], v[194:197], v[56:59]
	v_mfma_f32_16x16x32_bf16 v[56:59], v[160:163], v[190:193], v[56:59]
	v_mfma_f32_16x16x32_bf16 v[40:43], v[160:163], v[198:201], v[40:43]
	v_mfma_f32_16x16x32_bf16 v[40:43], v[170:173], v[202:205], v[40:43]
	v_mfma_f32_16x16x32_bf16 v[44:47], v[148:151], v[202:205], v[44:47]
	v_mfma_f32_16x16x32_bf16 v[44:47], v[144:147], v[198:201], v[44:47]
	v_mfma_f32_16x16x32_bf16 v[28:31], v[144:147], v[206:209], v[28:31]
	v_mfma_f32_16x16x32_bf16 v[28:31], v[148:151], v[210:213], v[28:31]
	v_mfma_f32_16x16x32_bf16 v[24:27], v[170:173], v[210:213], v[24:27]
	v_mfma_f32_16x16x32_bf16 v[24:27], v[160:163], v[206:209], v[24:27]
	v_mfma_f32_16x16x32_bf16 v[8:11], v[160:163], v[214:217], v[8:11]
	v_mfma_f32_16x16x32_bf16 v[8:11], v[170:173], v[218:221], v[8:11]
	v_mfma_f32_16x16x32_bf16 v[12:15], v[148:151], v[218:221], v[12:15]
	v_mfma_f32_16x16x32_bf16 v[12:15], v[144:147], v[214:217], v[12:15]
	s_setprio 0
	s_setprio 1
	v_mfma_f32_16x16x32_bf16 v[52:55], v[174:177], v[190:193], v[52:55]
	v_mfma_f32_16x16x32_bf16 v[52:55], v[178:181], v[194:197], v[52:55]
	v_mfma_f32_16x16x32_bf16 v[48:51], v[186:189], v[194:197], v[48:51]
	v_mfma_f32_16x16x32_bf16 v[48:51], v[182:185], v[190:193], v[48:51]
	v_mfma_f32_16x16x32_bf16 v[32:35], v[182:185], v[198:201], v[32:35]
	v_mfma_f32_16x16x32_bf16 v[32:35], v[186:189], v[202:205], v[32:35]
	v_mfma_f32_16x16x32_bf16 v[36:39], v[178:181], v[202:205], v[36:39]
	v_mfma_f32_16x16x32_bf16 v[36:39], v[174:177], v[198:201], v[36:39]
	v_mfma_f32_16x16x32_bf16 v[20:23], v[174:177], v[206:209], v[20:23]
	v_mfma_f32_16x16x32_bf16 v[20:23], v[178:181], v[210:213], v[20:23]
	v_mfma_f32_16x16x32_bf16 v[16:19], v[186:189], v[210:213], v[16:19]
	v_mfma_f32_16x16x32_bf16 v[16:19], v[182:185], v[206:209], v[16:19]
	v_mfma_f32_16x16x32_bf16 v[0:3], v[182:185], v[214:217], v[0:3]
	v_mfma_f32_16x16x32_bf16 v[0:3], v[186:189], v[218:221], v[0:3]
	v_mfma_f32_16x16x32_bf16 v[4:7], v[178:181], v[218:221], v[4:7]
	v_mfma_f32_16x16x32_bf16 v[4:7], v[174:177], v[214:217], v[4:7]
	s_setprio 0
	s_barrier
	s_add_i32 s51, s51, 2
	s_add_u32 s30, s30, 0x100
	s_addc_u32 s31, s31, 0
	s_add_u32 s49, s49, 0x100
	s_addc_u32 s50, s50, 0
	s_cmp_gt_u32 s51, 29
	s_cbranch_scc0 .LBB0_936
	s_and_b64 vcc, exec, s[16:17]
	s_cbranch_vccz .LBB0_939
	s_barrier

; #define PG8_STAGE(bufoff, gbase, voff) do { _Pragma("unroll") for (int _i = 0; _i < 2; ++_i) \
;         __builtin_amdgcn_global_load_lds((const unsigned*)((const char*)(gbase) + (voff)[_i]), (LAS unsigned*)(lds + (bufoff) + ldsw + _i * 8192), 16, 0, 0); } while (0)
; #define PG8_LDA(dst, b, h) do { _Pragma("unroll") for (int m = 0; m < 4; ++m) _Pragma("unroll") for (int k = 0; k < 2; ++k) dst[m][k] = *(const LAS bf16x8*)(lds + PG8_SA(b, h) + aoff + m * 2048 + k * 1024); } while (0)
; #define PG8_LDB(dst, b, h) do { _Pragma("unroll") for (int n = 0; n < 2; ++n) _Pragma("unroll") for (int k = 0; k < 2; ++k) dst[n][k] = *(const LAS bf16x8*)(lds + PG8_SB(b, h) + boff + n * 2048 + k * 1024); } while (0)
; #define PG8_MMA(ai, bj, At, Bt) do { __builtin_amdgcn_s_setprio(1); _Pragma("unroll") for (int m = 0; m < 4; ++m) _Pragma("unroll") for (int n = 0; n < 2; ++n) _Pragma("unroll") for (int k = 0; k < 2; ++k) \
;         acc[ai][bj][m][n] = __builtin_amdgcn_mfma_f32_16x16x32_bf16(Bt[n][k], At[m][k], acc[ai][bj][m][n], 0, 0, 0); __builtin_amdgcn_s_setprio(0); } while (0)
; #define PG8_WAIT_V(n) asm volatile("s_waitcnt vmcnt(" #n ")" ::: "memory")
; #define PG8_WAIT_L(n) asm volatile("s_waitcnt lgkmcnt(" #n ")" ::: "memory")
; #define PG8_BAR __builtin_amdgcn_s_barrier()
; #define PG8_SCHED __builtin_amdgcn_sched_barrier(0)
; DI void gemm_phase(LAS unsigned char* lds, const Gemm g, const StaticOrder& S, const Epi& E) {
;     ...
;             const bool last = (t == nt - 2);
;             const char* a1 = cA + (size_t)(t + 1) * kstep;
;             const char* a2 = last ? nA : cA + (size_t)(t + 2) * kstep; const char* b2 = last ? nB : cB + (size_t)(t + 2) * kstep;
;             const char* a3 = a2 + kstep; const char* b3 = b2 + kstep;
;             PG8_LDB(B0, 0, 0); PG8_LDB(B1, 0, 1); PG8_SCHED; PG8_LDA(At, 0, 0); PG8_STAGE(PG8_SA(1, 1), a1 + hsA, voffA);
;             PG8_WAIT_V(8); PG8_WAIT_L(0); PG8_BAR; PG8_MMA(0, 0, At, B0); PG8_MMA(0, 1, At, B1); PG8_BAR; PG8_SCHED;
;             PG8_LDA(At, 0, 1); PG8_STAGE(PG8_SB(0, 0), b2, voffB); PG8_STAGE(PG8_SB(0, 1), b2 + hsB, voffB); PG8_STAGE(PG8_SA(0, 0), a2, voffA);
;             PG8_WAIT_V(8); PG8_WAIT_L(0); PG8_BAR; PG8_MMA(1, 0, At, B0); PG8_MMA(1, 1, At, B1); PG8_BAR; PG8_SCHED;
.LBB0_1020:
	ds_read_b128 v[144:147], v155
	ds_read_b128 v[148:151], v155 offset:1024
	ds_read_b128 v[160:163], v155 offset:2048
	ds_read_b128 v[170:173], v155 offset:3072
	ds_read_b128 v[174:177], v156
	ds_read_b128 v[178:181], v156 offset:1024
	ds_read_b128 v[182:185], v156 offset:2048
	ds_read_b128 v[186:189], v156 offset:3072
	s_add_u32 s26, s24, 0xfff80080
	s_addc_u32 s27, s25, -1
	s_cmp_eq_u32 s49, 28
	s_cselect_b32 s29, s17, s27
	s_cselect_b32 s28, s41, s26
	s_cselect_b32 s27, s15, s48
	s_cselect_b32 s26, s42, s43
	v_lshl_add_u64 v[164:165], s[24:25], 0, v[136:137]
	s_add_i32 m0, s23, 0xc000
	ds_read_b128 v[190:193], v157
	ds_read_b128 v[194:197], v157 offset:1024
	ds_read_b128 v[198:201], v157 offset:2048
	ds_read_b128 v[202:205], v157 offset:3072
	ds_read_b128 v[206:209], v157 offset:4096
	ds_read_b128 v[210:213], v157 offset:5120
	ds_read_b128 v[214:217], v157 offset:6144
	ds_read_b128 v[218:221], v157 offset:7168
	global_load_lds_dwordx4 v[164:165], off
	v_lshl_add_u64 v[164:165], s[24:25], 0, v[138:139]
	s_add_i32 m0, s23, 0xe000
	s_nop 0
	global_load_lds_dwordx4 v[164:165], off
	s_waitcnt vmcnt(8)
	s_waitcnt lgkmcnt(0)
	s_barrier
	s_setprio 1
	s_waitcnt lgkmcnt(0)
	v_mfma_f32_16x16x32_bf16 v[124:127], v[144:147], v[190:193], v[124:127]
	v_mfma_f32_16x16x32_bf16 v[124:127], v[148:151], v[194:197], v[124:127]
	v_mfma_f32_16x16x32_bf16 v[120:123], v[170:173], v[194:197], v[120:123]
	v_mfma_f32_16x16x32_bf16 v[120:123], v[160:163], v[190:193], v[120:123]
	v_mfma_f32_16x16x32_bf16 v[104:107], v[160:163], v[198:201], v[104:107]
	v_mfma_f32_16x16x32_bf16 v[104:107], v[170:173], v[202:205], v[104:107]
	v_mfma_f32_16x16x32_bf16 v[108:111], v[148:151], v[202:205], v[108:111]
	v_mfma_f32_16x16x32_bf16 v[108:111], v[144:147], v[198:201], v[108:111]
	v_mfma_f32_16x16x32_bf16 v[92:95], v[144:147], v[206:209], v[92:95]
	v_mfma_f32_16x16x32_bf16 v[92:95], v[148:151], v[210:213], v[92:95]
	v_mfma_f32_16x16x32_bf16 v[88:91], v[170:173], v[210:213], v[88:91]
	v_mfma_f32_16x16x32_bf16 v[88:91], v[160:163], v[206:209], v[88:91]
	v_mfma_f32_16x16x32_bf16 v[72:75], v[160:163], v[214:217], v[72:75]
	v_mfma_f32_16x16x32_bf16 v[72:75], v[170:173], v[218:221], v[72:75]
	v_mfma_f32_16x16x32_bf16 v[76:79], v[148:151], v[218:221], v[76:79]
	v_mfma_f32_16x16x32_bf16 v[76:79], v[144:147], v[214:217], v[76:79]
	s_setprio 0
	s_setprio 1
	v_mfma_f32_16x16x32_bf16 v[116:119], v[174:177], v[190:193], v[116:119]
	v_mfma_f32_16x16x32_bf16 v[116:119], v[178:181], v[194:197], v[116:119]
	v_mfma_f32_16x16x32_bf16 v[112:115], v[186:189], v[194:197], v[112:115]
	v_mfma_f32_16x16x32_bf16 v[112:115], v[182:185], v[190:193], v[112:115]
	v_mfma_f32_16x16x32_bf16 v[96:99], v[182:185], v[198:201], v[96:99]
	v_mfma_f32_16x16x32_bf16 v[96:99], v[186:189], v[202:205], v[96:99]
	v_mfma_f32_16x16x32_bf16 v[100:103], v[178:181], v[202:205], v[100:103]
	v_mfma_f32_16x16x32_bf16 v[100:103], v[174:177], v[198:201], v[100:103]
	v_mfma_f32_16x16x32_bf16 v[84:87], v[174:177], v[206:209], v[84:87]
	v_mfma_f32_16x16x32_bf16 v[84:87], v[178:181], v[210:213], v[84:87]
	v_mfma_f32_16x16x32_bf16 v[80:83], v[186:189], v[210:213], v[80:83]
	v_mfma_f32_16x16x32_bf16 v[80:83], v[182:185], v[206:209], v[80:83]
	v_mfma_f32_16x16x32_bf16 v[64:67], v[182:185], v[214:217], v[64:67]
	v_mfma_f32_16x16x32_bf16 v[64:67], v[186:189], v[218:221], v[64:67]
	v_mfma_f32_16x16x32_bf16 v[68:71], v[178:181], v[218:221], v[68:71]
	v_mfma_f32_16x16x32_bf16 v[68:71], v[174:177], v[214:217], v[68:71]
	s_setprio 0
	s_barrier
	s_add_i32 s46, s37, s12
	v_lshl_add_u64 v[164:165], s[26:27], 0, v[132:133]
	s_mov_b32 m0, s46
	ds_read_b128 v[190:193], v157 offset:16384
	ds_read_b128 v[194:197], v157 offset:17408
	ds_read_b128 v[198:201], v157 offset:18432
	ds_read_b128 v[202:205], v157 offset:19456
	ds_read_b128 v[206:209], v157 offset:20480
	ds_read_b128 v[210:213], v157 offset:21504
	ds_read_b128 v[214:217], v157 offset:22528
	ds_read_b128 v[218:221], v157 offset:23552
	global_load_lds_dwordx4 v[164:165], off
	s_add_i32 m0, s46, 0x2000
	s_add_u32 s46, s26, 0x80000
	v_lshl_add_u64 v[222:223], s[26:27], 0, v[128:129]
	s_addc_u32 s47, s27, 0
	s_add_i32 s50, s38, s12
	global_load_lds_dwordx4 v[222:223], off
	v_lshl_add_u64 v[224:225], s[46:47], 0, v[132:133]
	s_mov_b32 m0, s50
	v_lshl_add_u64 v[226:227], s[28:29], 0, v[130:131]
	global_load_lds_dwordx4 v[224:225], off
	v_lshl_add_u64 v[224:225], s[46:47], 0, v[128:129]
	s_add_i32 m0, s50, 0x2000
	s_nop 0
	global_load_lds_dwordx4 v[224:225], off
	v_lshl_add_u64 v[224:225], s[28:29], 0, v[134:135]
	s_mov_b32 m0, s23
	s_nop 0
	global_load_lds_dwordx4 v[224:225], off
	s_mov_b32 m0, s30
	s_nop 0
	global_load_lds_dwordx4 v[226:227], off
	s_waitcnt vmcnt(8)
	s_waitcnt lgkmcnt(0)
	s_barrier
; #define PG8_STAGE(bufoff, gbase, voff) do { _Pragma("unroll") for (int _i = 0; _i < 2; ++_i) \
;         __builtin_amdgcn_global_load_lds((const unsigned*)((const char*)(gbase) + (voff)[_i]), (LAS unsigned*)(lds + (bufoff) + ldsw + _i * 8192), 16, 0, 0); } while (0)
; #define PG8_LDA(dst, b, h) do { _Pragma("unroll") for (int m = 0; m < 4; ++m) _Pragma("unroll") for (int k = 0; k < 2; ++k) dst[m][k] = *(const LAS bf16x8*)(lds + PG8_SA(b, h) + aoff + m * 2048 + k * 1024); } while (0)
; #define PG8_LDB(dst, b, h) do { _Pragma("unroll") for (int n = 0; n < 2; ++n) _Pragma("unroll") for (int k = 0; k < 2; ++k) dst[n][k] = *(const LAS bf16x8*)(lds + PG8_SB(b, h) + boff + n * 2048 + k * 1024); } while (0)
; #define PG8_MMA(ai, bj, At, Bt) do { __builtin_amdgcn_s_setprio(1); _Pragma("unroll") for (int m = 0; m < 4; ++m) _Pragma("unroll") for (int n = 0; n < 2; ++n) _Pragma("unroll") for (int k = 0; k < 2; ++k) \
;         acc[ai][bj][m][n] = __builtin_amdgcn_mfma_f32_16x16x32_bf16(Bt[n][k], At[m][k], acc[ai][bj][m][n], 0, 0, 0); __builtin_amdgcn_s_setprio(0); } while (0)
; #define PG8_WAIT_V(n) asm volatile("s_waitcnt vmcnt(" #n ")" ::: "memory")
; #define PG8_WAIT_L(n) asm volatile("s_waitcnt lgkmcnt(" #n ")" ::: "memory")
; #define PG8_BAR __builtin_amdgcn_s_barrier()
; #define PG8_SCHED __builtin_amdgcn_sched_barrier(0)
; DI void gemm_phase(LAS unsigned char* lds, const Gemm g, const StaticOrder& S, const Epi& E) {
;     ...
;             PG8_WAIT_V(8); PG8_WAIT_L(0); PG8_BAR; PG8_MMA(1, 0, At, B0); PG8_MMA(1, 1, At, B1); PG8_BAR; PG8_SCHED;
;             PG8_LDB(B0, 1, 0); PG8_LDB(B1, 1, 1); PG8_SCHED; PG8_LDA(At, 1, 0); PG8_STAGE(PG8_SA(0, 1), a2 + hsA, voffA);
;             PG8_WAIT_V(8); PG8_WAIT_L(0); PG8_BAR; PG8_MMA(0, 0, At, B0); PG8_MMA(0, 1, At, B1); PG8_BAR; PG8_SCHED;
	s_setprio 1
	s_waitcnt lgkmcnt(0)
	v_mfma_f32_16x16x32_bf16 v[60:63], v[144:147], v[190:193], v[60:63]
	v_mfma_f32_16x16x32_bf16 v[60:63], v[148:151], v[194:197], v[60:63]
	v_mfma_f32_16x16x32_bf16 v[56:59], v[170:173], v[194:197], v[56:59]
	v_mfma_f32_16x16x32_bf16 v[56:59], v[160:163], v[190:193], v[56:59]
	v_mfma_f32_16x16x32_bf16 v[40:43], v[160:163], v[198:201], v[40:43]
	v_mfma_f32_16x16x32_bf16 v[40:43], v[170:173], v[202:205], v[40:43]
	v_mfma_f32_16x16x32_bf16 v[44:47], v[148:151], v[202:205], v[44:47]
	v_mfma_f32_16x16x32_bf16 v[44:47], v[144:147], v[198:201], v[44:47]
	v_mfma_f32_16x16x32_bf16 v[28:31], v[144:147], v[206:209], v[28:31]
	v_mfma_f32_16x16x32_bf16 v[28:31], v[148:151], v[210:213], v[28:31]
	v_mfma_f32_16x16x32_bf16 v[24:27], v[170:173], v[210:213], v[24:27]
	v_mfma_f32_16x16x32_bf16 v[24:27], v[160:163], v[206:209], v[24:27]
	v_mfma_f32_16x16x32_bf16 v[8:11], v[160:163], v[214:217], v[8:11]
	v_mfma_f32_16x16x32_bf16 v[8:11], v[170:173], v[218:221], v[8:11]
	v_mfma_f32_16x16x32_bf16 v[12:15], v[148:151], v[218:221], v[12:15]
	v_mfma_f32_16x16x32_bf16 v[12:15], v[144:147], v[214:217], v[12:15]
	s_setprio 0
	s_setprio 1
	v_mfma_f32_16x16x32_bf16 v[52:55], v[174:177], v[190:193], v[52:55]
	v_mfma_f32_16x16x32_bf16 v[52:55], v[178:181], v[194:197], v[52:55]
	v_mfma_f32_16x16x32_bf16 v[48:51], v[186:189], v[194:197], v[48:51]
	v_mfma_f32_16x16x32_bf16 v[48:51], v[182:185], v[190:193], v[48:51]
	v_mfma_f32_16x16x32_bf16 v[32:35], v[182:185], v[198:201], v[32:35]
	v_mfma_f32_16x16x32_bf16 v[32:35], v[186:189], v[202:205], v[32:35]
	v_mfma_f32_16x16x32_bf16 v[36:39], v[178:181], v[202:205], v[36:39]
	v_mfma_f32_16x16x32_bf16 v[36:39], v[174:177], v[198:201], v[36:39]
	v_mfma_f32_16x16x32_bf16 v[20:23], v[174:177], v[206:209], v[20:23]
	v_mfma_f32_16x16x32_bf16 v[20:23], v[178:181], v[210:213], v[20:23]
	v_mfma_f32_16x16x32_bf16 v[16:19], v[186:189], v[210:213], v[16:19]
	v_mfma_f32_16x16x32_bf16 v[16:19], v[182:185], v[206:209], v[16:19]
	v_mfma_f32_16x16x32_bf16 v[0:3], v[182:185], v[214:217], v[0:3]
	v_mfma_f32_16x16x32_bf16 v[0:3], v[186:189], v[218:221], v[0:3]
	v_mfma_f32_16x16x32_bf16 v[4:7], v[178:181], v[218:221], v[4:7]
	v_mfma_f32_16x16x32_bf16 v[4:7], v[174:177], v[214:217], v[4:7]
	s_setprio 0
	s_barrier
	s_add_i32 s46, 0, 0x18000
	v_add_u32_e32 v159, s46, v153
	s_add_i32 s47, 0, 0x1c000
	ds_read_b128 v[144:147], v159
	ds_read_b128 v[148:151], v159 offset:1024
	ds_read_b128 v[160:163], v159 offset:2048
	ds_read_b128 v[170:173], v159 offset:3072
	v_add_u32_e32 v159, s47, v153
	ds_read_b128 v[174:177], v159
	ds_read_b128 v[178:181], v159 offset:1024
	ds_read_b128 v[182:185], v159 offset:2048
	ds_read_b128 v[186:189], v159 offset:3072
	s_add_u32 s28, s28, 0x80000
	s_addc_u32 s29, s29, 0
	s_mov_b32 m0, s31
	v_lshl_add_u64 v[228:229], s[28:29], 0, v[134:135]
	ds_read_b128 v[190:193], v157 offset:32768
	ds_read_b128 v[194:197], v157 offset:33792
	ds_read_b128 v[198:201], v157 offset:34816
	ds_read_b128 v[202:205], v157 offset:35840
	ds_read_b128 v[206:209], v157 offset:36864
	ds_read_b128 v[210:213], v157 offset:37888
	ds_read_b128 v[214:217], v157 offset:38912
	ds_read_b128 v[218:221], v157 offset:39936
	global_load_lds_dwordx4 v[228:229], off
	v_lshl_add_u64 v[228:229], s[28:29], 0, v[130:131]
	s_mov_b32 m0, s33
	s_nop 0
	global_load_lds_dwordx4 v[228:229], off
	s_waitcnt vmcnt(8)
	s_waitcnt lgkmcnt(0)
	s_barrier
	s_setprio 1
	s_waitcnt lgkmcnt(0)
	v_mfma_f32_16x16x32_bf16 v[124:127], v[144:147], v[190:193], v[124:127]
	v_mfma_f32_16x16x32_bf16 v[124:127], v[148:151], v[194:197], v[124:127]
	v_mfma_f32_16x16x32_bf16 v[120:123], v[170:173], v[194:197], v[120:123]
	v_mfma_f32_16x16x32_bf16 v[120:123], v[160:163], v[190:193], v[120:123]
	v_mfma_f32_16x16x32_bf16 v[104:107], v[160:163], v[198:201], v[104:107]
	v_mfma_f32_16x16x32_bf16 v[104:107], v[170:173], v[202:205], v[104:107]
	v_mfma_f32_16x16x32_bf16 v[108:111], v[148:151], v[202:205], v[108:111]
	v_mfma_f32_16x16x32_bf16 v[108:111], v[144:147], v[198:201], v[108:111]
	v_mfma_f32_16x16x32_bf16 v[92:95], v[144:147], v[206:209], v[92:95]
	v_mfma_f32_16x16x32_bf16 v[92:95], v[148:151], v[210:213], v[92:95]
	v_mfma_f32_16x16x32_bf16 v[88:91], v[170:173], v[210:213], v[88:91]
	v_mfma_f32_16x16x32_bf16 v[88:91], v[160:163], v[206:209], v[88:91]
	v_mfma_f32_16x16x32_bf16 v[72:75], v[160:163], v[214:217], v[72:75]
	v_mfma_f32_16x16x32_bf16 v[72:75], v[170:173], v[218:221], v[72:75]
	v_mfma_f32_16x16x32_bf16 v[76:79], v[148:151], v[218:221], v[76:79]
	v_mfma_f32_16x16x32_bf16 v[76:79], v[144:147], v[214:217], v[76:79]
	s_setprio 0
	s_setprio 1
	v_mfma_f32_16x16x32_bf16 v[116:119], v[174:177], v[190:193], v[116:119]
	v_mfma_f32_16x16x32_bf16 v[116:119], v[178:181], v[194:197], v[116:119]
	v_mfma_f32_16x16x32_bf16 v[112:115], v[186:189], v[194:197], v[112:115]
	v_mfma_f32_16x16x32_bf16 v[112:115], v[182:185], v[190:193], v[112:115]
	v_mfma_f32_16x16x32_bf16 v[96:99], v[182:185], v[198:201], v[96:99]
	v_mfma_f32_16x16x32_bf16 v[96:99], v[186:189], v[202:205], v[96:99]
	v_mfma_f32_16x16x32_bf16 v[100:103], v[178:181], v[202:205], v[100:103]
	v_mfma_f32_16x16x32_bf16 v[100:103], v[174:177], v[198:201], v[100:103]
	v_mfma_f32_16x16x32_bf16 v[84:87], v[174:177], v[206:209], v[84:87]
	v_mfma_f32_16x16x32_bf16 v[84:87], v[178:181], v[210:213], v[84:87]
	v_mfma_f32_16x16x32_bf16 v[80:83], v[186:189], v[210:213], v[80:83]
	v_mfma_f32_16x16x32_bf16 v[80:83], v[182:185], v[206:209], v[80:83]
	v_mfma_f32_16x16x32_bf16 v[64:67], v[182:185], v[214:217], v[64:67]
	v_mfma_f32_16x16x32_bf16 v[64:67], v[186:189], v[218:221], v[64:67]
	v_mfma_f32_16x16x32_bf16 v[68:71], v[178:181], v[218:221], v[68:71]
	v_mfma_f32_16x16x32_bf16 v[68:71], v[174:177], v[214:217], v[68:71]
	s_setprio 0
	s_barrier
; #define PG8_STAGE(bufoff, gbase, voff) do { _Pragma("unroll") for (int _i = 0; _i < 2; ++_i) \
;         __builtin_amdgcn_global_load_lds((const unsigned*)((const char*)(gbase) + (voff)[_i]), (LAS unsigned*)(lds + (bufoff) + ldsw + _i * 8192), 16, 0, 0); } while (0)
; #define PG8_LDA(dst, b, h) do { _Pragma("unroll") for (int m = 0; m < 4; ++m) _Pragma("unroll") for (int k = 0; k < 2; ++k) dst[m][k] = *(const LAS bf16x8*)(lds + PG8_SA(b, h) + aoff + m * 2048 + k * 1024); } while (0)
; #define PG8_MMA(ai, bj, At, Bt) do { __builtin_amdgcn_s_setprio(1); _Pragma("unroll") for (int m = 0; m < 4; ++m) _Pragma("unroll") for (int n = 0; n < 2; ++n) _Pragma("unroll") for (int k = 0; k < 2; ++k) \
;         acc[ai][bj][m][n] = __builtin_amdgcn_mfma_f32_16x16x32_bf16(Bt[n][k], At[m][k], acc[ai][bj][m][n], 0, 0, 0); __builtin_amdgcn_s_setprio(0); } while (0)
; #define PG8_WAIT_V(n) asm volatile("s_waitcnt vmcnt(" #n ")" ::: "memory")
; #define PG8_WAIT_L(n) asm volatile("s_waitcnt lgkmcnt(" #n ")" ::: "memory")
; #define PG8_BAR __builtin_amdgcn_s_barrier()
; #define PG8_SCHED __builtin_amdgcn_sched_barrier(0)
; DI void gemm_phase(LAS unsigned char* lds, const Gemm g, const StaticOrder& S, const Epi& E) {
;     ...
;             PG8_LDA(At, 1, 1); PG8_STAGE(PG8_SB(1, 0), b3, voffB); PG8_STAGE(PG8_SB(1, 1), b3 + hsB, voffB); PG8_STAGE(PG8_SA(1, 0), a3, voffA);
;             PG8_WAIT_V(8); PG8_WAIT_L(0); PG8_BAR; PG8_MMA(1, 0, At, B0); PG8_MMA(1, 1, At, B1); PG8_BAR; PG8_SCHED;
;         }
;         if (wr == 0) PG8_BAR;
	s_add_i32 s28, s46, s12
	v_lshl_add_u64 v[164:165], v[164:165], 0, s[8:9]
	s_mov_b32 m0, s28
	ds_read_b128 v[190:193], v157 offset:49152
	ds_read_b128 v[194:197], v157 offset:50176
	ds_read_b128 v[198:201], v157 offset:51200
	ds_read_b128 v[202:205], v157 offset:52224
	ds_read_b128 v[206:209], v157 offset:53248
	ds_read_b128 v[210:213], v157 offset:54272
	ds_read_b128 v[214:217], v157 offset:55296
	ds_read_b128 v[218:221], v157 offset:56320
	global_load_lds_dwordx4 v[164:165], off
	s_add_i32 m0, s28, 0x2000
	s_add_u32 s26, s26, 0x80080
	v_lshl_add_u64 v[164:165], v[222:223], 0, s[8:9]
	s_addc_u32 s27, s27, 0
	s_add_i32 s28, s47, s12
	global_load_lds_dwordx4 v[164:165], off
	v_lshl_add_u64 v[164:165], s[26:27], 0, v[132:133]
	s_mov_b32 m0, s28
	s_nop 0
	global_load_lds_dwordx4 v[164:165], off
	v_lshl_add_u64 v[164:165], s[26:27], 0, v[128:129]
	s_add_i32 m0, s28, 0x2000
	s_nop 0
	global_load_lds_dwordx4 v[164:165], off
	v_lshl_add_u64 v[164:165], v[224:225], 0, s[8:9]
	s_mov_b32 m0, s35
	s_nop 0
	global_load_lds_dwordx4 v[164:165], off
	v_lshl_add_u64 v[164:165], v[226:227], 0, s[8:9]
	s_mov_b32 m0, s36
	s_nop 0
	global_load_lds_dwordx4 v[164:165], off
	s_waitcnt vmcnt(8)
	s_waitcnt lgkmcnt(0)
	s_barrier
	s_setprio 1
	s_waitcnt lgkmcnt(0)
	v_mfma_f32_16x16x32_bf16 v[60:63], v[144:147], v[190:193], v[60:63]
	v_mfma_f32_16x16x32_bf16 v[60:63], v[148:151], v[194:197], v[60:63]
	v_mfma_f32_16x16x32_bf16 v[56:59], v[170:173], v[194:197], v[56:59]
	v_mfma_f32_16x16x32_bf16 v[56:59], v[160:163], v[190:193], v[56:59]
	v_mfma_f32_16x16x32_bf16 v[40:43], v[160:163], v[198:201], v[40:43]
	v_mfma_f32_16x16x32_bf16 v[40:43], v[170:173], v[202:205], v[40:43]
	v_mfma_f32_16x16x32_bf16 v[44:47], v[148:151], v[202:205], v[44:47]
	v_mfma_f32_16x16x32_bf16 v[44:47], v[144:147], v[198:201], v[44:47]
	v_mfma_f32_16x16x32_bf16 v[28:31], v[144:147], v[206:209], v[28:31]
	v_mfma_f32_16x16x32_bf16 v[28:31], v[148:151], v[210:213], v[28:31]
	v_mfma_f32_16x16x32_bf16 v[24:27], v[170:173], v[210:213], v[24:27]
	v_mfma_f32_16x16x32_bf16 v[24:27], v[160:163], v[206:209], v[24:27]
	v_mfma_f32_16x16x32_bf16 v[8:11], v[160:163], v[214:217], v[8:11]
	v_mfma_f32_16x16x32_bf16 v[8:11], v[170:173], v[218:221], v[8:11]
	v_mfma_f32_16x16x32_bf16 v[12:15], v[148:151], v[218:221], v[12:15]
	v_mfma_f32_16x16x32_bf16 v[12:15], v[144:147], v[214:217], v[12:15]
	s_setprio 0
	s_setprio 1
	v_mfma_f32_16x16x32_bf16 v[52:55], v[174:177], v[190:193], v[52:55]
	v_mfma_f32_16x16x32_bf16 v[52:55], v[178:181], v[194:197], v[52:55]
	v_mfma_f32_16x16x32_bf16 v[48:51], v[186:189], v[194:197], v[48:51]
	v_mfma_f32_16x16x32_bf16 v[48:51], v[182:185], v[190:193], v[48:51]
	v_mfma_f32_16x16x32_bf16 v[32:35], v[182:185], v[198:201], v[32:35]
	v_mfma_f32_16x16x32_bf16 v[32:35], v[186:189], v[202:205], v[32:35]
	v_mfma_f32_16x16x32_bf16 v[36:39], v[178:181], v[202:205], v[36:39]
	v_mfma_f32_16x16x32_bf16 v[36:39], v[174:177], v[198:201], v[36:39]
	v_mfma_f32_16x16x32_bf16 v[20:23], v[174:177], v[206:209], v[20:23]
	v_mfma_f32_16x16x32_bf16 v[20:23], v[178:181], v[210:213], v[20:23]
	v_mfma_f32_16x16x32_bf16 v[16:19], v[186:189], v[210:213], v[16:19]
	v_mfma_f32_16x16x32_bf16 v[16:19], v[182:185], v[206:209], v[16:19]
	v_mfma_f32_16x16x32_bf16 v[0:3], v[182:185], v[214:217], v[0:3]
	v_mfma_f32_16x16x32_bf16 v[0:3], v[186:189], v[218:221], v[0:3]
	v_mfma_f32_16x16x32_bf16 v[4:7], v[178:181], v[218:221], v[4:7]
	v_mfma_f32_16x16x32_bf16 v[4:7], v[174:177], v[214:217], v[4:7]
	s_setprio 0
	s_barrier
	s_add_i32 s49, s49, 2
	s_add_u32 s24, s24, 0x100
	s_addc_u32 s25, s25, 0
	s_add_u32 s43, s43, 0x100
	s_addc_u32 s48, s48, 0
	s_cmp_gt_u32 s49, 29
	s_cbranch_scc0 .LBB0_1020
	s_and_b64 vcc, exec, s[10:11]
	s_cbranch_vccz .LBB0_1023
	s_barrier

; #define PG8_STAGE(bufoff, gbase, voff) do { _Pragma("unroll") for (int _i = 0; _i < 2; ++_i) \
;         __builtin_amdgcn_global_load_lds((const unsigned*)((const char*)(gbase) + (voff)[_i]), (LAS unsigned*)(lds + (bufoff) + ldsw + _i * 8192), 16, 0, 0); } while (0)
; #define PG8_LDA(dst, b, h) do { _Pragma("unroll") for (int m = 0; m < 4; ++m) _Pragma("unroll") for (int k = 0; k < 2; ++k) dst[m][k] = *(const LAS bf16x8*)(lds + PG8_SA(b, h) + aoff + m * 2048 + k * 1024); } while (0)
; #define PG8_LDB(dst, b, h) do { _Pragma("unroll") for (int n = 0; n < 2; ++n) _Pragma("unroll") for (int k = 0; k < 2; ++k) dst[n][k] = *(const LAS bf16x8*)(lds + PG8_SB(b, h) + boff + n * 2048 + k * 1024); } while (0)
; #define PG8_MMA(ai, bj, At, Bt) do { __builtin_amdgcn_s_setprio(1); _Pragma("unroll") for (int m = 0; m < 4; ++m) _Pragma("unroll") for (int n = 0; n < 2; ++n) _Pragma("unroll") for (int k = 0; k < 2; ++k) \
;         acc[ai][bj][m][n] = __builtin_amdgcn_mfma_f32_16x16x32_bf16(Bt[n][k], At[m][k], acc[ai][bj][m][n], 0, 0, 0); __builtin_amdgcn_s_setprio(0); } while (0)
; #define PG8_WAIT_V(n) asm volatile("s_waitcnt vmcnt(" #n ")" ::: "memory")
; #define PG8_WAIT_L(n) asm volatile("s_waitcnt lgkmcnt(" #n ")" ::: "memory")
; #define PG8_BAR __builtin_amdgcn_s_barrier()
; #define PG8_SCHED __builtin_amdgcn_sched_barrier(0)
; DI void gemm_phase(LAS unsigned char* lds, const Gemm g, const StaticOrder& S, const Epi& E) {
;     ...
;         for (int t = 0; t < nt; t += 2) {
;             const bool last = (t == nt - 2);
;             const char* a1 = cA + (size_t)(t + 1) * kstep;
;             const char* a2 = last ? nA : cA + (size_t)(t + 2) * kstep; const char* b2 = last ? nB : cB + (size_t)(t + 2) * kstep;
;             const char* a3 = a2 + kstep; const char* b3 = b2 + kstep;
;             PG8_LDB(B0, 0, 0); PG8_LDB(B1, 0, 1); PG8_SCHED; PG8_LDA(At, 0, 0); PG8_STAGE(PG8_SA(1, 1), a1 + hsA, voffA);
;             PG8_WAIT_V(8); PG8_WAIT_L(0); PG8_BAR; PG8_MMA(0, 0, At, B0); PG8_MMA(0, 1, At, B1); PG8_BAR; PG8_SCHED;
;             PG8_LDA(At, 0, 1); PG8_STAGE(PG8_SB(0, 0), b2, voffB); PG8_STAGE(PG8_SB(0, 1), b2 + hsB, voffB); PG8_STAGE(PG8_SA(0, 0), a2, voffA);
.LBB0_1101:
	ds_read_b128 v[128:131], v165
	ds_read_b128 v[132:135], v165 offset:1024
	ds_read_b128 v[136:139], v165 offset:2048
	ds_read_b128 v[156:159], v165 offset:3072
	ds_read_b128 v[170:173], v166
	ds_read_b128 v[174:177], v166 offset:1024
	ds_read_b128 v[178:181], v166 offset:2048
	ds_read_b128 v[182:185], v166 offset:3072
	s_add_u32 s26, s24, 0x100
	s_addc_u32 s27, s25, 0
	s_cmpk_eq_i32 s53, 0x54
	s_cselect_b32 s31, s5, s27
	s_cselect_b32 s30, s4, s26
	s_cselect_b32 s29, s23, s52
	s_cselect_b32 s28, s22, s51
	v_lshl_add_u64 v[160:161], s[24:25], 0, v[148:149]
	s_add_i32 m0, s13, 0xc000
	ds_read_b128 v[186:189], v168
	ds_read_b128 v[190:193], v168 offset:1024
	ds_read_b128 v[194:197], v168 offset:2048
	ds_read_b128 v[198:201], v168 offset:3072
	ds_read_b128 v[202:205], v168 offset:4096
	ds_read_b128 v[206:209], v168 offset:5120
	ds_read_b128 v[210:213], v168 offset:6144
	ds_read_b128 v[214:217], v168 offset:7168
	global_load_lds_dwordx4 v[160:161], off
	v_lshl_add_u64 v[160:161], s[24:25], 0, v[150:151]
	s_add_i32 m0, s13, 0xe000
	s_nop 0
	global_load_lds_dwordx4 v[160:161], off
	s_waitcnt vmcnt(8)
	s_waitcnt lgkmcnt(0)
	s_barrier
	s_setprio 1
	s_waitcnt lgkmcnt(0)
	v_mfma_f32_16x16x32_bf16 v[124:127], v[128:131], v[186:189], v[124:127]
	v_mfma_f32_16x16x32_bf16 v[124:127], v[132:135], v[190:193], v[124:127]
	v_mfma_f32_16x16x32_bf16 v[120:123], v[156:159], v[190:193], v[120:123]
	v_mfma_f32_16x16x32_bf16 v[120:123], v[136:139], v[186:189], v[120:123]
	v_mfma_f32_16x16x32_bf16 v[104:107], v[136:139], v[194:197], v[104:107]
	v_mfma_f32_16x16x32_bf16 v[104:107], v[156:159], v[198:201], v[104:107]
	v_mfma_f32_16x16x32_bf16 v[112:115], v[132:135], v[198:201], v[112:115]
	v_mfma_f32_16x16x32_bf16 v[112:115], v[128:131], v[194:197], v[112:115]
	v_mfma_f32_16x16x32_bf16 v[92:95], v[128:131], v[202:205], v[92:95]
	v_mfma_f32_16x16x32_bf16 v[92:95], v[132:135], v[206:209], v[92:95]
	v_mfma_f32_16x16x32_bf16 v[88:91], v[156:159], v[206:209], v[88:91]
	v_mfma_f32_16x16x32_bf16 v[88:91], v[136:139], v[202:205], v[88:91]
	v_mfma_f32_16x16x32_bf16 v[72:75], v[136:139], v[210:213], v[72:75]
	v_mfma_f32_16x16x32_bf16 v[72:75], v[156:159], v[214:217], v[72:75]
	v_mfma_f32_16x16x32_bf16 v[76:79], v[132:135], v[214:217], v[76:79]
	v_mfma_f32_16x16x32_bf16 v[76:79], v[128:131], v[210:213], v[76:79]
	s_setprio 0
	s_setprio 1
	v_mfma_f32_16x16x32_bf16 v[116:119], v[170:173], v[186:189], v[116:119]
	v_mfma_f32_16x16x32_bf16 v[116:119], v[174:177], v[190:193], v[116:119]
	v_mfma_f32_16x16x32_bf16 v[108:111], v[182:185], v[190:193], v[108:111]
	v_mfma_f32_16x16x32_bf16 v[108:111], v[178:181], v[186:189], v[108:111]
	v_mfma_f32_16x16x32_bf16 v[96:99], v[178:181], v[194:197], v[96:99]
	v_mfma_f32_16x16x32_bf16 v[96:99], v[182:185], v[198:201], v[96:99]
	v_mfma_f32_16x16x32_bf16 v[100:103], v[174:177], v[198:201], v[100:103]
	v_mfma_f32_16x16x32_bf16 v[100:103], v[170:173], v[194:197], v[100:103]
	v_mfma_f32_16x16x32_bf16 v[84:87], v[170:173], v[202:205], v[84:87]
	v_mfma_f32_16x16x32_bf16 v[84:87], v[174:177], v[206:209], v[84:87]
	v_mfma_f32_16x16x32_bf16 v[80:83], v[182:185], v[206:209], v[80:83]
	v_mfma_f32_16x16x32_bf16 v[80:83], v[178:181], v[202:205], v[80:83]
	v_mfma_f32_16x16x32_bf16 v[64:67], v[178:181], v[210:213], v[64:67]
	v_mfma_f32_16x16x32_bf16 v[64:67], v[182:185], v[214:217], v[64:67]
	v_mfma_f32_16x16x32_bf16 v[68:71], v[174:177], v[214:217], v[68:71]
	v_mfma_f32_16x16x32_bf16 v[68:71], v[170:173], v[210:213], v[68:71]
	s_setprio 0
	s_barrier
	s_add_i32 s24, s39, s12
	v_lshl_add_u64 v[160:161], s[28:29], 0, v[142:143]
	s_mov_b32 m0, s24
	ds_read_b128 v[186:189], v168 offset:16384
	ds_read_b128 v[190:193], v168 offset:17408
	ds_read_b128 v[194:197], v168 offset:18432
	ds_read_b128 v[198:201], v168 offset:19456
	ds_read_b128 v[202:205], v168 offset:20480
	ds_read_b128 v[206:209], v168 offset:21504
	ds_read_b128 v[210:213], v168 offset:22528
	ds_read_b128 v[214:217], v168 offset:23552
	global_load_lds_dwordx4 v[160:161], off
	s_add_i32 m0, s24, 0x2000
	s_add_u32 s24, s28, 0x160000
	v_lshl_add_u64 v[218:219], s[28:29], 0, v[146:147]
	s_addc_u32 s25, s29, 0
	s_add_i32 s54, s40, s12
	global_load_lds_dwordx4 v[218:219], off
	v_lshl_add_u64 v[220:221], s[24:25], 0, v[142:143]
	s_mov_b32 m0, s54
	v_lshl_add_u64 v[222:223], s[30:31], 0, v[144:145]
	global_load_lds_dwordx4 v[220:221], off
	v_lshl_add_u64 v[220:221], s[24:25], 0, v[146:147]
	s_add_i32 m0, s54, 0x2000
	s_nop 0
	global_load_lds_dwordx4 v[220:221], off
	v_lshl_add_u64 v[220:221], s[30:31], 0, v[140:141]
	s_mov_b32 m0, s13
	s_nop 0
	global_load_lds_dwordx4 v[220:221], off
	s_mov_b32 m0, s33
	s_nop 0
	global_load_lds_dwordx4 v[222:223], off
	s_waitcnt vmcnt(8)
	s_waitcnt lgkmcnt(0)
	s_barrier
; #define PG8_STAGE(bufoff, gbase, voff) do { _Pragma("unroll") for (int _i = 0; _i < 2; ++_i) \
;         __builtin_amdgcn_global_load_lds((const unsigned*)((const char*)(gbase) + (voff)[_i]), (LAS unsigned*)(lds + (bufoff) + ldsw + _i * 8192), 16, 0, 0); } while (0)
; #define PG8_LDA(dst, b, h) do { _Pragma("unroll") for (int m = 0; m < 4; ++m) _Pragma("unroll") for (int k = 0; k < 2; ++k) dst[m][k] = *(const LAS bf16x8*)(lds + PG8_SA(b, h) + aoff + m * 2048 + k * 1024); } while (0)
; #define PG8_LDB(dst, b, h) do { _Pragma("unroll") for (int n = 0; n < 2; ++n) _Pragma("unroll") for (int k = 0; k < 2; ++k) dst[n][k] = *(const LAS bf16x8*)(lds + PG8_SB(b, h) + boff + n * 2048 + k * 1024); } while (0)
; #define PG8_MMA(ai, bj, At, Bt) do { __builtin_amdgcn_s_setprio(1); _Pragma("unroll") for (int m = 0; m < 4; ++m) _Pragma("unroll") for (int n = 0; n < 2; ++n) _Pragma("unroll") for (int k = 0; k < 2; ++k) \
;         acc[ai][bj][m][n] = __builtin_amdgcn_mfma_f32_16x16x32_bf16(Bt[n][k], At[m][k], acc[ai][bj][m][n], 0, 0, 0); __builtin_amdgcn_s_setprio(0); } while (0)
; #define PG8_WAIT_V(n) asm volatile("s_waitcnt vmcnt(" #n ")" ::: "memory")
; #define PG8_WAIT_L(n) asm volatile("s_waitcnt lgkmcnt(" #n ")" ::: "memory")
; #define PG8_BAR __builtin_amdgcn_s_barrier()
; #define PG8_SCHED __builtin_amdgcn_sched_barrier(0)
; DI void gemm_phase(LAS unsigned char* lds, const Gemm g, const StaticOrder& S, const Epi& E) {
;     ...
;             PG8_WAIT_V(8); PG8_WAIT_L(0); PG8_BAR; PG8_MMA(1, 0, At, B0); PG8_MMA(1, 1, At, B1); PG8_BAR; PG8_SCHED;
;             PG8_LDB(B0, 1, 0); PG8_LDB(B1, 1, 1); PG8_SCHED; PG8_LDA(At, 1, 0); PG8_STAGE(PG8_SA(0, 1), a2 + hsA, voffA);
;             PG8_WAIT_V(8); PG8_WAIT_L(0); PG8_BAR; PG8_MMA(0, 0, At, B0); PG8_MMA(0, 1, At, B1); PG8_BAR; PG8_SCHED;
	s_setprio 1
	s_waitcnt lgkmcnt(0)
	v_mfma_f32_16x16x32_bf16 v[60:63], v[128:131], v[186:189], v[60:63]
	v_mfma_f32_16x16x32_bf16 v[60:63], v[132:135], v[190:193], v[60:63]
	v_mfma_f32_16x16x32_bf16 v[56:59], v[156:159], v[190:193], v[56:59]
	v_mfma_f32_16x16x32_bf16 v[56:59], v[136:139], v[186:189], v[56:59]
	v_mfma_f32_16x16x32_bf16 v[40:43], v[136:139], v[194:197], v[40:43]
	v_mfma_f32_16x16x32_bf16 v[40:43], v[156:159], v[198:201], v[40:43]
	v_mfma_f32_16x16x32_bf16 v[48:51], v[132:135], v[198:201], v[48:51]
	v_mfma_f32_16x16x32_bf16 v[48:51], v[128:131], v[194:197], v[48:51]
	v_mfma_f32_16x16x32_bf16 v[36:39], v[128:131], v[202:205], v[36:39]
	v_mfma_f32_16x16x32_bf16 v[36:39], v[132:135], v[206:209], v[36:39]
	v_mfma_f32_16x16x32_bf16 v[28:31], v[156:159], v[206:209], v[28:31]
	v_mfma_f32_16x16x32_bf16 v[28:31], v[136:139], v[202:205], v[28:31]
	v_mfma_f32_16x16x32_bf16 v[12:15], v[136:139], v[210:213], v[12:15]
	v_mfma_f32_16x16x32_bf16 v[12:15], v[156:159], v[214:217], v[12:15]
	v_mfma_f32_16x16x32_bf16 v[20:23], v[132:135], v[214:217], v[20:23]
	v_mfma_f32_16x16x32_bf16 v[20:23], v[128:131], v[210:213], v[20:23]
	s_setprio 0
	s_setprio 1
	v_mfma_f32_16x16x32_bf16 v[52:55], v[170:173], v[186:189], v[52:55]
	v_mfma_f32_16x16x32_bf16 v[52:55], v[174:177], v[190:193], v[52:55]
	v_mfma_f32_16x16x32_bf16 v[44:47], v[182:185], v[190:193], v[44:47]
	v_mfma_f32_16x16x32_bf16 v[44:47], v[178:181], v[186:189], v[44:47]
	v_mfma_f32_16x16x32_bf16 v[24:27], v[178:181], v[194:197], v[24:27]
	v_mfma_f32_16x16x32_bf16 v[24:27], v[182:185], v[198:201], v[24:27]
	v_mfma_f32_16x16x32_bf16 v[32:35], v[174:177], v[198:201], v[32:35]
	v_mfma_f32_16x16x32_bf16 v[32:35], v[170:173], v[194:197], v[32:35]
	v_mfma_f32_16x16x32_bf16 v[16:19], v[170:173], v[202:205], v[16:19]
	v_mfma_f32_16x16x32_bf16 v[16:19], v[174:177], v[206:209], v[16:19]
	v_mfma_f32_16x16x32_bf16 v[8:11], v[182:185], v[206:209], v[8:11]
	v_mfma_f32_16x16x32_bf16 v[8:11], v[178:181], v[202:205], v[8:11]
	v_mfma_f32_16x16x32_bf16 v[0:3], v[178:181], v[210:213], v[0:3]
	v_mfma_f32_16x16x32_bf16 v[0:3], v[182:185], v[214:217], v[0:3]
	v_mfma_f32_16x16x32_bf16 v[4:7], v[174:177], v[214:217], v[4:7]
	v_mfma_f32_16x16x32_bf16 v[4:7], v[170:173], v[210:213], v[4:7]
	s_setprio 0
	s_barrier
	s_add_i32 s54, 0, 0x18000
	s_add_i32 s55, 0, 0x1c000
	v_add_u32_e32 v156, s54, v163
	v_add_u32_e32 v182, s55, v163
	ds_read_b128 v[128:131], v156
	ds_read_b128 v[132:135], v156 offset:1024
	ds_read_b128 v[136:139], v156 offset:2048
	ds_read_b128 v[156:159], v156 offset:3072
	ds_read_b128 v[170:173], v182
	ds_read_b128 v[174:177], v182 offset:1024
	ds_read_b128 v[178:181], v182 offset:2048
	ds_read_b128 v[182:185], v182 offset:3072
	s_add_u32 s24, s30, 0x160000
	s_addc_u32 s25, s31, 0
	s_mov_b32 m0, s34
	v_lshl_add_u64 v[224:225], s[24:25], 0, v[140:141]
	ds_read_b128 v[186:189], v168 offset:32768
	ds_read_b128 v[190:193], v168 offset:33792
	ds_read_b128 v[194:197], v168 offset:34816
	ds_read_b128 v[198:201], v168 offset:35840
	ds_read_b128 v[202:205], v168 offset:36864
	ds_read_b128 v[206:209], v168 offset:37888
	ds_read_b128 v[210:213], v168 offset:38912
	ds_read_b128 v[214:217], v168 offset:39936
	global_load_lds_dwordx4 v[224:225], off
	v_lshl_add_u64 v[224:225], s[24:25], 0, v[144:145]
	s_mov_b32 m0, s35
	s_nop 0
	global_load_lds_dwordx4 v[224:225], off
	s_waitcnt vmcnt(8)
	s_waitcnt lgkmcnt(0)
	s_barrier
	s_setprio 1
	s_waitcnt lgkmcnt(0)
	v_mfma_f32_16x16x32_bf16 v[124:127], v[128:131], v[186:189], v[124:127]
	v_mfma_f32_16x16x32_bf16 v[124:127], v[132:135], v[190:193], v[124:127]
	v_mfma_f32_16x16x32_bf16 v[120:123], v[156:159], v[190:193], v[120:123]
	v_mfma_f32_16x16x32_bf16 v[120:123], v[136:139], v[186:189], v[120:123]
	v_mfma_f32_16x16x32_bf16 v[104:107], v[136:139], v[194:197], v[104:107]
	v_mfma_f32_16x16x32_bf16 v[104:107], v[156:159], v[198:201], v[104:107]
	v_mfma_f32_16x16x32_bf16 v[112:115], v[132:135], v[198:201], v[112:115]
	v_mfma_f32_16x16x32_bf16 v[112:115], v[128:131], v[194:197], v[112:115]
	v_mfma_f32_16x16x32_bf16 v[92:95], v[128:131], v[202:205], v[92:95]
	v_mfma_f32_16x16x32_bf16 v[92:95], v[132:135], v[206:209], v[92:95]
	v_mfma_f32_16x16x32_bf16 v[88:91], v[156:159], v[206:209], v[88:91]
	v_mfma_f32_16x16x32_bf16 v[88:91], v[136:139], v[202:205], v[88:91]
	v_mfma_f32_16x16x32_bf16 v[72:75], v[136:139], v[210:213], v[72:75]
	v_mfma_f32_16x16x32_bf16 v[72:75], v[156:159], v[214:217], v[72:75]
	v_mfma_f32_16x16x32_bf16 v[76:79], v[132:135], v[214:217], v[76:79]
	v_mfma_f32_16x16x32_bf16 v[76:79], v[128:131], v[210:213], v[76:79]
	s_setprio 0
	s_setprio 1
	v_mfma_f32_16x16x32_bf16 v[116:119], v[170:173], v[186:189], v[116:119]
	v_mfma_f32_16x16x32_bf16 v[116:119], v[174:177], v[190:193], v[116:119]
	v_mfma_f32_16x16x32_bf16 v[108:111], v[182:185], v[190:193], v[108:111]
	v_mfma_f32_16x16x32_bf16 v[108:111], v[178:181], v[186:189], v[108:111]
	v_mfma_f32_16x16x32_bf16 v[96:99], v[178:181], v[194:197], v[96:99]
	v_mfma_f32_16x16x32_bf16 v[96:99], v[182:185], v[198:201], v[96:99]
	v_mfma_f32_16x16x32_bf16 v[100:103], v[174:177], v[198:201], v[100:103]
	v_mfma_f32_16x16x32_bf16 v[100:103], v[170:173], v[194:197], v[100:103]
	v_mfma_f32_16x16x32_bf16 v[84:87], v[170:173], v[202:205], v[84:87]
	v_mfma_f32_16x16x32_bf16 v[84:87], v[174:177], v[206:209], v[84:87]
	v_mfma_f32_16x16x32_bf16 v[80:83], v[182:185], v[206:209], v[80:83]
	v_mfma_f32_16x16x32_bf16 v[80:83], v[178:181], v[202:205], v[80:83]
	v_mfma_f32_16x16x32_bf16 v[64:67], v[178:181], v[210:213], v[64:67]
	v_mfma_f32_16x16x32_bf16 v[64:67], v[182:185], v[214:217], v[64:67]
	v_mfma_f32_16x16x32_bf16 v[68:71], v[174:177], v[214:217], v[68:71]
	v_mfma_f32_16x16x32_bf16 v[68:71], v[170:173], v[210:213], v[68:71]
	s_setprio 0
	s_barrier
; #define PG8_STAGE(bufoff, gbase, voff) do { _Pragma("unroll") for (int _i = 0; _i < 2; ++_i) \
;         __builtin_amdgcn_global_load_lds((const unsigned*)((const char*)(gbase) + (voff)[_i]), (LAS unsigned*)(lds + (bufoff) + ldsw + _i * 8192), 16, 0, 0); } while (0)
; #define PG8_LDA(dst, b, h) do { _Pragma("unroll") for (int m = 0; m < 4; ++m) _Pragma("unroll") for (int k = 0; k < 2; ++k) dst[m][k] = *(const LAS bf16x8*)(lds + PG8_SA(b, h) + aoff + m * 2048 + k * 1024); } while (0)
; #define PG8_MMA(ai, bj, At, Bt) do { __builtin_amdgcn_s_setprio(1); _Pragma("unroll") for (int m = 0; m < 4; ++m) _Pragma("unroll") for (int n = 0; n < 2; ++n) _Pragma("unroll") for (int k = 0; k < 2; ++k) \
;         acc[ai][bj][m][n] = __builtin_amdgcn_mfma_f32_16x16x32_bf16(Bt[n][k], At[m][k], acc[ai][bj][m][n], 0, 0, 0); __builtin_amdgcn_s_setprio(0); } while (0)
; #define PG8_WAIT_V(n) asm volatile("s_waitcnt vmcnt(" #n ")" ::: "memory")
; #define PG8_WAIT_L(n) asm volatile("s_waitcnt lgkmcnt(" #n ")" ::: "memory")
; #define PG8_BAR __builtin_amdgcn_s_barrier()
; #define PG8_SCHED __builtin_amdgcn_sched_barrier(0)
; DI void gemm_phase(LAS unsigned char* lds, const Gemm g, const StaticOrder& S, const Epi& E) {
;     ...
;             PG8_LDA(At, 1, 1); PG8_STAGE(PG8_SB(1, 0), b3, voffB); PG8_STAGE(PG8_SB(1, 1), b3 + hsB, voffB); PG8_STAGE(PG8_SA(1, 0), a3, voffA);
;             PG8_WAIT_V(8); PG8_WAIT_L(0); PG8_BAR; PG8_MMA(1, 0, At, B0); PG8_MMA(1, 1, At, B1); PG8_BAR; PG8_SCHED;
;         }
;         if (wr == 0) PG8_BAR;
	s_add_i32 s24, s54, s12
	v_lshl_add_u64 v[160:161], v[160:161], 0, s[8:9]
	s_mov_b32 m0, s24
	ds_read_b128 v[186:189], v168 offset:49152
	ds_read_b128 v[190:193], v168 offset:50176
	ds_read_b128 v[194:197], v168 offset:51200
	ds_read_b128 v[198:201], v168 offset:52224
	ds_read_b128 v[202:205], v168 offset:53248
	ds_read_b128 v[206:209], v168 offset:54272
	ds_read_b128 v[210:213], v168 offset:55296
	ds_read_b128 v[214:217], v168 offset:56320
	global_load_lds_dwordx4 v[160:161], off
	s_add_i32 m0, s24, 0x2000
	s_add_u32 s24, s28, 0x160080
	v_lshl_add_u64 v[160:161], v[218:219], 0, s[8:9]
	s_addc_u32 s25, s29, 0
	s_add_i32 s28, s55, s12
	global_load_lds_dwordx4 v[160:161], off
	v_lshl_add_u64 v[160:161], s[24:25], 0, v[142:143]
	s_mov_b32 m0, s28
	s_nop 0
	global_load_lds_dwordx4 v[160:161], off
	v_lshl_add_u64 v[160:161], s[24:25], 0, v[146:147]
	s_add_i32 m0, s28, 0x2000
	s_nop 0
	global_load_lds_dwordx4 v[160:161], off
	v_lshl_add_u64 v[160:161], v[220:221], 0, s[8:9]
	s_mov_b32 m0, s37
	s_nop 0
	global_load_lds_dwordx4 v[160:161], off
	v_lshl_add_u64 v[160:161], v[222:223], 0, s[8:9]
	s_mov_b32 m0, s38
	s_nop 0
	global_load_lds_dwordx4 v[160:161], off
	s_waitcnt vmcnt(8)
	s_waitcnt lgkmcnt(0)
	s_barrier
	s_setprio 1
	s_waitcnt lgkmcnt(0)
	v_mfma_f32_16x16x32_bf16 v[60:63], v[128:131], v[186:189], v[60:63]
	v_mfma_f32_16x16x32_bf16 v[60:63], v[132:135], v[190:193], v[60:63]
	v_mfma_f32_16x16x32_bf16 v[56:59], v[156:159], v[190:193], v[56:59]
	v_mfma_f32_16x16x32_bf16 v[56:59], v[136:139], v[186:189], v[56:59]
	v_mfma_f32_16x16x32_bf16 v[40:43], v[136:139], v[194:197], v[40:43]
	v_mfma_f32_16x16x32_bf16 v[40:43], v[156:159], v[198:201], v[40:43]
	v_mfma_f32_16x16x32_bf16 v[48:51], v[132:135], v[198:201], v[48:51]
	v_mfma_f32_16x16x32_bf16 v[48:51], v[128:131], v[194:197], v[48:51]
	v_mfma_f32_16x16x32_bf16 v[36:39], v[128:131], v[202:205], v[36:39]
	v_mfma_f32_16x16x32_bf16 v[36:39], v[132:135], v[206:209], v[36:39]
	v_mfma_f32_16x16x32_bf16 v[28:31], v[156:159], v[206:209], v[28:31]
	v_mfma_f32_16x16x32_bf16 v[28:31], v[136:139], v[202:205], v[28:31]
	v_mfma_f32_16x16x32_bf16 v[12:15], v[136:139], v[210:213], v[12:15]
	v_mfma_f32_16x16x32_bf16 v[12:15], v[156:159], v[214:217], v[12:15]
	v_mfma_f32_16x16x32_bf16 v[20:23], v[132:135], v[214:217], v[20:23]
	v_mfma_f32_16x16x32_bf16 v[20:23], v[128:131], v[210:213], v[20:23]
	s_setprio 0
	s_setprio 1
	v_mfma_f32_16x16x32_bf16 v[52:55], v[170:173], v[186:189], v[52:55]
	v_mfma_f32_16x16x32_bf16 v[52:55], v[174:177], v[190:193], v[52:55]
	v_mfma_f32_16x16x32_bf16 v[44:47], v[182:185], v[190:193], v[44:47]
	v_mfma_f32_16x16x32_bf16 v[44:47], v[178:181], v[186:189], v[44:47]
	v_mfma_f32_16x16x32_bf16 v[24:27], v[178:181], v[194:197], v[24:27]
	v_mfma_f32_16x16x32_bf16 v[24:27], v[182:185], v[198:201], v[24:27]
	v_mfma_f32_16x16x32_bf16 v[32:35], v[174:177], v[198:201], v[32:35]
	v_mfma_f32_16x16x32_bf16 v[32:35], v[170:173], v[194:197], v[32:35]
	v_mfma_f32_16x16x32_bf16 v[16:19], v[170:173], v[202:205], v[16:19]
	v_mfma_f32_16x16x32_bf16 v[16:19], v[174:177], v[206:209], v[16:19]
	v_mfma_f32_16x16x32_bf16 v[8:11], v[182:185], v[206:209], v[8:11]
	v_mfma_f32_16x16x32_bf16 v[8:11], v[178:181], v[202:205], v[8:11]
	v_mfma_f32_16x16x32_bf16 v[0:3], v[178:181], v[210:213], v[0:3]
	v_mfma_f32_16x16x32_bf16 v[0:3], v[182:185], v[214:217], v[0:3]
	v_mfma_f32_16x16x32_bf16 v[4:7], v[174:177], v[214:217], v[4:7]
	v_mfma_f32_16x16x32_bf16 v[4:7], v[170:173], v[210:213], v[4:7]
	s_setprio 0
	s_barrier
	s_add_i32 s53, s53, 2
	s_add_u32 s51, s51, 0x100
	s_addc_u32 s52, s52, 0
	s_cmpk_gt_u32 s53, 0x55
	s_mov_b64 s[24:25], s[26:27]
	s_cbranch_scc0 .LBB0_1101
	s_and_b64 vcc, exec, s[10:11]
	s_cbranch_vccz .LBB0_1104
	s_barrier
